# gla_prep: 64 strided per-frame k loads issued up front at item start instead of 32 load-wait pairs
# baseline (speedup 1.0000x reference)
; __device__ __forceinline__ float log_sigmoid(float x) { return fminf(x, 0.f) - __logf(1.f + __expf(-fabsf(x))); }
; __device__ __forceinline__ void gla_prep_item(LAS unsigned char* lds, int item, const bf16_t* Z, const float* W2, const float* Bg, bf16_t* KDT, float* DEC) {
;     ...
;     for (int i = tid; i < 1024; i += 512) { const int t = i >> 4, r = i & 15; zgs[i] = bf2f(Z[(row0 + t) * ZLD + ZZG + r]); }
;     __syncthreads();
;     const int h = tid >> 7, kd = tid & 127, col = h * 128 + kd;
;     float w[16];
; #pragma unroll
;     for (int r = 0; r < 16; ++r) w[r] = W2[r * 512 + col];
;     const float bias = Bg[col];
;     float bend = 0.f; float gv[64];
; #pragma unroll
;     for (int t = 0; t < 64; ++t) {
;         float x = bias;
; #pragma unroll
;         for (int r = 0; r < 16; ++r) x += zgs[t * 16 + r] * w[r];
;         gv[t] = log_sigmoid(x) * (1.f / 16.f); bend += gv[t];
;     }
;     float bc = 0.f;
;     bf16_t* dst = KDT + (size_t)((b * 4 + h) * 32 + c) * 8192 + (size_t)((kd >> 4) * 2 * 64 + (kd & 15)) * 8;
;     const bf16_t* gk = Z + row0 * ZLD + ZGK + col;
;     ...
;             kv[e] = bf2f(gk[(size_t)t * ZLD]) * __expf(bend - bc);
.LBB0_598:
	global_load_ushort v46, v[0:1], off
	v_add_co_u32_e32 v3, vcc, 0x200, v3
	s_waitcnt lgkmcnt(0)
	s_mov_b64 s[16:17], 0x30000
	v_lshl_add_u64 v[0:1], v[0:1], 0, s[16:17]
	s_xor_b64 s[16:17], vcc, -1
	s_and_b64 s[16:17], exec, s[16:17]
	s_or_b64 s[0:1], s[16:17], s[0:1]
	s_waitcnt vmcnt(0)
	v_lshlrev_b32_e32 v46, 16, v46
	ds_write_b32 v2, v46
	v_add_u32_e32 v2, 0x800, v2
	s_andn2_b64 exec, exec, s[0:1]
	s_cbranch_execnz .LBB0_598
	s_or_b64 exec, exec, s[0:1]
	s_waitcnt lgkmcnt(0)
	s_barrier
	global_load_dword v65, v[6:7], off
	global_load_dword v66, v[6:7], off offset:2048
	global_load_dword v67, v[8:9], off
	global_load_dword v68, v[10:11], off
	global_load_dword v55, v[12:13], off
	global_load_dword v62, v[14:15], off
	global_load_dword v63, v[16:17], off
	global_load_dword v64, v[18:19], off
	global_load_dword v52, v[20:21], off
	global_load_dword v53, v[22:23], off
	global_load_dword v50, v[24:25], off
	global_load_dword v51, v[26:27], off
	global_load_dword v48, v[28:29], off
	global_load_dword v49, v[30:31], off
	global_load_dword v46, v[32:33], off
	global_load_dword v47, v[34:35], off
	global_load_dword v69, v[36:37], off
	ds_read_b128 v[0:3], v5
	ds_read_b128 v[70:73], v5 offset:16
	ds_read_b128 v[74:77], v5 offset:32
	ds_read_b128 v[78:81], v5 offset:48
	s_and_b32 s9, s66, 31
	s_lshl_b32 s0, s9, 6
	s_or_b32 s6, s6, s0
	s_mulk_i32 s7, 0x1800
	v_mad_u64_u32 v[208:209], s[42:43], s6, v59, v[42:43]
	v_add_u32_e32 v209, s7, v209
	s_mov_b32 s43, 0
	global_load_ushort v140, v[208:209], off offset:2688
	s_mov_b32 s42, 0x2000
	v_lshl_add_u64 v[206:207], v[208:209], 0, s[42:43]
	global_load_ushort v141, v[206:207], off offset:640
	s_mov_b32 s42, 0x3000
	v_lshl_add_u64 v[206:207], v[208:209], 0, s[42:43]
	global_load_ushort v142, v[206:207], off offset:2688
	s_mov_b32 s42, 0x5000
	v_lshl_add_u64 v[206:207], v[208:209], 0, s[42:43]
	global_load_ushort v143, v[206:207], off offset:640
	s_mov_b32 s42, 0x6000
	v_lshl_add_u64 v[206:207], v[208:209], 0, s[42:43]
	global_load_ushort v144, v[206:207], off offset:2688
	s_mov_b32 s42, 0x8000
	v_lshl_add_u64 v[206:207], v[208:209], 0, s[42:43]
	global_load_ushort v145, v[206:207], off offset:640
	s_mov_b32 s42, 0x9000
	v_lshl_add_u64 v[206:207], v[208:209], 0, s[42:43]
	global_load_ushort v146, v[206:207], off offset:2688
	s_mov_b32 s42, 0xb000
	v_lshl_add_u64 v[206:207], v[208:209], 0, s[42:43]
	global_load_ushort v147, v[206:207], off offset:640
	s_mov_b32 s42, 0xc000
	v_lshl_add_u64 v[206:207], v[208:209], 0, s[42:43]
	global_load_ushort v148, v[206:207], off offset:2688
	s_mov_b32 s42, 0xe000
	v_lshl_add_u64 v[206:207], v[208:209], 0, s[42:43]
	global_load_ushort v149, v[206:207], off offset:640
	s_mov_b32 s42, 0xf000
	v_lshl_add_u64 v[206:207], v[208:209], 0, s[42:43]
	global_load_ushort v150, v[206:207], off offset:2688
	s_mov_b32 s42, 0x11000
	v_lshl_add_u64 v[206:207], v[208:209], 0, s[42:43]
	global_load_ushort v151, v[206:207], off offset:640
	s_mov_b32 s42, 0x12000
	v_lshl_add_u64 v[206:207], v[208:209], 0, s[42:43]
	global_load_ushort v152, v[206:207], off offset:2688
	s_mov_b32 s42, 0x14000
	v_lshl_add_u64 v[206:207], v[208:209], 0, s[42:43]
	global_load_ushort v153, v[206:207], off offset:640
	s_mov_b32 s42, 0x15000
	v_lshl_add_u64 v[206:207], v[208:209], 0, s[42:43]
	global_load_ushort v154, v[206:207], off offset:2688
	s_mov_b32 s42, 0x17000
	v_lshl_add_u64 v[206:207], v[208:209], 0, s[42:43]
	global_load_ushort v155, v[206:207], off offset:640
	s_mov_b32 s42, 0x18000
	v_lshl_add_u64 v[206:207], v[208:209], 0, s[42:43]
	global_load_ushort v156, v[206:207], off offset:2688
	s_mov_b32 s42, 0x1a000
	v_lshl_add_u64 v[206:207], v[208:209], 0, s[42:43]
	global_load_ushort v157, v[206:207], off offset:640
	s_mov_b32 s42, 0x1b000
	v_lshl_add_u64 v[206:207], v[208:209], 0, s[42:43]
	global_load_ushort v158, v[206:207], off offset:2688
	s_mov_b32 s42, 0x1d000
	v_lshl_add_u64 v[206:207], v[208:209], 0, s[42:43]
	global_load_ushort v159, v[206:207], off offset:640
	s_mov_b32 s42, 0x1e000
	v_lshl_add_u64 v[206:207], v[208:209], 0, s[42:43]
	global_load_ushort v160, v[206:207], off offset:2688
	s_mov_b32 s42, 0x20000
	v_lshl_add_u64 v[206:207], v[208:209], 0, s[42:43]
	global_load_ushort v161, v[206:207], off offset:640
	s_mov_b32 s42, 0x21000
	v_lshl_add_u64 v[206:207], v[208:209], 0, s[42:43]
	global_load_ushort v162, v[206:207], off offset:2688
	s_mov_b32 s42, 0x23000
	v_lshl_add_u64 v[206:207], v[208:209], 0, s[42:43]
	global_load_ushort v163, v[206:207], off offset:640
	s_mov_b32 s42, 0x24000
	v_lshl_add_u64 v[206:207], v[208:209], 0, s[42:43]
	global_load_ushort v164, v[206:207], off offset:2688
	s_mov_b32 s42, 0x26000
	v_lshl_add_u64 v[206:207], v[208:209], 0, s[42:43]
	global_load_ushort v165, v[206:207], off offset:640
	s_mov_b32 s42, 0x27000
	v_lshl_add_u64 v[206:207], v[208:209], 0, s[42:43]
	global_load_ushort v166, v[206:207], off offset:2688
	s_mov_b32 s42, 0x29000
	v_lshl_add_u64 v[206:207], v[208:209], 0, s[42:43]
	global_load_ushort v167, v[206:207], off offset:640
	s_mov_b32 s42, 0x2a000
	v_lshl_add_u64 v[206:207], v[208:209], 0, s[42:43]
	global_load_ushort v168, v[206:207], off offset:2688
	s_mov_b32 s42, 0x2c000
	v_lshl_add_u64 v[206:207], v[208:209], 0, s[42:43]
	global_load_ushort v169, v[206:207], off offset:640
	s_mov_b32 s42, 0x2d000
	v_lshl_add_u64 v[206:207], v[208:209], 0, s[42:43]
	global_load_ushort v170, v[206:207], off offset:2688
	s_mov_b32 s42, 0x2f000
	v_lshl_add_u64 v[206:207], v[208:209], 0, s[42:43]
	global_load_ushort v171, v[206:207], off offset:640
	s_mov_b32 s42, 0x30000
	v_lshl_add_u64 v[206:207], v[208:209], 0, s[42:43]
; __device__ __forceinline__ float log_sigmoid(float x) { return fminf(x, 0.f) - __logf(1.f + __expf(-fabsf(x))); }
; __device__ __forceinline__ void gla_prep_item(LAS unsigned char* lds, int item, const bf16_t* Z, const float* W2, const float* Bg, bf16_t* KDT, float* DEC) {
;     ...
;     for (int t = 0; t < 64; ++t) {
;         float x = bias;
; #pragma unroll
;         for (int r = 0; r < 16; ++r) x += zgs[t * 16 + r] * w[r];
;         gv[t] = log_sigmoid(x) * (1.f / 16.f); bend += gv[t];
;     ...
;             kv[e] = bf2f(gk[(size_t)t * ZLD]) * __expf(bend - bc);
	global_load_ushort v172, v[206:207], off offset:2688
	s_mov_b32 s42, 0x32000
	v_lshl_add_u64 v[206:207], v[208:209], 0, s[42:43]
	global_load_ushort v173, v[206:207], off offset:640
	s_mov_b32 s42, 0x33000
	v_lshl_add_u64 v[206:207], v[208:209], 0, s[42:43]
	global_load_ushort v174, v[206:207], off offset:2688
	s_mov_b32 s42, 0x35000
	v_lshl_add_u64 v[206:207], v[208:209], 0, s[42:43]
	global_load_ushort v175, v[206:207], off offset:640
	s_mov_b32 s42, 0x36000
	v_lshl_add_u64 v[206:207], v[208:209], 0, s[42:43]
	global_load_ushort v176, v[206:207], off offset:2688
	s_mov_b32 s42, 0x38000
	v_lshl_add_u64 v[206:207], v[208:209], 0, s[42:43]
	global_load_ushort v177, v[206:207], off offset:640
	s_mov_b32 s42, 0x39000
	v_lshl_add_u64 v[206:207], v[208:209], 0, s[42:43]
	global_load_ushort v178, v[206:207], off offset:2688
	s_mov_b32 s42, 0x3b000
	v_lshl_add_u64 v[206:207], v[208:209], 0, s[42:43]
	global_load_ushort v179, v[206:207], off offset:640
	s_mov_b32 s42, 0x3c000
	v_lshl_add_u64 v[206:207], v[208:209], 0, s[42:43]
	global_load_ushort v180, v[206:207], off offset:2688
	s_mov_b32 s42, 0x3e000
	v_lshl_add_u64 v[206:207], v[208:209], 0, s[42:43]
	global_load_ushort v181, v[206:207], off offset:640
	s_mov_b32 s42, 0x3f000
	v_lshl_add_u64 v[206:207], v[208:209], 0, s[42:43]
	global_load_ushort v182, v[206:207], off offset:2688
	s_mov_b32 s42, 0x41000
	v_lshl_add_u64 v[206:207], v[208:209], 0, s[42:43]
	global_load_ushort v183, v[206:207], off offset:640
	s_mov_b32 s42, 0x42000
	v_lshl_add_u64 v[206:207], v[208:209], 0, s[42:43]
	global_load_ushort v186, v[206:207], off offset:2688
	s_mov_b32 s42, 0x44000
	v_lshl_add_u64 v[206:207], v[208:209], 0, s[42:43]
	global_load_ushort v187, v[206:207], off offset:640
	s_mov_b32 s42, 0x45000
	v_lshl_add_u64 v[206:207], v[208:209], 0, s[42:43]
	global_load_ushort v188, v[206:207], off offset:2688
	s_mov_b32 s42, 0x47000
	v_lshl_add_u64 v[206:207], v[208:209], 0, s[42:43]
	global_load_ushort v189, v[206:207], off offset:640
	s_mov_b32 s42, 0x48000
	v_lshl_add_u64 v[206:207], v[208:209], 0, s[42:43]
	global_load_ushort v190, v[206:207], off offset:2688
	s_mov_b32 s42, 0x4a000
	v_lshl_add_u64 v[206:207], v[208:209], 0, s[42:43]
	global_load_ushort v191, v[206:207], off offset:640
	s_mov_b32 s42, 0x4b000
	v_lshl_add_u64 v[206:207], v[208:209], 0, s[42:43]
	global_load_ushort v192, v[206:207], off offset:2688
	s_mov_b32 s42, 0x4d000
	v_lshl_add_u64 v[206:207], v[208:209], 0, s[42:43]
	global_load_ushort v193, v[206:207], off offset:640
	s_mov_b32 s42, 0x4e000
	v_lshl_add_u64 v[206:207], v[208:209], 0, s[42:43]
	global_load_ushort v194, v[206:207], off offset:2688
	s_mov_b32 s42, 0x50000
	v_lshl_add_u64 v[206:207], v[208:209], 0, s[42:43]
	global_load_ushort v195, v[206:207], off offset:640
	s_mov_b32 s42, 0x51000
	v_lshl_add_u64 v[206:207], v[208:209], 0, s[42:43]
	global_load_ushort v196, v[206:207], off offset:2688
	s_mov_b32 s42, 0x53000
	v_lshl_add_u64 v[206:207], v[208:209], 0, s[42:43]
	global_load_ushort v197, v[206:207], off offset:640
	s_mov_b32 s42, 0x54000
	v_lshl_add_u64 v[206:207], v[208:209], 0, s[42:43]
	global_load_ushort v198, v[206:207], off offset:2688
	s_mov_b32 s42, 0x56000
	v_lshl_add_u64 v[206:207], v[208:209], 0, s[42:43]
	global_load_ushort v199, v[206:207], off offset:640
	s_mov_b32 s42, 0x57000
	v_lshl_add_u64 v[206:207], v[208:209], 0, s[42:43]
	global_load_ushort v200, v[206:207], off offset:2688
	s_mov_b32 s42, 0x59000
	v_lshl_add_u64 v[206:207], v[208:209], 0, s[42:43]
	global_load_ushort v201, v[206:207], off offset:640
	s_mov_b32 s42, 0x5a000
	v_lshl_add_u64 v[206:207], v[208:209], 0, s[42:43]
	global_load_ushort v202, v[206:207], off offset:2688
	s_mov_b32 s42, 0x5c000
	v_lshl_add_u64 v[206:207], v[208:209], 0, s[42:43]
	global_load_ushort v203, v[206:207], off offset:640
	s_mov_b32 s42, 0x5d000
	v_lshl_add_u64 v[206:207], v[208:209], 0, s[42:43]
	global_load_ushort v204, v[206:207], off offset:2688
	s_mov_b32 s42, 0x5f000
	v_lshl_add_u64 v[206:207], v[208:209], 0, s[42:43]
	global_load_ushort v205, v[206:207], off offset:640
	s_add_i32 s66, s66, s15
	s_add_i32 s65, s65, s15
	s_cmpk_gt_i32 s66, 0xff
	s_waitcnt vmcnt(0) lgkmcnt(3)
	v_fma_f32 v54, v65, v0, v69
	v_fmac_f32_e32 v54, v66, v1
	v_fmac_f32_e32 v54, v67, v2
	v_fmac_f32_e32 v54, v68, v3
	s_waitcnt lgkmcnt(2)
	v_fmac_f32_e32 v54, v55, v70
	v_fmac_f32_e32 v54, v62, v71
	v_fmac_f32_e32 v54, v63, v72
	v_fmac_f32_e32 v54, v64, v73
	s_waitcnt lgkmcnt(1)
	v_fmac_f32_e32 v54, v52, v74
	v_fmac_f32_e32 v54, v53, v75
	v_fmac_f32_e32 v54, v50, v76
	v_fmac_f32_e32 v54, v51, v77
	s_waitcnt lgkmcnt(0)
	v_pk_mul_f32 v[0:1], v[48:49], v[78:79]
	s_nop 0
	v_add_f32_e32 v0, v54, v0
	v_add_f32_e32 v2, v0, v1
	v_pk_mul_f32 v[0:1], v[46:47], v[80:81]
	s_nop 0
	v_add_f32_e32 v0, v2, v0
	v_add_f32_e32 v0, v0, v1
	v_min_f32_e32 v1, 0, v0
	v_mul_f32_e64 v0, |v0|, s11
	v_exp_f32_e32 v0, v0
	s_nop 0
	v_add_f32_e32 v0, 1.0, v0
	v_cmp_gt_f32_e32 vcc, s12, v0
	s_nop 1
	v_cndmask_b32_e64 v2, 0, 32, vcc
	v_ldexp_f32 v0, v0, v2
	v_log_f32_e32 v0, v0
	s_nop 0
	v_mul_f32_e32 v2, 0x3f317217, v0
	v_fma_f32 v2, v0, s13, -v2
	v_fmac_f32_e32 v2, 0x3377d1cf, v0
	v_fmac_f32_e32 v2, 0x3f317217, v0
	v_cmp_lt_f32_e64 s[0:1], |v0|, s36
	s_nop 1
	v_cndmask_b32_e64 v0, v0, v2, s[0:1]
	v_cndmask_b32_e32 v2, 0, v60, vcc
	v_sub_f32_e32 v0, v0, v2
	v_sub_f32_e32 v0, v1, v0
	s_mov_b32 s0, 0x3d800000
	v_fma_f32 v54, v0, s0, 0
	ds_read_b128 v[0:3], v5 offset:64
	s_waitcnt lgkmcnt(0)
	v_fma_f32 v70, v65, v0, v69
	v_fmac_f32_e32 v70, v66, v1
	v_fmac_f32_e32 v70, v67, v2
	v_fmac_f32_e32 v70, v68, v3
	ds_read_b128 v[0:3], v5 offset:80
	s_waitcnt lgkmcnt(0)
; __device__ __forceinline__ float log_sigmoid(float x) { return fminf(x, 0.f) - __logf(1.f + __expf(-fabsf(x))); }
; __device__ __forceinline__ void gla_prep_item(LAS unsigned char* lds, int item, const bf16_t* Z, const float* W2, const float* Bg, bf16_t* KDT, float* DEC) {
;     ...
;     for (int t = 0; t < 64; ++t) {
;         float x = bias;
; #pragma unroll
;         for (int r = 0; r < 16; ++r) x += zgs[t * 16 + r] * w[r];
;         gv[t] = log_sigmoid(x) * (1.f / 16.f); bend += gv[t];
	v_fmac_f32_e32 v70, v55, v0
	v_fmac_f32_e32 v70, v62, v1
	v_fmac_f32_e32 v70, v63, v2
	v_fmac_f32_e32 v70, v64, v3
	ds_read_b128 v[0:3], v5 offset:96
	s_waitcnt lgkmcnt(0)
	v_fmac_f32_e32 v70, v52, v0
	v_fmac_f32_e32 v70, v53, v1
	v_fmac_f32_e32 v70, v50, v2
	v_fmac_f32_e32 v70, v51, v3
	ds_read_b128 v[0:3], v5 offset:112
	s_waitcnt lgkmcnt(0)
	v_pk_mul_f32 v[0:1], v[48:49], v[0:1]
	s_nop 0
	v_add_f32_e32 v0, v70, v0
	v_add_f32_e32 v70, v0, v1
	v_pk_mul_f32 v[0:1], v[46:47], v[2:3]
	s_nop 0
	v_add_f32_e32 v0, v70, v0
	v_add_f32_e32 v0, v0, v1
	v_min_f32_e32 v1, 0, v0
	v_mul_f32_e64 v0, |v0|, s11
	v_exp_f32_e32 v0, v0
	s_nop 0
	v_add_f32_e32 v0, 1.0, v0
	v_cmp_gt_f32_e32 vcc, s12, v0
	s_nop 1
	v_cndmask_b32_e64 v2, 0, 32, vcc
	v_ldexp_f32 v0, v0, v2
	v_log_f32_e32 v0, v0
	s_nop 0
	v_mul_f32_e32 v2, 0x3f317217, v0
	v_fma_f32 v2, v0, s13, -v2
	v_fmac_f32_e32 v2, 0x3377d1cf, v0
	v_fmac_f32_e32 v2, 0x3f317217, v0
	v_cmp_lt_f32_e64 s[0:1], |v0|, s36
	s_nop 1
	v_cndmask_b32_e64 v0, v0, v2, s[0:1]
	v_cndmask_b32_e32 v2, 0, v60, vcc
	v_sub_f32_e32 v0, v0, v2
	v_sub_f32_e32 v0, v1, v0
	v_fmamk_f32 v70, v0, 0x3d800000, v54
	ds_read_b128 v[0:3], v5 offset:128
	s_waitcnt lgkmcnt(0)
	v_fma_f32 v71, v65, v0, v69
	v_fmac_f32_e32 v71, v66, v1
	v_fmac_f32_e32 v71, v67, v2
	v_fmac_f32_e32 v71, v68, v3
	ds_read_b128 v[0:3], v5 offset:144
	s_waitcnt lgkmcnt(0)
	v_fmac_f32_e32 v71, v55, v0
	v_fmac_f32_e32 v71, v62, v1
	v_fmac_f32_e32 v71, v63, v2
	v_fmac_f32_e32 v71, v64, v3
	ds_read_b128 v[0:3], v5 offset:160
	s_waitcnt lgkmcnt(0)
	v_fmac_f32_e32 v71, v52, v0
	v_fmac_f32_e32 v71, v53, v1
	v_fmac_f32_e32 v71, v50, v2
	v_fmac_f32_e32 v71, v51, v3
	ds_read_b128 v[0:3], v5 offset:176
	s_waitcnt lgkmcnt(0)
	v_pk_mul_f32 v[0:1], v[48:49], v[0:1]
	s_nop 0
	v_add_f32_e32 v0, v71, v0
	v_add_f32_e32 v71, v0, v1
	v_pk_mul_f32 v[0:1], v[46:47], v[2:3]
	s_nop 0
	v_add_f32_e32 v0, v71, v0
	v_add_f32_e32 v0, v0, v1
	v_min_f32_e32 v1, 0, v0
	v_mul_f32_e64 v0, |v0|, s11
	v_exp_f32_e32 v0, v0
	s_nop 0
	v_add_f32_e32 v0, 1.0, v0
	v_cmp_gt_f32_e32 vcc, s12, v0
	s_nop 1
	v_cndmask_b32_e64 v2, 0, 32, vcc
	v_ldexp_f32 v0, v0, v2
	v_log_f32_e32 v0, v0
	s_nop 0
	v_mul_f32_e32 v2, 0x3f317217, v0
	v_fma_f32 v2, v0, s13, -v2
	v_fmac_f32_e32 v2, 0x3377d1cf, v0
	v_fmac_f32_e32 v2, 0x3f317217, v0
	v_cmp_lt_f32_e64 s[0:1], |v0|, s36
	s_nop 1
	v_cndmask_b32_e64 v0, v0, v2, s[0:1]
	v_cndmask_b32_e32 v2, 0, v60, vcc
	v_sub_f32_e32 v0, v0, v2
	v_sub_f32_e32 v0, v1, v0
	v_fmamk_f32 v71, v0, 0x3d800000, v70
	ds_read_b128 v[0:3], v5 offset:192
	s_waitcnt lgkmcnt(0)
	v_fma_f32 v72, v65, v0, v69
	v_fmac_f32_e32 v72, v66, v1
	v_fmac_f32_e32 v72, v67, v2
	v_fmac_f32_e32 v72, v68, v3
	ds_read_b128 v[0:3], v5 offset:208
	s_waitcnt lgkmcnt(0)
	v_fmac_f32_e32 v72, v55, v0
	v_fmac_f32_e32 v72, v62, v1
	v_fmac_f32_e32 v72, v63, v2
	v_fmac_f32_e32 v72, v64, v3
	ds_read_b128 v[0:3], v5 offset:224
	s_waitcnt lgkmcnt(0)
	v_fmac_f32_e32 v72, v52, v0
	v_fmac_f32_e32 v72, v53, v1
	v_fmac_f32_e32 v72, v50, v2
	v_fmac_f32_e32 v72, v51, v3
	ds_read_b128 v[0:3], v5 offset:240
	s_waitcnt lgkmcnt(0)
	v_pk_mul_f32 v[0:1], v[48:49], v[0:1]
	s_nop 0
	v_add_f32_e32 v0, v72, v0
	v_add_f32_e32 v72, v0, v1
	v_pk_mul_f32 v[0:1], v[46:47], v[2:3]
	s_nop 0
	v_add_f32_e32 v0, v72, v0
	v_add_f32_e32 v0, v0, v1
	v_min_f32_e32 v1, 0, v0
	v_mul_f32_e64 v0, |v0|, s11
	v_exp_f32_e32 v0, v0
	s_nop 0
	v_add_f32_e32 v0, 1.0, v0
	v_cmp_gt_f32_e32 vcc, s12, v0
	s_nop 1
	v_cndmask_b32_e64 v2, 0, 32, vcc
	v_ldexp_f32 v0, v0, v2
	v_log_f32_e32 v0, v0
	s_nop 0
	v_mul_f32_e32 v2, 0x3f317217, v0
	v_fma_f32 v2, v0, s13, -v2
	v_fmac_f32_e32 v2, 0x3377d1cf, v0
	v_fmac_f32_e32 v2, 0x3f317217, v0
	v_cmp_lt_f32_e64 s[0:1], |v0|, s36
	s_nop 1
	v_cndmask_b32_e64 v0, v0, v2, s[0:1]
	v_cndmask_b32_e32 v2, 0, v60, vcc
	v_sub_f32_e32 v0, v0, v2
	v_sub_f32_e32 v0, v1, v0
	v_fmamk_f32 v72, v0, 0x3d800000, v71
	ds_read_b128 v[0:3], v5 offset:256
	s_waitcnt lgkmcnt(0)
	v_fma_f32 v73, v65, v0, v69
	v_fmac_f32_e32 v73, v66, v1
	v_fmac_f32_e32 v73, v67, v2
	v_fmac_f32_e32 v73, v68, v3
	ds_read_b128 v[0:3], v5 offset:272
	s_waitcnt lgkmcnt(0)
	v_fmac_f32_e32 v73, v55, v0
	v_fmac_f32_e32 v73, v62, v1
	v_fmac_f32_e32 v73, v63, v2
	v_fmac_f32_e32 v73, v64, v3
	ds_read_b128 v[0:3], v5 offset:288
	s_waitcnt lgkmcnt(0)
	v_fmac_f32_e32 v73, v52, v0
	v_fmac_f32_e32 v73, v53, v1
	v_fmac_f32_e32 v73, v50, v2
	v_fmac_f32_e32 v73, v51, v3
	ds_read_b128 v[0:3], v5 offset:304
	s_waitcnt lgkmcnt(0)
	v_pk_mul_f32 v[0:1], v[48:49], v[0:1]
	s_nop 0
	v_add_f32_e32 v0, v73, v0
	v_add_f32_e32 v73, v0, v1
	v_pk_mul_f32 v[0:1], v[46:47], v[2:3]
	s_nop 0
	v_add_f32_e32 v0, v73, v0
	v_add_f32_e32 v0, v0, v1
	v_min_f32_e32 v1, 0, v0
	v_mul_f32_e64 v0, |v0|, s11
	v_exp_f32_e32 v0, v0
	s_nop 0
	v_add_f32_e32 v0, 1.0, v0
	v_cmp_gt_f32_e32 vcc, s12, v0
	s_nop 1
	v_cndmask_b32_e64 v2, 0, 32, vcc
	v_ldexp_f32 v0, v0, v2
	v_log_f32_e32 v0, v0
	s_nop 0
	v_mul_f32_e32 v2, 0x3f317217, v0
	v_fma_f32 v2, v0, s13, -v2
	v_fmac_f32_e32 v2, 0x3377d1cf, v0
	v_fmac_f32_e32 v2, 0x3f317217, v0
	v_cmp_lt_f32_e64 s[0:1], |v0|, s36
	s_nop 1
	v_cndmask_b32_e64 v0, v0, v2, s[0:1]
	v_cndmask_b32_e32 v2, 0, v60, vcc
	v_sub_f32_e32 v0, v0, v2
	v_sub_f32_e32 v0, v1, v0
	v_fmamk_f32 v73, v0, 0x3d800000, v72
	ds_read_b128 v[0:3], v5 offset:320
	s_waitcnt lgkmcnt(0)
	v_fma_f32 v74, v65, v0, v69
	v_fmac_f32_e32 v74, v66, v1
	v_fmac_f32_e32 v74, v67, v2
	v_fmac_f32_e32 v74, v68, v3
	ds_read_b128 v[0:3], v5 offset:336
	s_waitcnt lgkmcnt(0)
	v_fmac_f32_e32 v74, v55, v0
	v_fmac_f32_e32 v74, v62, v1
	v_fmac_f32_e32 v74, v63, v2
	v_fmac_f32_e32 v74, v64, v3
	ds_read_b128 v[0:3], v5 offset:352
	s_waitcnt lgkmcnt(0)
; __device__ __forceinline__ float log_sigmoid(float x) { return fminf(x, 0.f) - __logf(1.f + __expf(-fabsf(x))); }
; __device__ __forceinline__ void gla_prep_item(LAS unsigned char* lds, int item, const bf16_t* Z, const float* W2, const float* Bg, bf16_t* KDT, float* DEC) {
;     ...
;     for (int t = 0; t < 64; ++t) {
;         float x = bias;
; #pragma unroll
;         for (int r = 0; r < 16; ++r) x += zgs[t * 16 + r] * w[r];
;         gv[t] = log_sigmoid(x) * (1.f / 16.f); bend += gv[t];
	v_fmac_f32_e32 v74, v52, v0
	v_fmac_f32_e32 v74, v53, v1
	v_fmac_f32_e32 v74, v50, v2
	v_fmac_f32_e32 v74, v51, v3
	ds_read_b128 v[0:3], v5 offset:368
	s_waitcnt lgkmcnt(0)
	v_pk_mul_f32 v[0:1], v[48:49], v[0:1]
	s_nop 0
	v_add_f32_e32 v0, v74, v0
	v_add_f32_e32 v74, v0, v1
	v_pk_mul_f32 v[0:1], v[46:47], v[2:3]
	s_nop 0
	v_add_f32_e32 v0, v74, v0
	v_add_f32_e32 v0, v0, v1
	v_min_f32_e32 v1, 0, v0
	v_mul_f32_e64 v0, |v0|, s11
	v_exp_f32_e32 v0, v0
	s_nop 0
	v_add_f32_e32 v0, 1.0, v0
	v_cmp_gt_f32_e32 vcc, s12, v0
	s_nop 1
	v_cndmask_b32_e64 v2, 0, 32, vcc
	v_ldexp_f32 v0, v0, v2
	v_log_f32_e32 v0, v0
	s_nop 0
	v_mul_f32_e32 v2, 0x3f317217, v0
	v_fma_f32 v2, v0, s13, -v2
	v_fmac_f32_e32 v2, 0x3377d1cf, v0
	v_fmac_f32_e32 v2, 0x3f317217, v0
	v_cmp_lt_f32_e64 s[0:1], |v0|, s36
	s_nop 1
	v_cndmask_b32_e64 v0, v0, v2, s[0:1]
	v_cndmask_b32_e32 v2, 0, v60, vcc
	v_sub_f32_e32 v0, v0, v2
	v_sub_f32_e32 v0, v1, v0
	v_fmamk_f32 v74, v0, 0x3d800000, v73
	ds_read_b128 v[0:3], v5 offset:384
	s_waitcnt lgkmcnt(0)
	v_fma_f32 v75, v65, v0, v69
	v_fmac_f32_e32 v75, v66, v1
	v_fmac_f32_e32 v75, v67, v2
	v_fmac_f32_e32 v75, v68, v3
	ds_read_b128 v[0:3], v5 offset:400
	s_waitcnt lgkmcnt(0)
	v_fmac_f32_e32 v75, v55, v0
	v_fmac_f32_e32 v75, v62, v1
	v_fmac_f32_e32 v75, v63, v2
	v_fmac_f32_e32 v75, v64, v3
	ds_read_b128 v[0:3], v5 offset:416
	s_waitcnt lgkmcnt(0)
	v_fmac_f32_e32 v75, v52, v0
	v_fmac_f32_e32 v75, v53, v1
	v_fmac_f32_e32 v75, v50, v2
	v_fmac_f32_e32 v75, v51, v3
	ds_read_b128 v[0:3], v5 offset:432
	s_waitcnt lgkmcnt(0)
	v_pk_mul_f32 v[0:1], v[48:49], v[0:1]
	s_nop 0
	v_add_f32_e32 v0, v75, v0
	v_add_f32_e32 v75, v0, v1
	v_pk_mul_f32 v[0:1], v[46:47], v[2:3]
	s_nop 0
	v_add_f32_e32 v0, v75, v0
	v_add_f32_e32 v0, v0, v1
	v_min_f32_e32 v1, 0, v0
	v_mul_f32_e64 v0, |v0|, s11
	v_exp_f32_e32 v0, v0
	s_nop 0
	v_add_f32_e32 v0, 1.0, v0
	v_cmp_gt_f32_e32 vcc, s12, v0
	s_nop 1
	v_cndmask_b32_e64 v2, 0, 32, vcc
	v_ldexp_f32 v0, v0, v2
	v_log_f32_e32 v0, v0
	s_nop 0
	v_mul_f32_e32 v2, 0x3f317217, v0
	v_fma_f32 v2, v0, s13, -v2
	v_fmac_f32_e32 v2, 0x3377d1cf, v0
	v_fmac_f32_e32 v2, 0x3f317217, v0
	v_cmp_lt_f32_e64 s[0:1], |v0|, s36
	s_nop 1
	v_cndmask_b32_e64 v0, v0, v2, s[0:1]
	v_cndmask_b32_e32 v2, 0, v60, vcc
	v_sub_f32_e32 v0, v0, v2
	v_sub_f32_e32 v0, v1, v0
	v_fmamk_f32 v75, v0, 0x3d800000, v74
	ds_read_b128 v[0:3], v5 offset:448
	s_waitcnt lgkmcnt(0)
	v_fma_f32 v76, v65, v0, v69
	v_fmac_f32_e32 v76, v66, v1
	v_fmac_f32_e32 v76, v67, v2
	v_fmac_f32_e32 v76, v68, v3
	ds_read_b128 v[0:3], v5 offset:464
	s_waitcnt lgkmcnt(0)
	v_fmac_f32_e32 v76, v55, v0
	v_fmac_f32_e32 v76, v62, v1
	v_fmac_f32_e32 v76, v63, v2
	v_fmac_f32_e32 v76, v64, v3
	ds_read_b128 v[0:3], v5 offset:480
	s_waitcnt lgkmcnt(0)
	v_fmac_f32_e32 v76, v52, v0
	v_fmac_f32_e32 v76, v53, v1
	v_fmac_f32_e32 v76, v50, v2
	v_fmac_f32_e32 v76, v51, v3
	ds_read_b128 v[0:3], v5 offset:496
	s_waitcnt lgkmcnt(0)
	v_pk_mul_f32 v[0:1], v[48:49], v[0:1]
	s_nop 0
	v_add_f32_e32 v0, v76, v0
	v_add_f32_e32 v76, v0, v1
	v_pk_mul_f32 v[0:1], v[46:47], v[2:3]
	s_nop 0
	v_add_f32_e32 v0, v76, v0
	v_add_f32_e32 v0, v0, v1
	v_min_f32_e32 v1, 0, v0
	v_mul_f32_e64 v0, |v0|, s11
	v_exp_f32_e32 v0, v0
	s_nop 0
	v_add_f32_e32 v0, 1.0, v0
	v_cmp_gt_f32_e32 vcc, s12, v0
	s_nop 1
	v_cndmask_b32_e64 v2, 0, 32, vcc
	v_ldexp_f32 v0, v0, v2
	v_log_f32_e32 v0, v0
	s_nop 0
	v_mul_f32_e32 v2, 0x3f317217, v0
	v_fma_f32 v2, v0, s13, -v2
	v_fmac_f32_e32 v2, 0x3377d1cf, v0
	v_fmac_f32_e32 v2, 0x3f317217, v0
	v_cmp_lt_f32_e64 s[0:1], |v0|, s36
	s_nop 1
	v_cndmask_b32_e64 v0, v0, v2, s[0:1]
	v_cndmask_b32_e32 v2, 0, v60, vcc
	v_sub_f32_e32 v0, v0, v2
	v_sub_f32_e32 v0, v1, v0
	v_fmamk_f32 v77, v0, 0x3d800000, v75
	ds_read_b128 v[0:3], v5 offset:512
	s_waitcnt lgkmcnt(0)
	v_fma_f32 v76, v65, v0, v69
	v_fmac_f32_e32 v76, v66, v1
	v_fmac_f32_e32 v76, v67, v2
	v_fmac_f32_e32 v76, v68, v3
	ds_read_b128 v[0:3], v5 offset:528
	s_waitcnt lgkmcnt(0)
	v_fmac_f32_e32 v76, v55, v0
	v_fmac_f32_e32 v76, v62, v1
	v_fmac_f32_e32 v76, v63, v2
	v_fmac_f32_e32 v76, v64, v3
	ds_read_b128 v[0:3], v5 offset:544
	s_waitcnt lgkmcnt(0)
	v_fmac_f32_e32 v76, v52, v0
	v_fmac_f32_e32 v76, v53, v1
	v_fmac_f32_e32 v76, v50, v2
	v_fmac_f32_e32 v76, v51, v3
	ds_read_b128 v[0:3], v5 offset:560
	s_waitcnt lgkmcnt(0)
	v_pk_mul_f32 v[0:1], v[48:49], v[0:1]
	s_nop 0
	v_add_f32_e32 v0, v76, v0
	v_add_f32_e32 v76, v0, v1
	v_pk_mul_f32 v[0:1], v[46:47], v[2:3]
	s_nop 0
	v_add_f32_e32 v0, v76, v0
	v_add_f32_e32 v0, v0, v1
	v_min_f32_e32 v1, 0, v0
	v_mul_f32_e64 v0, |v0|, s11
	v_exp_f32_e32 v0, v0
	s_nop 0
	v_add_f32_e32 v0, 1.0, v0
	v_cmp_gt_f32_e32 vcc, s12, v0
	s_nop 1
	v_cndmask_b32_e64 v2, 0, 32, vcc
	v_ldexp_f32 v0, v0, v2
	v_log_f32_e32 v0, v0
	s_nop 0
	v_mul_f32_e32 v2, 0x3f317217, v0
	v_fma_f32 v2, v0, s13, -v2
	v_fmac_f32_e32 v2, 0x3377d1cf, v0
	v_fmac_f32_e32 v2, 0x3f317217, v0
	v_cmp_lt_f32_e64 s[0:1], |v0|, s36
	s_nop 1
	v_cndmask_b32_e64 v0, v0, v2, s[0:1]
	v_cndmask_b32_e32 v2, 0, v60, vcc
	v_sub_f32_e32 v0, v0, v2
	v_sub_f32_e32 v0, v1, v0
	v_fmamk_f32 v76, v0, 0x3d800000, v77
	ds_read_b128 v[0:3], v5 offset:576
	s_waitcnt lgkmcnt(0)
	v_fma_f32 v78, v65, v0, v69
	v_fmac_f32_e32 v78, v66, v1
	v_fmac_f32_e32 v78, v67, v2
	v_fmac_f32_e32 v78, v68, v3
	ds_read_b128 v[0:3], v5 offset:592
	s_waitcnt lgkmcnt(0)
	v_fmac_f32_e32 v78, v55, v0
	v_fmac_f32_e32 v78, v62, v1
	v_fmac_f32_e32 v78, v63, v2
	v_fmac_f32_e32 v78, v64, v3
	ds_read_b128 v[0:3], v5 offset:608
	s_waitcnt lgkmcnt(0)
	v_fmac_f32_e32 v78, v52, v0
	v_fmac_f32_e32 v78, v53, v1
	v_fmac_f32_e32 v78, v50, v2
	v_fmac_f32_e32 v78, v51, v3
	ds_read_b128 v[0:3], v5 offset:624
	s_waitcnt lgkmcnt(0)
; __device__ __forceinline__ float log_sigmoid(float x) { return fminf(x, 0.f) - __logf(1.f + __expf(-fabsf(x))); }
; __device__ __forceinline__ void gla_prep_item(LAS unsigned char* lds, int item, const bf16_t* Z, const float* W2, const float* Bg, bf16_t* KDT, float* DEC) {
;     ...
;     for (int t = 0; t < 64; ++t) {
;         float x = bias;
; #pragma unroll
;         for (int r = 0; r < 16; ++r) x += zgs[t * 16 + r] * w[r];
;         gv[t] = log_sigmoid(x) * (1.f / 16.f); bend += gv[t];
	v_pk_mul_f32 v[0:1], v[48:49], v[0:1]
	s_nop 0
	v_add_f32_e32 v0, v78, v0
	v_add_f32_e32 v78, v0, v1
	v_pk_mul_f32 v[0:1], v[46:47], v[2:3]
	s_nop 0
	v_add_f32_e32 v0, v78, v0
	v_add_f32_e32 v0, v0, v1
	v_min_f32_e32 v1, 0, v0
	v_mul_f32_e64 v0, |v0|, s11
	v_exp_f32_e32 v0, v0
	s_nop 0
	v_add_f32_e32 v0, 1.0, v0
	v_cmp_gt_f32_e32 vcc, s12, v0
	s_nop 1
	v_cndmask_b32_e64 v2, 0, 32, vcc
	v_ldexp_f32 v0, v0, v2
	v_log_f32_e32 v0, v0
	s_nop 0
	v_mul_f32_e32 v2, 0x3f317217, v0
	v_fma_f32 v2, v0, s13, -v2
	v_fmac_f32_e32 v2, 0x3377d1cf, v0
	v_fmac_f32_e32 v2, 0x3f317217, v0
	v_cmp_lt_f32_e64 s[0:1], |v0|, s36
	s_nop 1
	v_cndmask_b32_e64 v0, v0, v2, s[0:1]
	v_cndmask_b32_e32 v2, 0, v60, vcc
	v_sub_f32_e32 v0, v0, v2
	v_sub_f32_e32 v0, v1, v0
	v_fmamk_f32 v78, v0, 0x3d800000, v76
	ds_read_b128 v[0:3], v5 offset:640
	s_waitcnt lgkmcnt(0)
	v_fma_f32 v79, v65, v0, v69
	v_fmac_f32_e32 v79, v66, v1
	v_fmac_f32_e32 v79, v67, v2
	v_fmac_f32_e32 v79, v68, v3
	ds_read_b128 v[0:3], v5 offset:656
	s_waitcnt lgkmcnt(0)
	v_fmac_f32_e32 v79, v55, v0
	v_fmac_f32_e32 v79, v62, v1
	v_fmac_f32_e32 v79, v63, v2
	v_fmac_f32_e32 v79, v64, v3
	ds_read_b128 v[0:3], v5 offset:672
	s_waitcnt lgkmcnt(0)
	v_fmac_f32_e32 v79, v52, v0
	v_fmac_f32_e32 v79, v53, v1
	v_fmac_f32_e32 v79, v50, v2
	v_fmac_f32_e32 v79, v51, v3
	ds_read_b128 v[0:3], v5 offset:688
	s_waitcnt lgkmcnt(0)
	v_pk_mul_f32 v[0:1], v[48:49], v[0:1]
	s_nop 0
	v_add_f32_e32 v0, v79, v0
	v_add_f32_e32 v79, v0, v1
	v_pk_mul_f32 v[0:1], v[46:47], v[2:3]
	s_nop 0
	v_add_f32_e32 v0, v79, v0
	v_add_f32_e32 v0, v0, v1
	v_min_f32_e32 v1, 0, v0
	v_mul_f32_e64 v0, |v0|, s11
	v_exp_f32_e32 v0, v0
	s_nop 0
	v_add_f32_e32 v0, 1.0, v0
	v_cmp_gt_f32_e32 vcc, s12, v0
	s_nop 1
	v_cndmask_b32_e64 v2, 0, 32, vcc
	v_ldexp_f32 v0, v0, v2
	v_log_f32_e32 v0, v0
	s_nop 0
	v_mul_f32_e32 v2, 0x3f317217, v0
	v_fma_f32 v2, v0, s13, -v2
	v_fmac_f32_e32 v2, 0x3377d1cf, v0
	v_fmac_f32_e32 v2, 0x3f317217, v0
	v_cmp_lt_f32_e64 s[0:1], |v0|, s36
	s_nop 1
	v_cndmask_b32_e64 v0, v0, v2, s[0:1]
	v_cndmask_b32_e32 v2, 0, v60, vcc
	v_sub_f32_e32 v0, v0, v2
	v_sub_f32_e32 v0, v1, v0
	v_fmamk_f32 v79, v0, 0x3d800000, v78
	ds_read_b128 v[0:3], v5 offset:704
	s_waitcnt lgkmcnt(0)
	v_fma_f32 v80, v65, v0, v69
	v_fmac_f32_e32 v80, v66, v1
	v_fmac_f32_e32 v80, v67, v2
	v_fmac_f32_e32 v80, v68, v3
	ds_read_b128 v[0:3], v5 offset:720
	s_waitcnt lgkmcnt(0)
	v_fmac_f32_e32 v80, v55, v0
	v_fmac_f32_e32 v80, v62, v1
	v_fmac_f32_e32 v80, v63, v2
	v_fmac_f32_e32 v80, v64, v3
	ds_read_b128 v[0:3], v5 offset:736
	s_waitcnt lgkmcnt(0)
	v_fmac_f32_e32 v80, v52, v0
	v_fmac_f32_e32 v80, v53, v1
	v_fmac_f32_e32 v80, v50, v2
	v_fmac_f32_e32 v80, v51, v3
	ds_read_b128 v[0:3], v5 offset:752
	s_waitcnt lgkmcnt(0)
	v_pk_mul_f32 v[0:1], v[48:49], v[0:1]
	s_nop 0
	v_add_f32_e32 v0, v80, v0
	v_add_f32_e32 v80, v0, v1
	v_pk_mul_f32 v[0:1], v[46:47], v[2:3]
	s_nop 0
	v_add_f32_e32 v0, v80, v0
	v_add_f32_e32 v0, v0, v1
	v_min_f32_e32 v1, 0, v0
	v_mul_f32_e64 v0, |v0|, s11
	v_exp_f32_e32 v0, v0
	s_nop 0
	v_add_f32_e32 v0, 1.0, v0
	v_cmp_gt_f32_e32 vcc, s12, v0
	s_nop 1
	v_cndmask_b32_e64 v2, 0, 32, vcc
	v_ldexp_f32 v0, v0, v2
	v_log_f32_e32 v0, v0
	s_nop 0
	v_mul_f32_e32 v2, 0x3f317217, v0
	v_fma_f32 v2, v0, s13, -v2
	v_fmac_f32_e32 v2, 0x3377d1cf, v0
	v_fmac_f32_e32 v2, 0x3f317217, v0
	v_cmp_lt_f32_e64 s[0:1], |v0|, s36
	s_nop 1
	v_cndmask_b32_e64 v0, v0, v2, s[0:1]
	v_cndmask_b32_e32 v2, 0, v60, vcc
	v_sub_f32_e32 v0, v0, v2
	v_sub_f32_e32 v0, v1, v0
	v_fmamk_f32 v80, v0, 0x3d800000, v79
	ds_read_b128 v[0:3], v5 offset:768
	s_waitcnt lgkmcnt(0)
	v_fma_f32 v81, v65, v0, v69
	v_fmac_f32_e32 v81, v66, v1
	v_fmac_f32_e32 v81, v67, v2
	v_fmac_f32_e32 v81, v68, v3
	ds_read_b128 v[0:3], v5 offset:784
	s_waitcnt lgkmcnt(0)
	v_fmac_f32_e32 v81, v55, v0
	v_fmac_f32_e32 v81, v62, v1
	v_fmac_f32_e32 v81, v63, v2
	v_fmac_f32_e32 v81, v64, v3
	ds_read_b128 v[0:3], v5 offset:800
	s_waitcnt lgkmcnt(0)
	v_fmac_f32_e32 v81, v52, v0
	v_fmac_f32_e32 v81, v53, v1
	v_fmac_f32_e32 v81, v50, v2
	v_fmac_f32_e32 v81, v51, v3
	ds_read_b128 v[0:3], v5 offset:816
	s_waitcnt lgkmcnt(0)
	v_pk_mul_f32 v[0:1], v[48:49], v[0:1]
	s_nop 0
	v_add_f32_e32 v0, v81, v0
	v_add_f32_e32 v81, v0, v1
	v_pk_mul_f32 v[0:1], v[46:47], v[2:3]
	s_nop 0
	v_add_f32_e32 v0, v81, v0
	v_add_f32_e32 v0, v0, v1
	v_min_f32_e32 v1, 0, v0
	v_mul_f32_e64 v0, |v0|, s11
	v_exp_f32_e32 v0, v0
	s_nop 0
	v_add_f32_e32 v0, 1.0, v0
	v_cmp_gt_f32_e32 vcc, s12, v0
	s_nop 1
	v_cndmask_b32_e64 v2, 0, 32, vcc
	v_ldexp_f32 v0, v0, v2
	v_log_f32_e32 v0, v0
	s_nop 0
	v_mul_f32_e32 v2, 0x3f317217, v0
	v_fma_f32 v2, v0, s13, -v2
	v_fmac_f32_e32 v2, 0x3377d1cf, v0
	v_fmac_f32_e32 v2, 0x3f317217, v0
	v_cmp_lt_f32_e64 s[0:1], |v0|, s36
	s_nop 1
	v_cndmask_b32_e64 v0, v0, v2, s[0:1]
	v_cndmask_b32_e32 v2, 0, v60, vcc
	v_sub_f32_e32 v0, v0, v2
	v_sub_f32_e32 v0, v1, v0
	v_fmamk_f32 v81, v0, 0x3d800000, v80
	ds_read_b128 v[0:3], v5 offset:832
	s_waitcnt lgkmcnt(0)
	v_fma_f32 v82, v65, v0, v69
	v_fmac_f32_e32 v82, v66, v1
	v_fmac_f32_e32 v82, v67, v2
	v_fmac_f32_e32 v82, v68, v3
	ds_read_b128 v[0:3], v5 offset:848
	s_waitcnt lgkmcnt(0)
	v_fmac_f32_e32 v82, v55, v0
	v_fmac_f32_e32 v82, v62, v1
	v_fmac_f32_e32 v82, v63, v2
	v_fmac_f32_e32 v82, v64, v3
	ds_read_b128 v[0:3], v5 offset:864
	s_waitcnt lgkmcnt(0)
	v_fmac_f32_e32 v82, v52, v0
	v_fmac_f32_e32 v82, v53, v1
	v_fmac_f32_e32 v82, v50, v2
	v_fmac_f32_e32 v82, v51, v3
	ds_read_b128 v[0:3], v5 offset:880
	s_waitcnt lgkmcnt(0)
; __device__ __forceinline__ float log_sigmoid(float x) { return fminf(x, 0.f) - __logf(1.f + __expf(-fabsf(x))); }
; __device__ __forceinline__ void gla_prep_item(LAS unsigned char* lds, int item, const bf16_t* Z, const float* W2, const float* Bg, bf16_t* KDT, float* DEC) {
;     ...
;     for (int t = 0; t < 64; ++t) {
;         float x = bias;
; #pragma unroll
;         for (int r = 0; r < 16; ++r) x += zgs[t * 16 + r] * w[r];
;         gv[t] = log_sigmoid(x) * (1.f / 16.f); bend += gv[t];
	v_pk_mul_f32 v[0:1], v[48:49], v[0:1]
	s_nop 0
	v_add_f32_e32 v0, v82, v0
	v_add_f32_e32 v82, v0, v1
	v_pk_mul_f32 v[0:1], v[46:47], v[2:3]
	s_nop 0
	v_add_f32_e32 v0, v82, v0
	v_add_f32_e32 v0, v0, v1
	v_min_f32_e32 v1, 0, v0
	v_mul_f32_e64 v0, |v0|, s11
	v_exp_f32_e32 v0, v0
	s_nop 0
	v_add_f32_e32 v0, 1.0, v0
	v_cmp_gt_f32_e32 vcc, s12, v0
	s_nop 1
	v_cndmask_b32_e64 v2, 0, 32, vcc
	v_ldexp_f32 v0, v0, v2
	v_log_f32_e32 v0, v0
	s_nop 0
	v_mul_f32_e32 v2, 0x3f317217, v0
	v_fma_f32 v2, v0, s13, -v2
	v_fmac_f32_e32 v2, 0x3377d1cf, v0
	v_fmac_f32_e32 v2, 0x3f317217, v0
	v_cmp_lt_f32_e64 s[0:1], |v0|, s36
	s_nop 1
	v_cndmask_b32_e64 v0, v0, v2, s[0:1]
	v_cndmask_b32_e32 v2, 0, v60, vcc
	v_sub_f32_e32 v0, v0, v2
	v_sub_f32_e32 v0, v1, v0
	v_fmamk_f32 v82, v0, 0x3d800000, v81
	ds_read_b128 v[0:3], v5 offset:896
	s_waitcnt lgkmcnt(0)
	v_fma_f32 v83, v65, v0, v69
	v_fmac_f32_e32 v83, v66, v1
	v_fmac_f32_e32 v83, v67, v2
	v_fmac_f32_e32 v83, v68, v3
	ds_read_b128 v[0:3], v5 offset:912
	s_waitcnt lgkmcnt(0)
	v_fmac_f32_e32 v83, v55, v0
	v_fmac_f32_e32 v83, v62, v1
	v_fmac_f32_e32 v83, v63, v2
	v_fmac_f32_e32 v83, v64, v3
	ds_read_b128 v[0:3], v5 offset:928
	s_waitcnt lgkmcnt(0)
	v_fmac_f32_e32 v83, v52, v0
	v_fmac_f32_e32 v83, v53, v1
	v_fmac_f32_e32 v83, v50, v2
	v_fmac_f32_e32 v83, v51, v3
	ds_read_b128 v[0:3], v5 offset:944
	s_waitcnt lgkmcnt(0)
	v_pk_mul_f32 v[0:1], v[48:49], v[0:1]
	s_nop 0
	v_add_f32_e32 v0, v83, v0
	v_add_f32_e32 v83, v0, v1
	v_pk_mul_f32 v[0:1], v[46:47], v[2:3]
	s_nop 0
	v_add_f32_e32 v0, v83, v0
	v_add_f32_e32 v0, v0, v1
	v_min_f32_e32 v1, 0, v0
	v_mul_f32_e64 v0, |v0|, s11
	v_exp_f32_e32 v0, v0
	s_nop 0
	v_add_f32_e32 v0, 1.0, v0
	v_cmp_gt_f32_e32 vcc, s12, v0
	s_nop 1
	v_cndmask_b32_e64 v2, 0, 32, vcc
	v_ldexp_f32 v0, v0, v2
	v_log_f32_e32 v0, v0
	s_nop 0
	v_mul_f32_e32 v2, 0x3f317217, v0
	v_fma_f32 v2, v0, s13, -v2
	v_fmac_f32_e32 v2, 0x3377d1cf, v0
	v_fmac_f32_e32 v2, 0x3f317217, v0
	v_cmp_lt_f32_e64 s[0:1], |v0|, s36
	s_nop 1
	v_cndmask_b32_e64 v0, v0, v2, s[0:1]
	v_cndmask_b32_e32 v2, 0, v60, vcc
	v_sub_f32_e32 v0, v0, v2
	v_sub_f32_e32 v0, v1, v0
	v_fmamk_f32 v83, v0, 0x3d800000, v82
	ds_read_b128 v[0:3], v5 offset:960
	s_waitcnt lgkmcnt(0)
	v_fma_f32 v84, v65, v0, v69
	v_fmac_f32_e32 v84, v66, v1
	v_fmac_f32_e32 v84, v67, v2
	v_fmac_f32_e32 v84, v68, v3
	ds_read_b128 v[0:3], v5 offset:976
	s_waitcnt lgkmcnt(0)
	v_fmac_f32_e32 v84, v55, v0
	v_fmac_f32_e32 v84, v62, v1
	v_fmac_f32_e32 v84, v63, v2
	v_fmac_f32_e32 v84, v64, v3
	ds_read_b128 v[0:3], v5 offset:992
	s_waitcnt lgkmcnt(0)
	v_fmac_f32_e32 v84, v52, v0
	v_fmac_f32_e32 v84, v53, v1
	v_fmac_f32_e32 v84, v50, v2
	v_fmac_f32_e32 v84, v51, v3
	ds_read_b128 v[0:3], v5 offset:1008
	s_waitcnt lgkmcnt(0)
	v_pk_mul_f32 v[0:1], v[48:49], v[0:1]
	s_nop 0
	v_add_f32_e32 v0, v84, v0
	v_add_f32_e32 v84, v0, v1
	v_pk_mul_f32 v[0:1], v[46:47], v[2:3]
	s_nop 0
	v_add_f32_e32 v0, v84, v0
	v_add_f32_e32 v0, v0, v1
	v_min_f32_e32 v1, 0, v0
	v_mul_f32_e64 v0, |v0|, s11
	v_exp_f32_e32 v0, v0
	s_nop 0
	v_add_f32_e32 v0, 1.0, v0
	v_cmp_gt_f32_e32 vcc, s12, v0
	s_nop 1
	v_cndmask_b32_e64 v2, 0, 32, vcc
	v_ldexp_f32 v0, v0, v2
	v_log_f32_e32 v0, v0
	s_nop 0
	v_mul_f32_e32 v2, 0x3f317217, v0
	v_fma_f32 v2, v0, s13, -v2
	v_fmac_f32_e32 v2, 0x3377d1cf, v0
	v_fmac_f32_e32 v2, 0x3f317217, v0
	v_cmp_lt_f32_e64 s[0:1], |v0|, s36
	s_nop 1
	v_cndmask_b32_e64 v0, v0, v2, s[0:1]
	v_cndmask_b32_e32 v2, 0, v60, vcc
	v_sub_f32_e32 v0, v0, v2
	v_sub_f32_e32 v0, v1, v0
	v_fmamk_f32 v84, v0, 0x3d800000, v83
	ds_read_b128 v[0:3], v5 offset:1024
	s_waitcnt lgkmcnt(0)
	v_fma_f32 v85, v65, v0, v69
	v_fmac_f32_e32 v85, v66, v1
	v_fmac_f32_e32 v85, v67, v2
	v_fmac_f32_e32 v85, v68, v3
	ds_read_b128 v[0:3], v5 offset:1040
	s_waitcnt lgkmcnt(0)
	v_fmac_f32_e32 v85, v55, v0
	v_fmac_f32_e32 v85, v62, v1
	v_fmac_f32_e32 v85, v63, v2
	v_fmac_f32_e32 v85, v64, v3
	ds_read_b128 v[0:3], v5 offset:1056
	s_waitcnt lgkmcnt(0)
	v_fmac_f32_e32 v85, v52, v0
	v_fmac_f32_e32 v85, v53, v1
	v_fmac_f32_e32 v85, v50, v2
	v_fmac_f32_e32 v85, v51, v3
	ds_read_b128 v[0:3], v5 offset:1072
	s_waitcnt lgkmcnt(0)
	v_pk_mul_f32 v[0:1], v[48:49], v[0:1]
	s_nop 0
	v_add_f32_e32 v0, v85, v0
	v_add_f32_e32 v85, v0, v1
	v_pk_mul_f32 v[0:1], v[46:47], v[2:3]
	s_nop 0
	v_add_f32_e32 v0, v85, v0
	v_add_f32_e32 v0, v0, v1
	v_min_f32_e32 v1, 0, v0
	v_mul_f32_e64 v0, |v0|, s11
	v_exp_f32_e32 v0, v0
	s_nop 0
	v_add_f32_e32 v0, 1.0, v0
	v_cmp_gt_f32_e32 vcc, s12, v0
	s_nop 1
	v_cndmask_b32_e64 v2, 0, 32, vcc
	v_ldexp_f32 v0, v0, v2
	v_log_f32_e32 v0, v0
	s_nop 0
	v_mul_f32_e32 v2, 0x3f317217, v0
	v_fma_f32 v2, v0, s13, -v2
	v_fmac_f32_e32 v2, 0x3377d1cf, v0
	v_fmac_f32_e32 v2, 0x3f317217, v0
	v_cmp_lt_f32_e64 s[0:1], |v0|, s36
	s_nop 1
	v_cndmask_b32_e64 v0, v0, v2, s[0:1]
	v_cndmask_b32_e32 v2, 0, v60, vcc
	v_sub_f32_e32 v0, v0, v2
	v_sub_f32_e32 v0, v1, v0
	v_fmamk_f32 v85, v0, 0x3d800000, v84
	ds_read_b128 v[0:3], v5 offset:1088
	s_waitcnt lgkmcnt(0)
	v_fma_f32 v86, v65, v0, v69
	v_fmac_f32_e32 v86, v66, v1
	v_fmac_f32_e32 v86, v67, v2
	v_fmac_f32_e32 v86, v68, v3
	ds_read_b128 v[0:3], v5 offset:1104
	s_waitcnt lgkmcnt(0)
	v_fmac_f32_e32 v86, v55, v0
	v_fmac_f32_e32 v86, v62, v1
	v_fmac_f32_e32 v86, v63, v2
	v_fmac_f32_e32 v86, v64, v3
	ds_read_b128 v[0:3], v5 offset:1120
	s_waitcnt lgkmcnt(0)
	v_fmac_f32_e32 v86, v52, v0
	v_fmac_f32_e32 v86, v53, v1
	v_fmac_f32_e32 v86, v50, v2
	v_fmac_f32_e32 v86, v51, v3
	ds_read_b128 v[0:3], v5 offset:1136
	s_waitcnt lgkmcnt(0)
; __device__ __forceinline__ float log_sigmoid(float x) { return fminf(x, 0.f) - __logf(1.f + __expf(-fabsf(x))); }
; __device__ __forceinline__ void gla_prep_item(LAS unsigned char* lds, int item, const bf16_t* Z, const float* W2, const float* Bg, bf16_t* KDT, float* DEC) {
;     ...
;     for (int t = 0; t < 64; ++t) {
;         float x = bias;
; #pragma unroll
;         for (int r = 0; r < 16; ++r) x += zgs[t * 16 + r] * w[r];
;         gv[t] = log_sigmoid(x) * (1.f / 16.f); bend += gv[t];
	v_pk_mul_f32 v[0:1], v[48:49], v[0:1]
	s_nop 0
	v_add_f32_e32 v0, v86, v0
	v_add_f32_e32 v86, v0, v1
	v_pk_mul_f32 v[0:1], v[46:47], v[2:3]
	s_nop 0
	v_add_f32_e32 v0, v86, v0
	v_add_f32_e32 v0, v0, v1
	v_min_f32_e32 v1, 0, v0
	v_mul_f32_e64 v0, |v0|, s11
	v_exp_f32_e32 v0, v0
	s_nop 0
	v_add_f32_e32 v0, 1.0, v0
	v_cmp_gt_f32_e32 vcc, s12, v0
	s_nop 1
	v_cndmask_b32_e64 v2, 0, 32, vcc
	v_ldexp_f32 v0, v0, v2
	v_log_f32_e32 v0, v0
	s_nop 0
	v_mul_f32_e32 v2, 0x3f317217, v0
	v_fma_f32 v2, v0, s13, -v2
	v_fmac_f32_e32 v2, 0x3377d1cf, v0
	v_fmac_f32_e32 v2, 0x3f317217, v0
	v_cmp_lt_f32_e64 s[0:1], |v0|, s36
	s_nop 1
	v_cndmask_b32_e64 v0, v0, v2, s[0:1]
	v_cndmask_b32_e32 v2, 0, v60, vcc
	v_sub_f32_e32 v0, v0, v2
	v_sub_f32_e32 v0, v1, v0
	v_fmamk_f32 v86, v0, 0x3d800000, v85
	ds_read_b128 v[0:3], v5 offset:1152
	s_waitcnt lgkmcnt(0)
	v_fma_f32 v87, v65, v0, v69
	v_fmac_f32_e32 v87, v66, v1
	v_fmac_f32_e32 v87, v67, v2
	v_fmac_f32_e32 v87, v68, v3
	ds_read_b128 v[0:3], v5 offset:1168
	s_waitcnt lgkmcnt(0)
	v_fmac_f32_e32 v87, v55, v0
	v_fmac_f32_e32 v87, v62, v1
	v_fmac_f32_e32 v87, v63, v2
	v_fmac_f32_e32 v87, v64, v3
	ds_read_b128 v[0:3], v5 offset:1184
	s_waitcnt lgkmcnt(0)
	v_fmac_f32_e32 v87, v52, v0
	v_fmac_f32_e32 v87, v53, v1
	v_fmac_f32_e32 v87, v50, v2
	v_fmac_f32_e32 v87, v51, v3
	ds_read_b128 v[0:3], v5 offset:1200
	s_waitcnt lgkmcnt(0)
	v_pk_mul_f32 v[0:1], v[48:49], v[0:1]
	s_nop 0
	v_add_f32_e32 v0, v87, v0
	v_add_f32_e32 v87, v0, v1
	v_pk_mul_f32 v[0:1], v[46:47], v[2:3]
	s_nop 0
	v_add_f32_e32 v0, v87, v0
	v_add_f32_e32 v0, v0, v1
	v_min_f32_e32 v1, 0, v0
	v_mul_f32_e64 v0, |v0|, s11
	v_exp_f32_e32 v0, v0
	s_nop 0
	v_add_f32_e32 v0, 1.0, v0
	v_cmp_gt_f32_e32 vcc, s12, v0
	s_nop 1
	v_cndmask_b32_e64 v2, 0, 32, vcc
	v_ldexp_f32 v0, v0, v2
	v_log_f32_e32 v0, v0
	s_nop 0
	v_mul_f32_e32 v2, 0x3f317217, v0
	v_fma_f32 v2, v0, s13, -v2
	v_fmac_f32_e32 v2, 0x3377d1cf, v0
	v_fmac_f32_e32 v2, 0x3f317217, v0
	v_cmp_lt_f32_e64 s[0:1], |v0|, s36
	s_nop 1
	v_cndmask_b32_e64 v0, v0, v2, s[0:1]
	v_cndmask_b32_e32 v2, 0, v60, vcc
	v_sub_f32_e32 v0, v0, v2
	v_sub_f32_e32 v0, v1, v0
	v_fmamk_f32 v87, v0, 0x3d800000, v86
	ds_read_b128 v[0:3], v5 offset:1216
	s_waitcnt lgkmcnt(0)
	v_fma_f32 v88, v65, v0, v69
	v_fmac_f32_e32 v88, v66, v1
	v_fmac_f32_e32 v88, v67, v2
	v_fmac_f32_e32 v88, v68, v3
	ds_read_b128 v[0:3], v5 offset:1232
	s_waitcnt lgkmcnt(0)
	v_fmac_f32_e32 v88, v55, v0
	v_fmac_f32_e32 v88, v62, v1
	v_fmac_f32_e32 v88, v63, v2
	v_fmac_f32_e32 v88, v64, v3
	ds_read_b128 v[0:3], v5 offset:1248
	s_waitcnt lgkmcnt(0)
	v_fmac_f32_e32 v88, v52, v0
	v_fmac_f32_e32 v88, v53, v1
	v_fmac_f32_e32 v88, v50, v2
	v_fmac_f32_e32 v88, v51, v3
	ds_read_b128 v[0:3], v5 offset:1264
	s_waitcnt lgkmcnt(0)
	v_pk_mul_f32 v[0:1], v[48:49], v[0:1]
	s_nop 0
	v_add_f32_e32 v0, v88, v0
	v_add_f32_e32 v88, v0, v1
	v_pk_mul_f32 v[0:1], v[46:47], v[2:3]
	s_nop 0
	v_add_f32_e32 v0, v88, v0
	v_add_f32_e32 v0, v0, v1
	v_min_f32_e32 v1, 0, v0
	v_mul_f32_e64 v0, |v0|, s11
	v_exp_f32_e32 v0, v0
	s_nop 0
	v_add_f32_e32 v0, 1.0, v0
	v_cmp_gt_f32_e32 vcc, s12, v0
	s_nop 1
	v_cndmask_b32_e64 v2, 0, 32, vcc
	v_ldexp_f32 v0, v0, v2
	v_log_f32_e32 v0, v0
	s_nop 0
	v_mul_f32_e32 v2, 0x3f317217, v0
	v_fma_f32 v2, v0, s13, -v2
	v_fmac_f32_e32 v2, 0x3377d1cf, v0
	v_fmac_f32_e32 v2, 0x3f317217, v0
	v_cmp_lt_f32_e64 s[0:1], |v0|, s36
	s_nop 1
	v_cndmask_b32_e64 v0, v0, v2, s[0:1]
	v_cndmask_b32_e32 v2, 0, v60, vcc
	v_sub_f32_e32 v0, v0, v2
	v_sub_f32_e32 v0, v1, v0
	v_fmamk_f32 v88, v0, 0x3d800000, v87
	ds_read_b128 v[0:3], v5 offset:1280
	s_waitcnt lgkmcnt(0)
	v_fma_f32 v89, v65, v0, v69
	v_fmac_f32_e32 v89, v66, v1
	v_fmac_f32_e32 v89, v67, v2
	v_fmac_f32_e32 v89, v68, v3
	ds_read_b128 v[0:3], v5 offset:1296
	s_waitcnt lgkmcnt(0)
	v_fmac_f32_e32 v89, v55, v0
	v_fmac_f32_e32 v89, v62, v1
	v_fmac_f32_e32 v89, v63, v2
	v_fmac_f32_e32 v89, v64, v3
	ds_read_b128 v[0:3], v5 offset:1312
	s_waitcnt lgkmcnt(0)
	v_fmac_f32_e32 v89, v52, v0
	v_fmac_f32_e32 v89, v53, v1
	v_fmac_f32_e32 v89, v50, v2
	v_fmac_f32_e32 v89, v51, v3
	ds_read_b128 v[0:3], v5 offset:1328
	s_waitcnt lgkmcnt(0)
	v_pk_mul_f32 v[0:1], v[48:49], v[0:1]
	s_nop 0
	v_add_f32_e32 v0, v89, v0
	v_add_f32_e32 v89, v0, v1
	v_pk_mul_f32 v[0:1], v[46:47], v[2:3]
	s_nop 0
	v_add_f32_e32 v0, v89, v0
	v_add_f32_e32 v0, v0, v1
	v_min_f32_e32 v1, 0, v0
	v_mul_f32_e64 v0, |v0|, s11
	v_exp_f32_e32 v0, v0
	s_nop 0
	v_add_f32_e32 v0, 1.0, v0
	v_cmp_gt_f32_e32 vcc, s12, v0
	s_nop 1
	v_cndmask_b32_e64 v2, 0, 32, vcc
	v_ldexp_f32 v0, v0, v2
	v_log_f32_e32 v0, v0
	s_nop 0
	v_mul_f32_e32 v2, 0x3f317217, v0
	v_fma_f32 v2, v0, s13, -v2
	v_fmac_f32_e32 v2, 0x3377d1cf, v0
	v_fmac_f32_e32 v2, 0x3f317217, v0
	v_cmp_lt_f32_e64 s[0:1], |v0|, s36
	s_nop 1
	v_cndmask_b32_e64 v0, v0, v2, s[0:1]
	v_cndmask_b32_e32 v2, 0, v60, vcc
	v_sub_f32_e32 v0, v0, v2
	v_sub_f32_e32 v0, v1, v0
	v_fmamk_f32 v89, v0, 0x3d800000, v88
	ds_read_b128 v[0:3], v5 offset:1344
	s_waitcnt lgkmcnt(0)
	v_fma_f32 v90, v65, v0, v69
	v_fmac_f32_e32 v90, v66, v1
	v_fmac_f32_e32 v90, v67, v2
	v_fmac_f32_e32 v90, v68, v3
	ds_read_b128 v[0:3], v5 offset:1360
	s_waitcnt lgkmcnt(0)
	v_fmac_f32_e32 v90, v55, v0
	v_fmac_f32_e32 v90, v62, v1
	v_fmac_f32_e32 v90, v63, v2
	v_fmac_f32_e32 v90, v64, v3
	ds_read_b128 v[0:3], v5 offset:1376
	s_waitcnt lgkmcnt(0)
	v_fmac_f32_e32 v90, v52, v0
	v_fmac_f32_e32 v90, v53, v1
	v_fmac_f32_e32 v90, v50, v2
	v_fmac_f32_e32 v90, v51, v3
	ds_read_b128 v[0:3], v5 offset:1392
	s_waitcnt lgkmcnt(0)
; __device__ __forceinline__ float log_sigmoid(float x) { return fminf(x, 0.f) - __logf(1.f + __expf(-fabsf(x))); }
; __device__ __forceinline__ void gla_prep_item(LAS unsigned char* lds, int item, const bf16_t* Z, const float* W2, const float* Bg, bf16_t* KDT, float* DEC) {
;     ...
;     for (int t = 0; t < 64; ++t) {
;         float x = bias;
; #pragma unroll
;         for (int r = 0; r < 16; ++r) x += zgs[t * 16 + r] * w[r];
;         gv[t] = log_sigmoid(x) * (1.f / 16.f); bend += gv[t];
	v_pk_mul_f32 v[0:1], v[48:49], v[0:1]
	s_nop 0
	v_add_f32_e32 v0, v90, v0
	v_add_f32_e32 v90, v0, v1
	v_pk_mul_f32 v[0:1], v[46:47], v[2:3]
	s_nop 0
	v_add_f32_e32 v0, v90, v0
	v_add_f32_e32 v0, v0, v1
	v_min_f32_e32 v1, 0, v0
	v_mul_f32_e64 v0, |v0|, s11
	v_exp_f32_e32 v0, v0
	s_nop 0
	v_add_f32_e32 v0, 1.0, v0
	v_cmp_gt_f32_e32 vcc, s12, v0
	s_nop 1
	v_cndmask_b32_e64 v2, 0, 32, vcc
	v_ldexp_f32 v0, v0, v2
	v_log_f32_e32 v0, v0
	s_nop 0
	v_mul_f32_e32 v2, 0x3f317217, v0
	v_fma_f32 v2, v0, s13, -v2
	v_fmac_f32_e32 v2, 0x3377d1cf, v0
	v_fmac_f32_e32 v2, 0x3f317217, v0
	v_cmp_lt_f32_e64 s[0:1], |v0|, s36
	s_nop 1
	v_cndmask_b32_e64 v0, v0, v2, s[0:1]
	v_cndmask_b32_e32 v2, 0, v60, vcc
	v_sub_f32_e32 v0, v0, v2
	v_sub_f32_e32 v0, v1, v0
	v_fmamk_f32 v90, v0, 0x3d800000, v89
	ds_read_b128 v[0:3], v5 offset:1408
	s_waitcnt lgkmcnt(0)
	v_fma_f32 v91, v65, v0, v69
	v_fmac_f32_e32 v91, v66, v1
	v_fmac_f32_e32 v91, v67, v2
	v_fmac_f32_e32 v91, v68, v3
	ds_read_b128 v[0:3], v5 offset:1424
	s_waitcnt lgkmcnt(0)
	v_fmac_f32_e32 v91, v55, v0
	v_fmac_f32_e32 v91, v62, v1
	v_fmac_f32_e32 v91, v63, v2
	v_fmac_f32_e32 v91, v64, v3
	ds_read_b128 v[0:3], v5 offset:1440
	s_waitcnt lgkmcnt(0)
	v_fmac_f32_e32 v91, v52, v0
	v_fmac_f32_e32 v91, v53, v1
	v_fmac_f32_e32 v91, v50, v2
	v_fmac_f32_e32 v91, v51, v3
	ds_read_b128 v[0:3], v5 offset:1456
	s_waitcnt lgkmcnt(0)
	v_pk_mul_f32 v[0:1], v[48:49], v[0:1]
	s_nop 0
	v_add_f32_e32 v0, v91, v0
	v_add_f32_e32 v91, v0, v1
	v_pk_mul_f32 v[0:1], v[46:47], v[2:3]
	s_nop 0
	v_add_f32_e32 v0, v91, v0
	v_add_f32_e32 v0, v0, v1
	v_min_f32_e32 v1, 0, v0
	v_mul_f32_e64 v0, |v0|, s11
	v_exp_f32_e32 v0, v0
	s_nop 0
	v_add_f32_e32 v0, 1.0, v0
	v_cmp_gt_f32_e32 vcc, s12, v0
	s_nop 1
	v_cndmask_b32_e64 v2, 0, 32, vcc
	v_ldexp_f32 v0, v0, v2
	v_log_f32_e32 v0, v0
	s_nop 0
	v_mul_f32_e32 v2, 0x3f317217, v0
	v_fma_f32 v2, v0, s13, -v2
	v_fmac_f32_e32 v2, 0x3377d1cf, v0
	v_fmac_f32_e32 v2, 0x3f317217, v0
	v_cmp_lt_f32_e64 s[0:1], |v0|, s36
	s_nop 1
	v_cndmask_b32_e64 v0, v0, v2, s[0:1]
	v_cndmask_b32_e32 v2, 0, v60, vcc
	v_sub_f32_e32 v0, v0, v2
	v_sub_f32_e32 v0, v1, v0
	v_fmamk_f32 v91, v0, 0x3d800000, v90
	ds_read_b128 v[0:3], v5 offset:1472
	s_waitcnt lgkmcnt(0)
	v_fma_f32 v92, v65, v0, v69
	v_fmac_f32_e32 v92, v66, v1
	v_fmac_f32_e32 v92, v67, v2
	v_fmac_f32_e32 v92, v68, v3
	ds_read_b128 v[0:3], v5 offset:1488
	s_waitcnt lgkmcnt(0)
	v_fmac_f32_e32 v92, v55, v0
	v_fmac_f32_e32 v92, v62, v1
	v_fmac_f32_e32 v92, v63, v2
	v_fmac_f32_e32 v92, v64, v3
	ds_read_b128 v[0:3], v5 offset:1504
	s_waitcnt lgkmcnt(0)
	v_fmac_f32_e32 v92, v52, v0
	v_fmac_f32_e32 v92, v53, v1
	v_fmac_f32_e32 v92, v50, v2
	v_fmac_f32_e32 v92, v51, v3
	ds_read_b128 v[0:3], v5 offset:1520
	s_waitcnt lgkmcnt(0)
	v_pk_mul_f32 v[0:1], v[48:49], v[0:1]
	s_nop 0
	v_add_f32_e32 v0, v92, v0
	v_add_f32_e32 v92, v0, v1
	v_pk_mul_f32 v[0:1], v[46:47], v[2:3]
	s_nop 0
	v_add_f32_e32 v0, v92, v0
	v_add_f32_e32 v0, v0, v1
	v_min_f32_e32 v1, 0, v0
	v_mul_f32_e64 v0, |v0|, s11
	v_exp_f32_e32 v0, v0
	s_nop 0
	v_add_f32_e32 v0, 1.0, v0
	v_cmp_gt_f32_e32 vcc, s12, v0
	s_nop 1
	v_cndmask_b32_e64 v2, 0, 32, vcc
	v_ldexp_f32 v0, v0, v2
	v_log_f32_e32 v0, v0
	s_nop 0
	v_mul_f32_e32 v2, 0x3f317217, v0
	v_fma_f32 v2, v0, s13, -v2
	v_fmac_f32_e32 v2, 0x3377d1cf, v0
	v_fmac_f32_e32 v2, 0x3f317217, v0
	v_cmp_lt_f32_e64 s[0:1], |v0|, s36
	s_nop 1
	v_cndmask_b32_e64 v0, v0, v2, s[0:1]
	v_cndmask_b32_e32 v2, 0, v60, vcc
	v_sub_f32_e32 v0, v0, v2
	v_sub_f32_e32 v0, v1, v0
	v_fmamk_f32 v92, v0, 0x3d800000, v91
	ds_read_b128 v[0:3], v5 offset:1536
	s_waitcnt lgkmcnt(0)
	v_fma_f32 v93, v65, v0, v69
	v_fmac_f32_e32 v93, v66, v1
	v_fmac_f32_e32 v93, v67, v2
	v_fmac_f32_e32 v93, v68, v3
	ds_read_b128 v[0:3], v5 offset:1552
	s_waitcnt lgkmcnt(0)
	v_fmac_f32_e32 v93, v55, v0
	v_fmac_f32_e32 v93, v62, v1
	v_fmac_f32_e32 v93, v63, v2
	v_fmac_f32_e32 v93, v64, v3
	ds_read_b128 v[0:3], v5 offset:1568
	s_waitcnt lgkmcnt(0)
	v_fmac_f32_e32 v93, v52, v0
	v_fmac_f32_e32 v93, v53, v1
	v_fmac_f32_e32 v93, v50, v2
	v_fmac_f32_e32 v93, v51, v3
	ds_read_b128 v[0:3], v5 offset:1584
	s_waitcnt lgkmcnt(0)
	v_pk_mul_f32 v[0:1], v[48:49], v[0:1]
	s_nop 0
	v_add_f32_e32 v0, v93, v0
	v_add_f32_e32 v93, v0, v1
	v_pk_mul_f32 v[0:1], v[46:47], v[2:3]
	s_nop 0
	v_add_f32_e32 v0, v93, v0
	v_add_f32_e32 v0, v0, v1
	v_min_f32_e32 v1, 0, v0
	v_mul_f32_e64 v0, |v0|, s11
	v_exp_f32_e32 v0, v0
	s_nop 0
	v_add_f32_e32 v0, 1.0, v0
	v_cmp_gt_f32_e32 vcc, s12, v0
	s_nop 1
	v_cndmask_b32_e64 v2, 0, 32, vcc
	v_ldexp_f32 v0, v0, v2
	v_log_f32_e32 v0, v0
	s_nop 0
	v_mul_f32_e32 v2, 0x3f317217, v0
	v_fma_f32 v2, v0, s13, -v2
	v_fmac_f32_e32 v2, 0x3377d1cf, v0
	v_fmac_f32_e32 v2, 0x3f317217, v0
	v_cmp_lt_f32_e64 s[0:1], |v0|, s36
	s_nop 1
	v_cndmask_b32_e64 v0, v0, v2, s[0:1]
	v_cndmask_b32_e32 v2, 0, v60, vcc
	v_sub_f32_e32 v0, v0, v2
	v_sub_f32_e32 v0, v1, v0
	v_fmamk_f32 v93, v0, 0x3d800000, v92
	ds_read_b128 v[0:3], v5 offset:1600
	s_waitcnt lgkmcnt(0)
	v_fma_f32 v94, v65, v0, v69
	v_fmac_f32_e32 v94, v66, v1
	v_fmac_f32_e32 v94, v67, v2
	v_fmac_f32_e32 v94, v68, v3
	ds_read_b128 v[0:3], v5 offset:1616
	s_waitcnt lgkmcnt(0)
	v_fmac_f32_e32 v94, v55, v0
	v_fmac_f32_e32 v94, v62, v1
	v_fmac_f32_e32 v94, v63, v2
	v_fmac_f32_e32 v94, v64, v3
	ds_read_b128 v[0:3], v5 offset:1632
	s_waitcnt lgkmcnt(0)
	v_fmac_f32_e32 v94, v52, v0
	v_fmac_f32_e32 v94, v53, v1
	v_fmac_f32_e32 v94, v50, v2
	v_fmac_f32_e32 v94, v51, v3
	ds_read_b128 v[0:3], v5 offset:1648
	s_waitcnt lgkmcnt(0)
; __device__ __forceinline__ float log_sigmoid(float x) { return fminf(x, 0.f) - __logf(1.f + __expf(-fabsf(x))); }
; __device__ __forceinline__ void gla_prep_item(LAS unsigned char* lds, int item, const bf16_t* Z, const float* W2, const float* Bg, bf16_t* KDT, float* DEC) {
;     ...
;     for (int t = 0; t < 64; ++t) {
;         float x = bias;
; #pragma unroll
;         for (int r = 0; r < 16; ++r) x += zgs[t * 16 + r] * w[r];
;         gv[t] = log_sigmoid(x) * (1.f / 16.f); bend += gv[t];
	v_pk_mul_f32 v[0:1], v[48:49], v[0:1]
	s_nop 0
	v_add_f32_e32 v0, v94, v0
	v_add_f32_e32 v94, v0, v1
	v_pk_mul_f32 v[0:1], v[46:47], v[2:3]
	s_nop 0
	v_add_f32_e32 v0, v94, v0
	v_add_f32_e32 v0, v0, v1
	v_min_f32_e32 v1, 0, v0
	v_mul_f32_e64 v0, |v0|, s11
	v_exp_f32_e32 v0, v0
	s_nop 0
	v_add_f32_e32 v0, 1.0, v0
	v_cmp_gt_f32_e32 vcc, s12, v0
	s_nop 1
	v_cndmask_b32_e64 v2, 0, 32, vcc
	v_ldexp_f32 v0, v0, v2
	v_log_f32_e32 v0, v0
	s_nop 0
	v_mul_f32_e32 v2, 0x3f317217, v0
	v_fma_f32 v2, v0, s13, -v2
	v_fmac_f32_e32 v2, 0x3377d1cf, v0
	v_fmac_f32_e32 v2, 0x3f317217, v0
	v_cmp_lt_f32_e64 s[0:1], |v0|, s36
	s_nop 1
	v_cndmask_b32_e64 v0, v0, v2, s[0:1]
	v_cndmask_b32_e32 v2, 0, v60, vcc
	v_sub_f32_e32 v0, v0, v2
	v_sub_f32_e32 v0, v1, v0
	v_fmamk_f32 v94, v0, 0x3d800000, v93
	ds_read_b128 v[0:3], v5 offset:1664
	s_waitcnt lgkmcnt(0)
	v_fma_f32 v95, v65, v0, v69
	v_fmac_f32_e32 v95, v66, v1
	v_fmac_f32_e32 v95, v67, v2
	v_fmac_f32_e32 v95, v68, v3
	ds_read_b128 v[0:3], v5 offset:1680
	s_waitcnt lgkmcnt(0)
	v_fmac_f32_e32 v95, v55, v0
	v_fmac_f32_e32 v95, v62, v1
	v_fmac_f32_e32 v95, v63, v2
	v_fmac_f32_e32 v95, v64, v3
	ds_read_b128 v[0:3], v5 offset:1696
	s_waitcnt lgkmcnt(0)
	v_fmac_f32_e32 v95, v52, v0
	v_fmac_f32_e32 v95, v53, v1
	v_fmac_f32_e32 v95, v50, v2
	v_fmac_f32_e32 v95, v51, v3
	ds_read_b128 v[0:3], v5 offset:1712
	s_waitcnt lgkmcnt(0)
	v_pk_mul_f32 v[0:1], v[48:49], v[0:1]
	s_nop 0
	v_add_f32_e32 v0, v95, v0
	v_add_f32_e32 v95, v0, v1
	v_pk_mul_f32 v[0:1], v[46:47], v[2:3]
	s_nop 0
	v_add_f32_e32 v0, v95, v0
	v_add_f32_e32 v0, v0, v1
	v_min_f32_e32 v1, 0, v0
	v_mul_f32_e64 v0, |v0|, s11
	v_exp_f32_e32 v0, v0
	s_nop 0
	v_add_f32_e32 v0, 1.0, v0
	v_cmp_gt_f32_e32 vcc, s12, v0
	s_nop 1
	v_cndmask_b32_e64 v2, 0, 32, vcc
	v_ldexp_f32 v0, v0, v2
	v_log_f32_e32 v0, v0
	s_nop 0
	v_mul_f32_e32 v2, 0x3f317217, v0
	v_fma_f32 v2, v0, s13, -v2
	v_fmac_f32_e32 v2, 0x3377d1cf, v0
	v_fmac_f32_e32 v2, 0x3f317217, v0
	v_cmp_lt_f32_e64 s[0:1], |v0|, s36
	s_nop 1
	v_cndmask_b32_e64 v0, v0, v2, s[0:1]
	v_cndmask_b32_e32 v2, 0, v60, vcc
	v_sub_f32_e32 v0, v0, v2
	v_sub_f32_e32 v0, v1, v0
	v_fmamk_f32 v95, v0, 0x3d800000, v94
	ds_read_b128 v[0:3], v5 offset:1728
	s_waitcnt lgkmcnt(0)
	v_fma_f32 v96, v65, v0, v69
	v_fmac_f32_e32 v96, v66, v1
	v_fmac_f32_e32 v96, v67, v2
	v_fmac_f32_e32 v96, v68, v3
	ds_read_b128 v[0:3], v5 offset:1744
	s_waitcnt lgkmcnt(0)
	v_fmac_f32_e32 v96, v55, v0
	v_fmac_f32_e32 v96, v62, v1
	v_fmac_f32_e32 v96, v63, v2
	v_fmac_f32_e32 v96, v64, v3
	ds_read_b128 v[0:3], v5 offset:1760
	s_waitcnt lgkmcnt(0)
	v_fmac_f32_e32 v96, v52, v0
	v_fmac_f32_e32 v96, v53, v1
	v_fmac_f32_e32 v96, v50, v2
	v_fmac_f32_e32 v96, v51, v3
	ds_read_b128 v[0:3], v5 offset:1776
	s_waitcnt lgkmcnt(0)
	v_pk_mul_f32 v[0:1], v[48:49], v[0:1]
	s_nop 0
	v_add_f32_e32 v0, v96, v0
	v_add_f32_e32 v96, v0, v1
	v_pk_mul_f32 v[0:1], v[46:47], v[2:3]
	s_nop 0
	v_add_f32_e32 v0, v96, v0
	v_add_f32_e32 v0, v0, v1
	v_min_f32_e32 v1, 0, v0
	v_mul_f32_e64 v0, |v0|, s11
	v_exp_f32_e32 v0, v0
	s_nop 0
	v_add_f32_e32 v0, 1.0, v0
	v_cmp_gt_f32_e32 vcc, s12, v0
	s_nop 1
	v_cndmask_b32_e64 v2, 0, 32, vcc
	v_ldexp_f32 v0, v0, v2
	v_log_f32_e32 v0, v0
	s_nop 0
	v_mul_f32_e32 v2, 0x3f317217, v0
	v_fma_f32 v2, v0, s13, -v2
	v_fmac_f32_e32 v2, 0x3377d1cf, v0
	v_fmac_f32_e32 v2, 0x3f317217, v0
	v_cmp_lt_f32_e64 s[0:1], |v0|, s36
	s_nop 1
	v_cndmask_b32_e64 v0, v0, v2, s[0:1]
	v_cndmask_b32_e32 v2, 0, v60, vcc
	v_sub_f32_e32 v0, v0, v2
	v_sub_f32_e32 v0, v1, v0
	v_fmamk_f32 v96, v0, 0x3d800000, v95
	ds_read_b128 v[0:3], v5 offset:1792
	s_waitcnt lgkmcnt(0)
	v_fma_f32 v97, v65, v0, v69
	v_fmac_f32_e32 v97, v66, v1
	v_fmac_f32_e32 v97, v67, v2
	v_fmac_f32_e32 v97, v68, v3
	ds_read_b128 v[0:3], v5 offset:1808
	s_waitcnt lgkmcnt(0)
	v_fmac_f32_e32 v97, v55, v0
	v_fmac_f32_e32 v97, v62, v1
	v_fmac_f32_e32 v97, v63, v2
	v_fmac_f32_e32 v97, v64, v3
	ds_read_b128 v[0:3], v5 offset:1824
	s_waitcnt lgkmcnt(0)
	v_fmac_f32_e32 v97, v52, v0
	v_fmac_f32_e32 v97, v53, v1
	v_fmac_f32_e32 v97, v50, v2
	v_fmac_f32_e32 v97, v51, v3
	ds_read_b128 v[0:3], v5 offset:1840
	s_waitcnt lgkmcnt(0)
	v_pk_mul_f32 v[0:1], v[48:49], v[0:1]
	s_nop 0
	v_add_f32_e32 v0, v97, v0
	v_add_f32_e32 v97, v0, v1
	v_pk_mul_f32 v[0:1], v[46:47], v[2:3]
	s_nop 0
	v_add_f32_e32 v0, v97, v0
	v_add_f32_e32 v0, v0, v1
	v_min_f32_e32 v1, 0, v0
	v_mul_f32_e64 v0, |v0|, s11
	v_exp_f32_e32 v0, v0
	s_nop 0
	v_add_f32_e32 v0, 1.0, v0
	v_cmp_gt_f32_e32 vcc, s12, v0
	s_nop 1
	v_cndmask_b32_e64 v2, 0, 32, vcc
	v_ldexp_f32 v0, v0, v2
	v_log_f32_e32 v0, v0
	s_nop 0
	v_mul_f32_e32 v2, 0x3f317217, v0
	v_fma_f32 v2, v0, s13, -v2
	v_fmac_f32_e32 v2, 0x3377d1cf, v0
	v_fmac_f32_e32 v2, 0x3f317217, v0
	v_cmp_lt_f32_e64 s[0:1], |v0|, s36
	s_nop 1
	v_cndmask_b32_e64 v0, v0, v2, s[0:1]
	v_cndmask_b32_e32 v2, 0, v60, vcc
	v_sub_f32_e32 v0, v0, v2
	v_sub_f32_e32 v0, v1, v0
	v_fmamk_f32 v97, v0, 0x3d800000, v96
	ds_read_b128 v[0:3], v5 offset:1856
	s_waitcnt lgkmcnt(0)
	v_fma_f32 v98, v65, v0, v69
	v_fmac_f32_e32 v98, v66, v1
	v_fmac_f32_e32 v98, v67, v2
	v_fmac_f32_e32 v98, v68, v3
	ds_read_b128 v[0:3], v5 offset:1872
	s_waitcnt lgkmcnt(0)
	v_fmac_f32_e32 v98, v55, v0
	v_fmac_f32_e32 v98, v62, v1
	v_fmac_f32_e32 v98, v63, v2
	v_fmac_f32_e32 v98, v64, v3
	ds_read_b128 v[0:3], v5 offset:1888
	s_waitcnt lgkmcnt(0)
	v_fmac_f32_e32 v98, v52, v0
	v_fmac_f32_e32 v98, v53, v1
	v_fmac_f32_e32 v98, v50, v2
	v_fmac_f32_e32 v98, v51, v3
	ds_read_b128 v[0:3], v5 offset:1904
	s_waitcnt lgkmcnt(0)
; __device__ __forceinline__ float log_sigmoid(float x) { return fminf(x, 0.f) - __logf(1.f + __expf(-fabsf(x))); }
; __device__ __forceinline__ void gla_prep_item(LAS unsigned char* lds, int item, const bf16_t* Z, const float* W2, const float* Bg, bf16_t* KDT, float* DEC) {
;     ...
;     for (int t = 0; t < 64; ++t) {
;         float x = bias;
; #pragma unroll
;         for (int r = 0; r < 16; ++r) x += zgs[t * 16 + r] * w[r];
;         gv[t] = log_sigmoid(x) * (1.f / 16.f); bend += gv[t];
	v_pk_mul_f32 v[0:1], v[48:49], v[0:1]
	s_nop 0
	v_add_f32_e32 v0, v98, v0
	v_add_f32_e32 v98, v0, v1
	v_pk_mul_f32 v[0:1], v[46:47], v[2:3]
	s_nop 0
	v_add_f32_e32 v0, v98, v0
	v_add_f32_e32 v0, v0, v1
	v_min_f32_e32 v1, 0, v0
	v_mul_f32_e64 v0, |v0|, s11
	v_exp_f32_e32 v0, v0
	s_nop 0
	v_add_f32_e32 v0, 1.0, v0
	v_cmp_gt_f32_e32 vcc, s12, v0
	s_nop 1
	v_cndmask_b32_e64 v2, 0, 32, vcc
	v_ldexp_f32 v0, v0, v2
	v_log_f32_e32 v0, v0
	s_nop 0
	v_mul_f32_e32 v2, 0x3f317217, v0
	v_fma_f32 v2, v0, s13, -v2
	v_fmac_f32_e32 v2, 0x3377d1cf, v0
	v_fmac_f32_e32 v2, 0x3f317217, v0
	v_cmp_lt_f32_e64 s[0:1], |v0|, s36
	s_nop 1
	v_cndmask_b32_e64 v0, v0, v2, s[0:1]
	v_cndmask_b32_e32 v2, 0, v60, vcc
	v_sub_f32_e32 v0, v0, v2
	v_sub_f32_e32 v0, v1, v0
	v_fmamk_f32 v98, v0, 0x3d800000, v97
	ds_read_b128 v[0:3], v5 offset:1920
	s_waitcnt lgkmcnt(0)
	v_fma_f32 v99, v65, v0, v69
	v_fmac_f32_e32 v99, v66, v1
	v_fmac_f32_e32 v99, v67, v2
	v_fmac_f32_e32 v99, v68, v3
	ds_read_b128 v[0:3], v5 offset:1936
	s_waitcnt lgkmcnt(0)
	v_fmac_f32_e32 v99, v55, v0
	v_fmac_f32_e32 v99, v62, v1
	v_fmac_f32_e32 v99, v63, v2
	v_fmac_f32_e32 v99, v64, v3
	ds_read_b128 v[0:3], v5 offset:1952
	s_waitcnt lgkmcnt(0)
	v_fmac_f32_e32 v99, v52, v0
	v_fmac_f32_e32 v99, v53, v1
	v_fmac_f32_e32 v99, v50, v2
	v_fmac_f32_e32 v99, v51, v3
	ds_read_b128 v[0:3], v5 offset:1968
	s_waitcnt lgkmcnt(0)
	v_pk_mul_f32 v[0:1], v[48:49], v[0:1]
	s_nop 0
	v_add_f32_e32 v0, v99, v0
	v_add_f32_e32 v99, v0, v1
	v_pk_mul_f32 v[0:1], v[46:47], v[2:3]
	s_nop 0
	v_add_f32_e32 v0, v99, v0
	v_add_f32_e32 v0, v0, v1
	v_min_f32_e32 v1, 0, v0
	v_mul_f32_e64 v0, |v0|, s11
	v_exp_f32_e32 v0, v0
	s_nop 0
	v_add_f32_e32 v0, 1.0, v0
	v_cmp_gt_f32_e32 vcc, s12, v0
	s_nop 1
	v_cndmask_b32_e64 v2, 0, 32, vcc
	v_ldexp_f32 v0, v0, v2
	v_log_f32_e32 v0, v0
	s_nop 0
	v_mul_f32_e32 v2, 0x3f317217, v0
	v_fma_f32 v2, v0, s13, -v2
	v_fmac_f32_e32 v2, 0x3377d1cf, v0
	v_fmac_f32_e32 v2, 0x3f317217, v0
	v_cmp_lt_f32_e64 s[0:1], |v0|, s36
	s_nop 1
	v_cndmask_b32_e64 v0, v0, v2, s[0:1]
	v_cndmask_b32_e32 v2, 0, v60, vcc
	v_sub_f32_e32 v0, v0, v2
	v_sub_f32_e32 v0, v1, v0
	v_fmamk_f32 v99, v0, 0x3d800000, v98
	ds_read_b128 v[0:3], v5 offset:1984
	s_waitcnt lgkmcnt(0)
	v_fma_f32 v100, v65, v0, v69
	v_fmac_f32_e32 v100, v66, v1
	v_fmac_f32_e32 v100, v67, v2
	v_fmac_f32_e32 v100, v68, v3
	ds_read_b128 v[0:3], v5 offset:2000
	s_waitcnt lgkmcnt(0)
	v_fmac_f32_e32 v100, v55, v0
	v_fmac_f32_e32 v100, v62, v1
	v_fmac_f32_e32 v100, v63, v2
	v_fmac_f32_e32 v100, v64, v3
	ds_read_b128 v[0:3], v5 offset:2016
	s_waitcnt lgkmcnt(0)
	v_fmac_f32_e32 v100, v52, v0
	v_fmac_f32_e32 v100, v53, v1
	v_fmac_f32_e32 v100, v50, v2
	v_fmac_f32_e32 v100, v51, v3
	ds_read_b128 v[0:3], v5 offset:2032
	s_waitcnt lgkmcnt(0)
	v_pk_mul_f32 v[0:1], v[48:49], v[0:1]
	s_nop 0
	v_add_f32_e32 v0, v100, v0
	v_add_f32_e32 v100, v0, v1
	v_pk_mul_f32 v[0:1], v[46:47], v[2:3]
	s_nop 0
	v_add_f32_e32 v0, v100, v0
	v_add_f32_e32 v0, v0, v1
	v_min_f32_e32 v1, 0, v0
	v_mul_f32_e64 v0, |v0|, s11
	v_exp_f32_e32 v0, v0
	s_nop 0
	v_add_f32_e32 v0, 1.0, v0
	v_cmp_gt_f32_e32 vcc, s12, v0
	s_nop 1
	v_cndmask_b32_e64 v2, 0, 32, vcc
	v_ldexp_f32 v0, v0, v2
	v_log_f32_e32 v0, v0
	s_nop 0
	v_mul_f32_e32 v2, 0x3f317217, v0
	v_fma_f32 v2, v0, s13, -v2
	v_fmac_f32_e32 v2, 0x3377d1cf, v0
	v_fmac_f32_e32 v2, 0x3f317217, v0
	v_cmp_lt_f32_e64 s[0:1], |v0|, s36
	s_nop 1
	v_cndmask_b32_e64 v0, v0, v2, s[0:1]
	v_cndmask_b32_e32 v2, 0, v60, vcc
	v_sub_f32_e32 v0, v0, v2
	v_sub_f32_e32 v0, v1, v0
	v_fmamk_f32 v100, v0, 0x3d800000, v99
	ds_read_b128 v[0:3], v5 offset:2048
	s_waitcnt lgkmcnt(0)
	v_fma_f32 v101, v65, v0, v69
	v_fmac_f32_e32 v101, v66, v1
	v_fmac_f32_e32 v101, v67, v2
	v_fmac_f32_e32 v101, v68, v3
	ds_read_b128 v[0:3], v5 offset:2064
	s_waitcnt lgkmcnt(0)
	v_fmac_f32_e32 v101, v55, v0
	v_fmac_f32_e32 v101, v62, v1
	v_fmac_f32_e32 v101, v63, v2
	v_fmac_f32_e32 v101, v64, v3
	ds_read_b128 v[0:3], v5 offset:2080
	s_waitcnt lgkmcnt(0)
	v_fmac_f32_e32 v101, v52, v0
	v_fmac_f32_e32 v101, v53, v1
	v_fmac_f32_e32 v101, v50, v2
	v_fmac_f32_e32 v101, v51, v3
	ds_read_b128 v[0:3], v5 offset:2096
	s_waitcnt lgkmcnt(0)
	v_pk_mul_f32 v[0:1], v[48:49], v[0:1]
	s_nop 0
	v_add_f32_e32 v0, v101, v0
	v_add_f32_e32 v101, v0, v1
	v_pk_mul_f32 v[0:1], v[46:47], v[2:3]
	s_nop 0
	v_add_f32_e32 v0, v101, v0
	v_add_f32_e32 v0, v0, v1
	v_min_f32_e32 v1, 0, v0
	v_mul_f32_e64 v0, |v0|, s11
	v_exp_f32_e32 v0, v0
	s_nop 0
	v_add_f32_e32 v0, 1.0, v0
	v_cmp_gt_f32_e32 vcc, s12, v0
	s_nop 1
	v_cndmask_b32_e64 v2, 0, 32, vcc
	v_ldexp_f32 v0, v0, v2
	v_log_f32_e32 v0, v0
	s_nop 0
	v_mul_f32_e32 v2, 0x3f317217, v0
	v_fma_f32 v2, v0, s13, -v2
	v_fmac_f32_e32 v2, 0x3377d1cf, v0
	v_fmac_f32_e32 v2, 0x3f317217, v0
	v_cmp_lt_f32_e64 s[0:1], |v0|, s36
	s_nop 1
	v_cndmask_b32_e64 v0, v0, v2, s[0:1]
	v_cndmask_b32_e32 v2, 0, v60, vcc
	v_sub_f32_e32 v0, v0, v2
	v_sub_f32_e32 v0, v1, v0
	v_fmamk_f32 v101, v0, 0x3d800000, v100
	ds_read_b128 v[0:3], v5 offset:2112
	s_waitcnt lgkmcnt(0)
	v_fma_f32 v102, v65, v0, v69
	v_fmac_f32_e32 v102, v66, v1
	v_fmac_f32_e32 v102, v67, v2
	v_fmac_f32_e32 v102, v68, v3
	ds_read_b128 v[0:3], v5 offset:2128
	s_waitcnt lgkmcnt(0)
	v_fmac_f32_e32 v102, v55, v0
	v_fmac_f32_e32 v102, v62, v1
	v_fmac_f32_e32 v102, v63, v2
	v_fmac_f32_e32 v102, v64, v3
	ds_read_b128 v[0:3], v5 offset:2144
	s_waitcnt lgkmcnt(0)
	v_fmac_f32_e32 v102, v52, v0
	v_fmac_f32_e32 v102, v53, v1
	v_fmac_f32_e32 v102, v50, v2
	v_fmac_f32_e32 v102, v51, v3
	ds_read_b128 v[0:3], v5 offset:2160
	s_waitcnt lgkmcnt(0)
; __device__ __forceinline__ float log_sigmoid(float x) { return fminf(x, 0.f) - __logf(1.f + __expf(-fabsf(x))); }
; __device__ __forceinline__ void gla_prep_item(LAS unsigned char* lds, int item, const bf16_t* Z, const float* W2, const float* Bg, bf16_t* KDT, float* DEC) {
;     ...
;     for (int t = 0; t < 64; ++t) {
;         float x = bias;
; #pragma unroll
;         for (int r = 0; r < 16; ++r) x += zgs[t * 16 + r] * w[r];
;         gv[t] = log_sigmoid(x) * (1.f / 16.f); bend += gv[t];
	v_pk_mul_f32 v[0:1], v[48:49], v[0:1]
	s_nop 0
	v_add_f32_e32 v0, v102, v0
	v_add_f32_e32 v102, v0, v1
	v_pk_mul_f32 v[0:1], v[46:47], v[2:3]
	s_nop 0
	v_add_f32_e32 v0, v102, v0
	v_add_f32_e32 v0, v0, v1
	v_min_f32_e32 v1, 0, v0
	v_mul_f32_e64 v0, |v0|, s11
	v_exp_f32_e32 v0, v0
	s_nop 0
	v_add_f32_e32 v0, 1.0, v0
	v_cmp_gt_f32_e32 vcc, s12, v0
	s_nop 1
	v_cndmask_b32_e64 v2, 0, 32, vcc
	v_ldexp_f32 v0, v0, v2
	v_log_f32_e32 v0, v0
	s_nop 0
	v_mul_f32_e32 v2, 0x3f317217, v0
	v_fma_f32 v2, v0, s13, -v2
	v_fmac_f32_e32 v2, 0x3377d1cf, v0
	v_fmac_f32_e32 v2, 0x3f317217, v0
	v_cmp_lt_f32_e64 s[0:1], |v0|, s36
	s_nop 1
	v_cndmask_b32_e64 v0, v0, v2, s[0:1]
	v_cndmask_b32_e32 v2, 0, v60, vcc
	v_sub_f32_e32 v0, v0, v2
	v_sub_f32_e32 v0, v1, v0
	v_fmamk_f32 v102, v0, 0x3d800000, v101
	ds_read_b128 v[0:3], v5 offset:2176
	s_waitcnt lgkmcnt(0)
	v_fma_f32 v103, v65, v0, v69
	v_fmac_f32_e32 v103, v66, v1
	v_fmac_f32_e32 v103, v67, v2
	v_fmac_f32_e32 v103, v68, v3
	ds_read_b128 v[0:3], v5 offset:2192
	s_waitcnt lgkmcnt(0)
	v_fmac_f32_e32 v103, v55, v0
	v_fmac_f32_e32 v103, v62, v1
	v_fmac_f32_e32 v103, v63, v2
	v_fmac_f32_e32 v103, v64, v3
	ds_read_b128 v[0:3], v5 offset:2208
	s_waitcnt lgkmcnt(0)
	v_fmac_f32_e32 v103, v52, v0
	v_fmac_f32_e32 v103, v53, v1
	v_fmac_f32_e32 v103, v50, v2
	v_fmac_f32_e32 v103, v51, v3
	ds_read_b128 v[0:3], v5 offset:2224
	s_waitcnt lgkmcnt(0)
	v_pk_mul_f32 v[0:1], v[48:49], v[0:1]
	s_nop 0
	v_add_f32_e32 v0, v103, v0
	v_add_f32_e32 v103, v0, v1
	v_pk_mul_f32 v[0:1], v[46:47], v[2:3]
	s_nop 0
	v_add_f32_e32 v0, v103, v0
	v_add_f32_e32 v0, v0, v1
	v_min_f32_e32 v1, 0, v0
	v_mul_f32_e64 v0, |v0|, s11
	v_exp_f32_e32 v0, v0
	s_nop 0
	v_add_f32_e32 v0, 1.0, v0
	v_cmp_gt_f32_e32 vcc, s12, v0
	s_nop 1
	v_cndmask_b32_e64 v2, 0, 32, vcc
	v_ldexp_f32 v0, v0, v2
	v_log_f32_e32 v0, v0
	s_nop 0
	v_mul_f32_e32 v2, 0x3f317217, v0
	v_fma_f32 v2, v0, s13, -v2
	v_fmac_f32_e32 v2, 0x3377d1cf, v0
	v_fmac_f32_e32 v2, 0x3f317217, v0
	v_cmp_lt_f32_e64 s[0:1], |v0|, s36
	s_nop 1
	v_cndmask_b32_e64 v0, v0, v2, s[0:1]
	v_cndmask_b32_e32 v2, 0, v60, vcc
	v_sub_f32_e32 v0, v0, v2
	v_sub_f32_e32 v0, v1, v0
	v_fmamk_f32 v103, v0, 0x3d800000, v102
	ds_read_b128 v[0:3], v5 offset:2240
	s_waitcnt lgkmcnt(0)
	v_fma_f32 v104, v65, v0, v69
	v_fmac_f32_e32 v104, v66, v1
	v_fmac_f32_e32 v104, v67, v2
	v_fmac_f32_e32 v104, v68, v3
	ds_read_b128 v[0:3], v5 offset:2256
	s_waitcnt lgkmcnt(0)
	v_fmac_f32_e32 v104, v55, v0
	v_fmac_f32_e32 v104, v62, v1
	v_fmac_f32_e32 v104, v63, v2
	v_fmac_f32_e32 v104, v64, v3
	ds_read_b128 v[0:3], v5 offset:2272
	s_waitcnt lgkmcnt(0)
	v_fmac_f32_e32 v104, v52, v0
	v_fmac_f32_e32 v104, v53, v1
	v_fmac_f32_e32 v104, v50, v2
	v_fmac_f32_e32 v104, v51, v3
	ds_read_b128 v[0:3], v5 offset:2288
	s_waitcnt lgkmcnt(0)
	v_pk_mul_f32 v[0:1], v[48:49], v[0:1]
	s_nop 0
	v_add_f32_e32 v0, v104, v0
	v_add_f32_e32 v104, v0, v1
	v_pk_mul_f32 v[0:1], v[46:47], v[2:3]
	s_nop 0
	v_add_f32_e32 v0, v104, v0
	v_add_f32_e32 v0, v0, v1
	v_min_f32_e32 v1, 0, v0
	v_mul_f32_e64 v0, |v0|, s11
	v_exp_f32_e32 v0, v0
	s_nop 0
	v_add_f32_e32 v0, 1.0, v0
	v_cmp_gt_f32_e32 vcc, s12, v0
	s_nop 1
	v_cndmask_b32_e64 v2, 0, 32, vcc
	v_ldexp_f32 v0, v0, v2
	v_log_f32_e32 v0, v0
	s_nop 0
	v_mul_f32_e32 v2, 0x3f317217, v0
	v_fma_f32 v2, v0, s13, -v2
	v_fmac_f32_e32 v2, 0x3377d1cf, v0
	v_fmac_f32_e32 v2, 0x3f317217, v0
	v_cmp_lt_f32_e64 s[0:1], |v0|, s36
	s_nop 1
	v_cndmask_b32_e64 v0, v0, v2, s[0:1]
	v_cndmask_b32_e32 v2, 0, v60, vcc
	v_sub_f32_e32 v0, v0, v2
	v_sub_f32_e32 v0, v1, v0
	v_fmamk_f32 v104, v0, 0x3d800000, v103
	ds_read_b128 v[0:3], v5 offset:2304
	s_waitcnt lgkmcnt(0)
	v_fma_f32 v105, v65, v0, v69
	v_fmac_f32_e32 v105, v66, v1
	v_fmac_f32_e32 v105, v67, v2
	v_fmac_f32_e32 v105, v68, v3
	ds_read_b128 v[0:3], v5 offset:2320
	s_waitcnt lgkmcnt(0)
	v_fmac_f32_e32 v105, v55, v0
	v_fmac_f32_e32 v105, v62, v1
	v_fmac_f32_e32 v105, v63, v2
	v_fmac_f32_e32 v105, v64, v3
	ds_read_b128 v[0:3], v5 offset:2336
	s_waitcnt lgkmcnt(0)
	v_fmac_f32_e32 v105, v52, v0
	v_fmac_f32_e32 v105, v53, v1
	v_fmac_f32_e32 v105, v50, v2
	v_fmac_f32_e32 v105, v51, v3
	ds_read_b128 v[0:3], v5 offset:2352
	s_waitcnt lgkmcnt(0)
	v_pk_mul_f32 v[0:1], v[48:49], v[0:1]
	s_nop 0
	v_add_f32_e32 v0, v105, v0
	v_add_f32_e32 v105, v0, v1
	v_pk_mul_f32 v[0:1], v[46:47], v[2:3]
	s_nop 0
	v_add_f32_e32 v0, v105, v0
	v_add_f32_e32 v0, v0, v1
	v_min_f32_e32 v1, 0, v0
	v_mul_f32_e64 v0, |v0|, s11
	v_exp_f32_e32 v0, v0
	s_nop 0
	v_add_f32_e32 v0, 1.0, v0
	v_cmp_gt_f32_e32 vcc, s12, v0
	s_nop 1
	v_cndmask_b32_e64 v2, 0, 32, vcc
	v_ldexp_f32 v0, v0, v2
	v_log_f32_e32 v0, v0
	s_nop 0
	v_mul_f32_e32 v2, 0x3f317217, v0
	v_fma_f32 v2, v0, s13, -v2
	v_fmac_f32_e32 v2, 0x3377d1cf, v0
	v_fmac_f32_e32 v2, 0x3f317217, v0
	v_cmp_lt_f32_e64 s[0:1], |v0|, s36
	s_nop 1
	v_cndmask_b32_e64 v0, v0, v2, s[0:1]
	v_cndmask_b32_e32 v2, 0, v60, vcc
	v_sub_f32_e32 v0, v0, v2
	v_sub_f32_e32 v0, v1, v0
	v_fmamk_f32 v105, v0, 0x3d800000, v104
	ds_read_b128 v[0:3], v5 offset:2368
	s_waitcnt lgkmcnt(0)
	v_fma_f32 v106, v65, v0, v69
	v_fmac_f32_e32 v106, v66, v1
	v_fmac_f32_e32 v106, v67, v2
	v_fmac_f32_e32 v106, v68, v3
	ds_read_b128 v[0:3], v5 offset:2384
	s_waitcnt lgkmcnt(0)
	v_fmac_f32_e32 v106, v55, v0
	v_fmac_f32_e32 v106, v62, v1
	v_fmac_f32_e32 v106, v63, v2
	v_fmac_f32_e32 v106, v64, v3
	ds_read_b128 v[0:3], v5 offset:2400
	s_waitcnt lgkmcnt(0)
	v_fmac_f32_e32 v106, v52, v0
	v_fmac_f32_e32 v106, v53, v1
	v_fmac_f32_e32 v106, v50, v2
	v_fmac_f32_e32 v106, v51, v3
	ds_read_b128 v[0:3], v5 offset:2416
	s_waitcnt lgkmcnt(0)
; __device__ __forceinline__ float log_sigmoid(float x) { return fminf(x, 0.f) - __logf(1.f + __expf(-fabsf(x))); }
; __device__ __forceinline__ void gla_prep_item(LAS unsigned char* lds, int item, const bf16_t* Z, const float* W2, const float* Bg, bf16_t* KDT, float* DEC) {
;     ...
;     for (int t = 0; t < 64; ++t) {
;         float x = bias;
; #pragma unroll
;         for (int r = 0; r < 16; ++r) x += zgs[t * 16 + r] * w[r];
;         gv[t] = log_sigmoid(x) * (1.f / 16.f); bend += gv[t];
	v_pk_mul_f32 v[0:1], v[48:49], v[0:1]
	s_nop 0
	v_add_f32_e32 v0, v106, v0
	v_add_f32_e32 v106, v0, v1
	v_pk_mul_f32 v[0:1], v[46:47], v[2:3]
	s_nop 0
	v_add_f32_e32 v0, v106, v0
	v_add_f32_e32 v0, v0, v1
	v_min_f32_e32 v1, 0, v0
	v_mul_f32_e64 v0, |v0|, s11
	v_exp_f32_e32 v0, v0
	s_nop 0
	v_add_f32_e32 v0, 1.0, v0
	v_cmp_gt_f32_e32 vcc, s12, v0
	s_nop 1
	v_cndmask_b32_e64 v2, 0, 32, vcc
	v_ldexp_f32 v0, v0, v2
	v_log_f32_e32 v0, v0
	s_nop 0
	v_mul_f32_e32 v2, 0x3f317217, v0
	v_fma_f32 v2, v0, s13, -v2
	v_fmac_f32_e32 v2, 0x3377d1cf, v0
	v_fmac_f32_e32 v2, 0x3f317217, v0
	v_cmp_lt_f32_e64 s[0:1], |v0|, s36
	s_nop 1
	v_cndmask_b32_e64 v0, v0, v2, s[0:1]
	v_cndmask_b32_e32 v2, 0, v60, vcc
	v_sub_f32_e32 v0, v0, v2
	v_sub_f32_e32 v0, v1, v0
	v_fmamk_f32 v106, v0, 0x3d800000, v105
	ds_read_b128 v[0:3], v5 offset:2432
	s_waitcnt lgkmcnt(0)
	v_fma_f32 v107, v65, v0, v69
	v_fmac_f32_e32 v107, v66, v1
	v_fmac_f32_e32 v107, v67, v2
	v_fmac_f32_e32 v107, v68, v3
	ds_read_b128 v[0:3], v5 offset:2448
	s_waitcnt lgkmcnt(0)
	v_fmac_f32_e32 v107, v55, v0
	v_fmac_f32_e32 v107, v62, v1
	v_fmac_f32_e32 v107, v63, v2
	v_fmac_f32_e32 v107, v64, v3
	ds_read_b128 v[0:3], v5 offset:2464
	s_waitcnt lgkmcnt(0)
	v_fmac_f32_e32 v107, v52, v0
	v_fmac_f32_e32 v107, v53, v1
	v_fmac_f32_e32 v107, v50, v2
	v_fmac_f32_e32 v107, v51, v3
	ds_read_b128 v[0:3], v5 offset:2480
	s_waitcnt lgkmcnt(0)
	v_pk_mul_f32 v[0:1], v[48:49], v[0:1]
	s_nop 0
	v_add_f32_e32 v0, v107, v0
	v_add_f32_e32 v107, v0, v1
	v_pk_mul_f32 v[0:1], v[46:47], v[2:3]
	s_nop 0
	v_add_f32_e32 v0, v107, v0
	v_add_f32_e32 v0, v0, v1
	v_min_f32_e32 v1, 0, v0
	v_mul_f32_e64 v0, |v0|, s11
	v_exp_f32_e32 v0, v0
	s_nop 0
	v_add_f32_e32 v0, 1.0, v0
	v_cmp_gt_f32_e32 vcc, s12, v0
	s_nop 1
	v_cndmask_b32_e64 v2, 0, 32, vcc
	v_ldexp_f32 v0, v0, v2
	v_log_f32_e32 v0, v0
	s_nop 0
	v_mul_f32_e32 v2, 0x3f317217, v0
	v_fma_f32 v2, v0, s13, -v2
	v_fmac_f32_e32 v2, 0x3377d1cf, v0
	v_fmac_f32_e32 v2, 0x3f317217, v0
	v_cmp_lt_f32_e64 s[0:1], |v0|, s36
	s_nop 1
	v_cndmask_b32_e64 v0, v0, v2, s[0:1]
	v_cndmask_b32_e32 v2, 0, v60, vcc
	v_sub_f32_e32 v0, v0, v2
	v_sub_f32_e32 v0, v1, v0
	v_fmamk_f32 v107, v0, 0x3d800000, v106
	ds_read_b128 v[0:3], v5 offset:2496
	s_waitcnt lgkmcnt(0)
	v_fma_f32 v108, v65, v0, v69
	v_fmac_f32_e32 v108, v66, v1
	v_fmac_f32_e32 v108, v67, v2
	v_fmac_f32_e32 v108, v68, v3
	ds_read_b128 v[0:3], v5 offset:2512
	s_waitcnt lgkmcnt(0)
	v_fmac_f32_e32 v108, v55, v0
	v_fmac_f32_e32 v108, v62, v1
	v_fmac_f32_e32 v108, v63, v2
	v_fmac_f32_e32 v108, v64, v3
	ds_read_b128 v[0:3], v5 offset:2528
	s_waitcnt lgkmcnt(0)
	v_fmac_f32_e32 v108, v52, v0
	v_fmac_f32_e32 v108, v53, v1
	v_fmac_f32_e32 v108, v50, v2
	v_fmac_f32_e32 v108, v51, v3
	ds_read_b128 v[0:3], v5 offset:2544
	s_waitcnt lgkmcnt(0)
	v_pk_mul_f32 v[0:1], v[48:49], v[0:1]
	s_nop 0
	v_add_f32_e32 v0, v108, v0
	v_add_f32_e32 v108, v0, v1
	v_pk_mul_f32 v[0:1], v[46:47], v[2:3]
	s_nop 0
	v_add_f32_e32 v0, v108, v0
	v_add_f32_e32 v0, v0, v1
	v_min_f32_e32 v1, 0, v0
	v_mul_f32_e64 v0, |v0|, s11
	v_exp_f32_e32 v0, v0
	s_nop 0
	v_add_f32_e32 v0, 1.0, v0
	v_cmp_gt_f32_e32 vcc, s12, v0
	s_nop 1
	v_cndmask_b32_e64 v2, 0, 32, vcc
	v_ldexp_f32 v0, v0, v2
	v_log_f32_e32 v0, v0
	s_nop 0
	v_mul_f32_e32 v2, 0x3f317217, v0
	v_fma_f32 v2, v0, s13, -v2
	v_fmac_f32_e32 v2, 0x3377d1cf, v0
	v_fmac_f32_e32 v2, 0x3f317217, v0
	v_cmp_lt_f32_e64 s[0:1], |v0|, s36
	s_nop 1
	v_cndmask_b32_e64 v0, v0, v2, s[0:1]
	v_cndmask_b32_e32 v2, 0, v60, vcc
	v_sub_f32_e32 v0, v0, v2
	v_sub_f32_e32 v0, v1, v0
	v_fmamk_f32 v108, v0, 0x3d800000, v107
	ds_read_b128 v[0:3], v5 offset:2560
	s_waitcnt lgkmcnt(0)
	v_fma_f32 v109, v65, v0, v69
	v_fmac_f32_e32 v109, v66, v1
	v_fmac_f32_e32 v109, v67, v2
	v_fmac_f32_e32 v109, v68, v3
	ds_read_b128 v[0:3], v5 offset:2576
	s_waitcnt lgkmcnt(0)
	v_fmac_f32_e32 v109, v55, v0
	v_fmac_f32_e32 v109, v62, v1
	v_fmac_f32_e32 v109, v63, v2
	v_fmac_f32_e32 v109, v64, v3
	ds_read_b128 v[0:3], v5 offset:2592
	s_waitcnt lgkmcnt(0)
	v_fmac_f32_e32 v109, v52, v0
	v_fmac_f32_e32 v109, v53, v1
	v_fmac_f32_e32 v109, v50, v2
	v_fmac_f32_e32 v109, v51, v3
	ds_read_b128 v[0:3], v5 offset:2608
	s_waitcnt lgkmcnt(0)
	v_pk_mul_f32 v[0:1], v[48:49], v[0:1]
	s_nop 0
	v_add_f32_e32 v0, v109, v0
	v_add_f32_e32 v109, v0, v1
	v_pk_mul_f32 v[0:1], v[46:47], v[2:3]
	s_nop 0
	v_add_f32_e32 v0, v109, v0
	v_add_f32_e32 v0, v0, v1
	v_min_f32_e32 v1, 0, v0
	v_mul_f32_e64 v0, |v0|, s11
	v_exp_f32_e32 v0, v0
	s_nop 0
	v_add_f32_e32 v0, 1.0, v0
	v_cmp_gt_f32_e32 vcc, s12, v0
	s_nop 1
	v_cndmask_b32_e64 v2, 0, 32, vcc
	v_ldexp_f32 v0, v0, v2
	v_log_f32_e32 v0, v0
	s_nop 0
	v_mul_f32_e32 v2, 0x3f317217, v0
	v_fma_f32 v2, v0, s13, -v2
	v_fmac_f32_e32 v2, 0x3377d1cf, v0
	v_fmac_f32_e32 v2, 0x3f317217, v0
	v_cmp_lt_f32_e64 s[0:1], |v0|, s36
	s_nop 1
	v_cndmask_b32_e64 v0, v0, v2, s[0:1]
	v_cndmask_b32_e32 v2, 0, v60, vcc
	v_sub_f32_e32 v0, v0, v2
	v_sub_f32_e32 v0, v1, v0
	v_fmamk_f32 v109, v0, 0x3d800000, v108
	ds_read_b128 v[0:3], v5 offset:2624
	s_waitcnt lgkmcnt(0)
	v_fma_f32 v110, v65, v0, v69
	v_fmac_f32_e32 v110, v66, v1
	v_fmac_f32_e32 v110, v67, v2
	v_fmac_f32_e32 v110, v68, v3
	ds_read_b128 v[0:3], v5 offset:2640
	s_waitcnt lgkmcnt(0)
	v_fmac_f32_e32 v110, v55, v0
	v_fmac_f32_e32 v110, v62, v1
	v_fmac_f32_e32 v110, v63, v2
	v_fmac_f32_e32 v110, v64, v3
	ds_read_b128 v[0:3], v5 offset:2656
	s_waitcnt lgkmcnt(0)
	v_fmac_f32_e32 v110, v52, v0
	v_fmac_f32_e32 v110, v53, v1
	v_fmac_f32_e32 v110, v50, v2
	v_fmac_f32_e32 v110, v51, v3
	ds_read_b128 v[0:3], v5 offset:2672
	s_waitcnt lgkmcnt(0)
; __device__ __forceinline__ float log_sigmoid(float x) { return fminf(x, 0.f) - __logf(1.f + __expf(-fabsf(x))); }
; __device__ __forceinline__ void gla_prep_item(LAS unsigned char* lds, int item, const bf16_t* Z, const float* W2, const float* Bg, bf16_t* KDT, float* DEC) {
;     ...
;     for (int t = 0; t < 64; ++t) {
;         float x = bias;
; #pragma unroll
;         for (int r = 0; r < 16; ++r) x += zgs[t * 16 + r] * w[r];
;         gv[t] = log_sigmoid(x) * (1.f / 16.f); bend += gv[t];
	v_pk_mul_f32 v[0:1], v[48:49], v[0:1]
	s_nop 0
	v_add_f32_e32 v0, v110, v0
	v_add_f32_e32 v110, v0, v1
	v_pk_mul_f32 v[0:1], v[46:47], v[2:3]
	s_nop 0
	v_add_f32_e32 v0, v110, v0
	v_add_f32_e32 v0, v0, v1
	v_min_f32_e32 v1, 0, v0
	v_mul_f32_e64 v0, |v0|, s11
	v_exp_f32_e32 v0, v0
	s_nop 0
	v_add_f32_e32 v0, 1.0, v0
	v_cmp_gt_f32_e32 vcc, s12, v0
	s_nop 1
	v_cndmask_b32_e64 v2, 0, 32, vcc
	v_ldexp_f32 v0, v0, v2
	v_log_f32_e32 v0, v0
	s_nop 0
	v_mul_f32_e32 v2, 0x3f317217, v0
	v_fma_f32 v2, v0, s13, -v2
	v_fmac_f32_e32 v2, 0x3377d1cf, v0
	v_fmac_f32_e32 v2, 0x3f317217, v0
	v_cmp_lt_f32_e64 s[0:1], |v0|, s36
	s_nop 1
	v_cndmask_b32_e64 v0, v0, v2, s[0:1]
	v_cndmask_b32_e32 v2, 0, v60, vcc
	v_sub_f32_e32 v0, v0, v2
	v_sub_f32_e32 v0, v1, v0
	v_fmamk_f32 v110, v0, 0x3d800000, v109
	ds_read_b128 v[0:3], v5 offset:2688
	s_waitcnt lgkmcnt(0)
	v_fma_f32 v111, v65, v0, v69
	v_fmac_f32_e32 v111, v66, v1
	v_fmac_f32_e32 v111, v67, v2
	v_fmac_f32_e32 v111, v68, v3
	ds_read_b128 v[0:3], v5 offset:2704
	s_waitcnt lgkmcnt(0)
	v_fmac_f32_e32 v111, v55, v0
	v_fmac_f32_e32 v111, v62, v1
	v_fmac_f32_e32 v111, v63, v2
	v_fmac_f32_e32 v111, v64, v3
	ds_read_b128 v[0:3], v5 offset:2720
	s_waitcnt lgkmcnt(0)
	v_fmac_f32_e32 v111, v52, v0
	v_fmac_f32_e32 v111, v53, v1
	v_fmac_f32_e32 v111, v50, v2
	v_fmac_f32_e32 v111, v51, v3
	ds_read_b128 v[0:3], v5 offset:2736
	s_waitcnt lgkmcnt(0)
	v_pk_mul_f32 v[0:1], v[48:49], v[0:1]
	s_nop 0
	v_add_f32_e32 v0, v111, v0
	v_add_f32_e32 v111, v0, v1
	v_pk_mul_f32 v[0:1], v[46:47], v[2:3]
	s_nop 0
	v_add_f32_e32 v0, v111, v0
	v_add_f32_e32 v0, v0, v1
	v_min_f32_e32 v1, 0, v0
	v_mul_f32_e64 v0, |v0|, s11
	v_exp_f32_e32 v0, v0
	s_nop 0
	v_add_f32_e32 v0, 1.0, v0
	v_cmp_gt_f32_e32 vcc, s12, v0
	s_nop 1
	v_cndmask_b32_e64 v2, 0, 32, vcc
	v_ldexp_f32 v0, v0, v2
	v_log_f32_e32 v0, v0
	s_nop 0
	v_mul_f32_e32 v2, 0x3f317217, v0
	v_fma_f32 v2, v0, s13, -v2
	v_fmac_f32_e32 v2, 0x3377d1cf, v0
	v_fmac_f32_e32 v2, 0x3f317217, v0
	v_cmp_lt_f32_e64 s[0:1], |v0|, s36
	s_nop 1
	v_cndmask_b32_e64 v0, v0, v2, s[0:1]
	v_cndmask_b32_e32 v2, 0, v60, vcc
	v_sub_f32_e32 v0, v0, v2
	v_sub_f32_e32 v0, v1, v0
	v_fmamk_f32 v111, v0, 0x3d800000, v110
	ds_read_b128 v[0:3], v5 offset:2752
	s_waitcnt lgkmcnt(0)
	v_fma_f32 v112, v65, v0, v69
	v_fmac_f32_e32 v112, v66, v1
	v_fmac_f32_e32 v112, v67, v2
	v_fmac_f32_e32 v112, v68, v3
	ds_read_b128 v[0:3], v5 offset:2768
	s_waitcnt lgkmcnt(0)
	v_fmac_f32_e32 v112, v55, v0
	v_fmac_f32_e32 v112, v62, v1
	v_fmac_f32_e32 v112, v63, v2
	v_fmac_f32_e32 v112, v64, v3
	ds_read_b128 v[0:3], v5 offset:2784
	s_waitcnt lgkmcnt(0)
	v_fmac_f32_e32 v112, v52, v0
	v_fmac_f32_e32 v112, v53, v1
	v_fmac_f32_e32 v112, v50, v2
	v_fmac_f32_e32 v112, v51, v3
	ds_read_b128 v[0:3], v5 offset:2800
	s_waitcnt lgkmcnt(0)
	v_pk_mul_f32 v[0:1], v[48:49], v[0:1]
	s_nop 0
	v_add_f32_e32 v0, v112, v0
	v_add_f32_e32 v112, v0, v1
	v_pk_mul_f32 v[0:1], v[46:47], v[2:3]
	s_nop 0
	v_add_f32_e32 v0, v112, v0
	v_add_f32_e32 v0, v0, v1
	v_min_f32_e32 v1, 0, v0
	v_mul_f32_e64 v0, |v0|, s11
	v_exp_f32_e32 v0, v0
	s_nop 0
	v_add_f32_e32 v0, 1.0, v0
	v_cmp_gt_f32_e32 vcc, s12, v0
	s_nop 1
	v_cndmask_b32_e64 v2, 0, 32, vcc
	v_ldexp_f32 v0, v0, v2
	v_log_f32_e32 v0, v0
	s_nop 0
	v_mul_f32_e32 v2, 0x3f317217, v0
	v_fma_f32 v2, v0, s13, -v2
	v_fmac_f32_e32 v2, 0x3377d1cf, v0
	v_fmac_f32_e32 v2, 0x3f317217, v0
	v_cmp_lt_f32_e64 s[0:1], |v0|, s36
	s_nop 1
	v_cndmask_b32_e64 v0, v0, v2, s[0:1]
	v_cndmask_b32_e32 v2, 0, v60, vcc
	v_sub_f32_e32 v0, v0, v2
	v_sub_f32_e32 v0, v1, v0
	v_fmamk_f32 v112, v0, 0x3d800000, v111
	ds_read_b128 v[0:3], v5 offset:2816
	s_waitcnt lgkmcnt(0)
	v_fma_f32 v113, v65, v0, v69
	v_fmac_f32_e32 v113, v66, v1
	v_fmac_f32_e32 v113, v67, v2
	v_fmac_f32_e32 v113, v68, v3
	ds_read_b128 v[0:3], v5 offset:2832
	s_waitcnt lgkmcnt(0)
	v_fmac_f32_e32 v113, v55, v0
	v_fmac_f32_e32 v113, v62, v1
	v_fmac_f32_e32 v113, v63, v2
	v_fmac_f32_e32 v113, v64, v3
	ds_read_b128 v[0:3], v5 offset:2848
	s_waitcnt lgkmcnt(0)
	v_fmac_f32_e32 v113, v52, v0
	v_fmac_f32_e32 v113, v53, v1
	v_fmac_f32_e32 v113, v50, v2
	v_fmac_f32_e32 v113, v51, v3
	ds_read_b128 v[0:3], v5 offset:2864
	s_waitcnt lgkmcnt(0)
	v_pk_mul_f32 v[0:1], v[48:49], v[0:1]
	s_nop 0
	v_add_f32_e32 v0, v113, v0
	v_add_f32_e32 v113, v0, v1
	v_pk_mul_f32 v[0:1], v[46:47], v[2:3]
	s_nop 0
	v_add_f32_e32 v0, v113, v0
	v_add_f32_e32 v0, v0, v1
	v_min_f32_e32 v1, 0, v0
	v_mul_f32_e64 v0, |v0|, s11
	v_exp_f32_e32 v0, v0
	s_nop 0
	v_add_f32_e32 v0, 1.0, v0
	v_cmp_gt_f32_e32 vcc, s12, v0
	s_nop 1
	v_cndmask_b32_e64 v2, 0, 32, vcc
	v_ldexp_f32 v0, v0, v2
	v_log_f32_e32 v0, v0
	s_nop 0
	v_mul_f32_e32 v2, 0x3f317217, v0
	v_fma_f32 v2, v0, s13, -v2
	v_fmac_f32_e32 v2, 0x3377d1cf, v0
	v_fmac_f32_e32 v2, 0x3f317217, v0
	v_cmp_lt_f32_e64 s[0:1], |v0|, s36
	s_nop 1
	v_cndmask_b32_e64 v0, v0, v2, s[0:1]
	v_cndmask_b32_e32 v2, 0, v60, vcc
	v_sub_f32_e32 v0, v0, v2
	v_sub_f32_e32 v0, v1, v0
	v_fmamk_f32 v113, v0, 0x3d800000, v112
	ds_read_b128 v[0:3], v5 offset:2880
	s_waitcnt lgkmcnt(0)
	v_fma_f32 v114, v65, v0, v69
	v_fmac_f32_e32 v114, v66, v1
	v_fmac_f32_e32 v114, v67, v2
	v_fmac_f32_e32 v114, v68, v3
	ds_read_b128 v[0:3], v5 offset:2896
	s_waitcnt lgkmcnt(0)
	v_fmac_f32_e32 v114, v55, v0
	v_fmac_f32_e32 v114, v62, v1
	v_fmac_f32_e32 v114, v63, v2
	v_fmac_f32_e32 v114, v64, v3
	ds_read_b128 v[0:3], v5 offset:2912
	s_waitcnt lgkmcnt(0)
	v_fmac_f32_e32 v114, v52, v0
	v_fmac_f32_e32 v114, v53, v1
	v_fmac_f32_e32 v114, v50, v2
	v_fmac_f32_e32 v114, v51, v3
	ds_read_b128 v[0:3], v5 offset:2928
	s_waitcnt lgkmcnt(0)
; __device__ __forceinline__ float log_sigmoid(float x) { return fminf(x, 0.f) - __logf(1.f + __expf(-fabsf(x))); }
; __device__ __forceinline__ void gla_prep_item(LAS unsigned char* lds, int item, const bf16_t* Z, const float* W2, const float* Bg, bf16_t* KDT, float* DEC) {
;     ...
;     for (int t = 0; t < 64; ++t) {
;         float x = bias;
; #pragma unroll
;         for (int r = 0; r < 16; ++r) x += zgs[t * 16 + r] * w[r];
;         gv[t] = log_sigmoid(x) * (1.f / 16.f); bend += gv[t];
	v_pk_mul_f32 v[0:1], v[48:49], v[0:1]
	s_nop 0
	v_add_f32_e32 v0, v114, v0
	v_add_f32_e32 v114, v0, v1
	v_pk_mul_f32 v[0:1], v[46:47], v[2:3]
	s_nop 0
	v_add_f32_e32 v0, v114, v0
	v_add_f32_e32 v0, v0, v1
	v_min_f32_e32 v1, 0, v0
	v_mul_f32_e64 v0, |v0|, s11
	v_exp_f32_e32 v0, v0
	s_nop 0
	v_add_f32_e32 v0, 1.0, v0
	v_cmp_gt_f32_e32 vcc, s12, v0
	s_nop 1
	v_cndmask_b32_e64 v2, 0, 32, vcc
	v_ldexp_f32 v0, v0, v2
	v_log_f32_e32 v0, v0
	s_nop 0
	v_mul_f32_e32 v2, 0x3f317217, v0
	v_fma_f32 v2, v0, s13, -v2
	v_fmac_f32_e32 v2, 0x3377d1cf, v0
	v_fmac_f32_e32 v2, 0x3f317217, v0
	v_cmp_lt_f32_e64 s[0:1], |v0|, s36
	s_nop 1
	v_cndmask_b32_e64 v0, v0, v2, s[0:1]
	v_cndmask_b32_e32 v2, 0, v60, vcc
	v_sub_f32_e32 v0, v0, v2
	v_sub_f32_e32 v0, v1, v0
	v_fmamk_f32 v114, v0, 0x3d800000, v113
	ds_read_b128 v[0:3], v5 offset:2944
	s_waitcnt lgkmcnt(0)
	v_fma_f32 v115, v65, v0, v69
	v_fmac_f32_e32 v115, v66, v1
	v_fmac_f32_e32 v115, v67, v2
	v_fmac_f32_e32 v115, v68, v3
	ds_read_b128 v[0:3], v5 offset:2960
	s_waitcnt lgkmcnt(0)
	v_fmac_f32_e32 v115, v55, v0
	v_fmac_f32_e32 v115, v62, v1
	v_fmac_f32_e32 v115, v63, v2
	v_fmac_f32_e32 v115, v64, v3
	ds_read_b128 v[0:3], v5 offset:2976
	s_waitcnt lgkmcnt(0)
	v_fmac_f32_e32 v115, v52, v0
	v_fmac_f32_e32 v115, v53, v1
	v_fmac_f32_e32 v115, v50, v2
	v_fmac_f32_e32 v115, v51, v3
	ds_read_b128 v[0:3], v5 offset:2992
	s_waitcnt lgkmcnt(0)
	v_pk_mul_f32 v[0:1], v[48:49], v[0:1]
	s_nop 0
	v_add_f32_e32 v0, v115, v0
	v_add_f32_e32 v115, v0, v1
	v_pk_mul_f32 v[0:1], v[46:47], v[2:3]
	s_nop 0
	v_add_f32_e32 v0, v115, v0
	v_add_f32_e32 v0, v0, v1
	v_min_f32_e32 v1, 0, v0
	v_mul_f32_e64 v0, |v0|, s11
	v_exp_f32_e32 v0, v0
	s_nop 0
	v_add_f32_e32 v0, 1.0, v0
	v_cmp_gt_f32_e32 vcc, s12, v0
	s_nop 1
	v_cndmask_b32_e64 v2, 0, 32, vcc
	v_ldexp_f32 v0, v0, v2
	v_log_f32_e32 v0, v0
	s_nop 0
	v_mul_f32_e32 v2, 0x3f317217, v0
	v_fma_f32 v2, v0, s13, -v2
	v_fmac_f32_e32 v2, 0x3377d1cf, v0
	v_fmac_f32_e32 v2, 0x3f317217, v0
	v_cmp_lt_f32_e64 s[0:1], |v0|, s36
	s_nop 1
	v_cndmask_b32_e64 v0, v0, v2, s[0:1]
	v_cndmask_b32_e32 v2, 0, v60, vcc
	v_sub_f32_e32 v0, v0, v2
	v_sub_f32_e32 v0, v1, v0
	v_fmamk_f32 v115, v0, 0x3d800000, v114
	ds_read_b128 v[0:3], v5 offset:3008
	s_waitcnt lgkmcnt(0)
	v_fma_f32 v116, v65, v0, v69
	v_fmac_f32_e32 v116, v66, v1
	v_fmac_f32_e32 v116, v67, v2
	v_fmac_f32_e32 v116, v68, v3
	ds_read_b128 v[0:3], v5 offset:3024
	s_waitcnt lgkmcnt(0)
	v_fmac_f32_e32 v116, v55, v0
	v_fmac_f32_e32 v116, v62, v1
	v_fmac_f32_e32 v116, v63, v2
	v_fmac_f32_e32 v116, v64, v3
	ds_read_b128 v[0:3], v5 offset:3040
	s_waitcnt lgkmcnt(0)
	v_fmac_f32_e32 v116, v52, v0
	v_fmac_f32_e32 v116, v53, v1
	v_fmac_f32_e32 v116, v50, v2
	v_fmac_f32_e32 v116, v51, v3
	ds_read_b128 v[0:3], v5 offset:3056
	s_waitcnt lgkmcnt(0)
	v_pk_mul_f32 v[0:1], v[48:49], v[0:1]
	s_nop 0
	v_add_f32_e32 v0, v116, v0
	v_add_f32_e32 v116, v0, v1
	v_pk_mul_f32 v[0:1], v[46:47], v[2:3]
	s_nop 0
	v_add_f32_e32 v0, v116, v0
	v_add_f32_e32 v0, v0, v1
	v_min_f32_e32 v1, 0, v0
	v_mul_f32_e64 v0, |v0|, s11
	v_exp_f32_e32 v0, v0
	s_nop 0
	v_add_f32_e32 v0, 1.0, v0
	v_cmp_gt_f32_e32 vcc, s12, v0
	s_nop 1
	v_cndmask_b32_e64 v2, 0, 32, vcc
	v_ldexp_f32 v0, v0, v2
	v_log_f32_e32 v0, v0
	s_nop 0
	v_mul_f32_e32 v2, 0x3f317217, v0
	v_fma_f32 v2, v0, s13, -v2
	v_fmac_f32_e32 v2, 0x3377d1cf, v0
	v_fmac_f32_e32 v2, 0x3f317217, v0
	v_cmp_lt_f32_e64 s[0:1], |v0|, s36
	s_nop 1
	v_cndmask_b32_e64 v0, v0, v2, s[0:1]
	v_cndmask_b32_e32 v2, 0, v60, vcc
	v_sub_f32_e32 v0, v0, v2
	v_sub_f32_e32 v0, v1, v0
	v_fmamk_f32 v116, v0, 0x3d800000, v115
	ds_read_b128 v[0:3], v5 offset:3072
	s_waitcnt lgkmcnt(0)
	v_fma_f32 v117, v65, v0, v69
	v_fmac_f32_e32 v117, v66, v1
	v_fmac_f32_e32 v117, v67, v2
	v_fmac_f32_e32 v117, v68, v3
	ds_read_b128 v[0:3], v5 offset:3088
	s_waitcnt lgkmcnt(0)
	v_fmac_f32_e32 v117, v55, v0
	v_fmac_f32_e32 v117, v62, v1
	v_fmac_f32_e32 v117, v63, v2
	v_fmac_f32_e32 v117, v64, v3
	ds_read_b128 v[0:3], v5 offset:3104
	s_waitcnt lgkmcnt(0)
	v_fmac_f32_e32 v117, v52, v0
	v_fmac_f32_e32 v117, v53, v1
	v_fmac_f32_e32 v117, v50, v2
	v_fmac_f32_e32 v117, v51, v3
	ds_read_b128 v[0:3], v5 offset:3120
	s_waitcnt lgkmcnt(0)
	v_pk_mul_f32 v[0:1], v[48:49], v[0:1]
	s_nop 0
	v_add_f32_e32 v0, v117, v0
	v_add_f32_e32 v117, v0, v1
	v_pk_mul_f32 v[0:1], v[46:47], v[2:3]
	s_nop 0
	v_add_f32_e32 v0, v117, v0
	v_add_f32_e32 v0, v0, v1
	v_min_f32_e32 v1, 0, v0
	v_mul_f32_e64 v0, |v0|, s11
	v_exp_f32_e32 v0, v0
	s_nop 0
	v_add_f32_e32 v0, 1.0, v0
	v_cmp_gt_f32_e32 vcc, s12, v0
	s_nop 1
	v_cndmask_b32_e64 v2, 0, 32, vcc
	v_ldexp_f32 v0, v0, v2
	v_log_f32_e32 v0, v0
	s_nop 0
	v_mul_f32_e32 v2, 0x3f317217, v0
	v_fma_f32 v2, v0, s13, -v2
	v_fmac_f32_e32 v2, 0x3377d1cf, v0
	v_fmac_f32_e32 v2, 0x3f317217, v0
	v_cmp_lt_f32_e64 s[0:1], |v0|, s36
	s_nop 1
	v_cndmask_b32_e64 v0, v0, v2, s[0:1]
	v_cndmask_b32_e32 v2, 0, v60, vcc
	v_sub_f32_e32 v0, v0, v2
	v_sub_f32_e32 v0, v1, v0
	v_fmamk_f32 v117, v0, 0x3d800000, v116
	ds_read_b128 v[0:3], v5 offset:3136
	s_waitcnt lgkmcnt(0)
	v_fma_f32 v118, v65, v0, v69
	v_fmac_f32_e32 v118, v66, v1
	v_fmac_f32_e32 v118, v67, v2
	v_fmac_f32_e32 v118, v68, v3
	ds_read_b128 v[0:3], v5 offset:3152
	s_waitcnt lgkmcnt(0)
	v_fmac_f32_e32 v118, v55, v0
	v_fmac_f32_e32 v118, v62, v1
	v_fmac_f32_e32 v118, v63, v2
	v_fmac_f32_e32 v118, v64, v3
	ds_read_b128 v[0:3], v5 offset:3168
	s_waitcnt lgkmcnt(0)
	v_fmac_f32_e32 v118, v52, v0
	v_fmac_f32_e32 v118, v53, v1
	v_fmac_f32_e32 v118, v50, v2
	v_fmac_f32_e32 v118, v51, v3
	ds_read_b128 v[0:3], v5 offset:3184
	s_waitcnt lgkmcnt(0)
; __device__ __forceinline__ float log_sigmoid(float x) { return fminf(x, 0.f) - __logf(1.f + __expf(-fabsf(x))); }
; __device__ __forceinline__ void gla_prep_item(LAS unsigned char* lds, int item, const bf16_t* Z, const float* W2, const float* Bg, bf16_t* KDT, float* DEC) {
;     ...
;     for (int t = 0; t < 64; ++t) {
;         float x = bias;
; #pragma unroll
;         for (int r = 0; r < 16; ++r) x += zgs[t * 16 + r] * w[r];
;         gv[t] = log_sigmoid(x) * (1.f / 16.f); bend += gv[t];
	v_pk_mul_f32 v[0:1], v[48:49], v[0:1]
	s_nop 0
	v_add_f32_e32 v0, v118, v0
	v_add_f32_e32 v118, v0, v1
	v_pk_mul_f32 v[0:1], v[46:47], v[2:3]
	s_nop 0
	v_add_f32_e32 v0, v118, v0
	v_add_f32_e32 v0, v0, v1
	v_min_f32_e32 v1, 0, v0
	v_mul_f32_e64 v0, |v0|, s11
	v_exp_f32_e32 v0, v0
	s_nop 0
	v_add_f32_e32 v0, 1.0, v0
	v_cmp_gt_f32_e32 vcc, s12, v0
	s_nop 1
	v_cndmask_b32_e64 v2, 0, 32, vcc
	v_ldexp_f32 v0, v0, v2
	v_log_f32_e32 v0, v0
	s_nop 0
	v_mul_f32_e32 v2, 0x3f317217, v0
	v_fma_f32 v2, v0, s13, -v2
	v_fmac_f32_e32 v2, 0x3377d1cf, v0
	v_fmac_f32_e32 v2, 0x3f317217, v0
	v_cmp_lt_f32_e64 s[0:1], |v0|, s36
	s_nop 1
	v_cndmask_b32_e64 v0, v0, v2, s[0:1]
	v_cndmask_b32_e32 v2, 0, v60, vcc
	v_sub_f32_e32 v0, v0, v2
	v_sub_f32_e32 v0, v1, v0
	v_fmamk_f32 v118, v0, 0x3d800000, v117
	ds_read_b128 v[0:3], v5 offset:3200
	s_waitcnt lgkmcnt(0)
	v_fma_f32 v119, v65, v0, v69
	v_fmac_f32_e32 v119, v66, v1
	v_fmac_f32_e32 v119, v67, v2
	v_fmac_f32_e32 v119, v68, v3
	ds_read_b128 v[0:3], v5 offset:3216
	s_waitcnt lgkmcnt(0)
	v_fmac_f32_e32 v119, v55, v0
	v_fmac_f32_e32 v119, v62, v1
	v_fmac_f32_e32 v119, v63, v2
	v_fmac_f32_e32 v119, v64, v3
	ds_read_b128 v[0:3], v5 offset:3232
	s_waitcnt lgkmcnt(0)
	v_fmac_f32_e32 v119, v52, v0
	v_fmac_f32_e32 v119, v53, v1
	v_fmac_f32_e32 v119, v50, v2
	v_fmac_f32_e32 v119, v51, v3
	ds_read_b128 v[0:3], v5 offset:3248
	s_waitcnt lgkmcnt(0)
	v_pk_mul_f32 v[0:1], v[48:49], v[0:1]
	s_nop 0
	v_add_f32_e32 v0, v119, v0
	v_add_f32_e32 v119, v0, v1
	v_pk_mul_f32 v[0:1], v[46:47], v[2:3]
	s_nop 0
	v_add_f32_e32 v0, v119, v0
	v_add_f32_e32 v0, v0, v1
	v_min_f32_e32 v1, 0, v0
	v_mul_f32_e64 v0, |v0|, s11
	v_exp_f32_e32 v0, v0
	s_nop 0
	v_add_f32_e32 v0, 1.0, v0
	v_cmp_gt_f32_e32 vcc, s12, v0
	s_nop 1
	v_cndmask_b32_e64 v2, 0, 32, vcc
	v_ldexp_f32 v0, v0, v2
	v_log_f32_e32 v0, v0
	s_nop 0
	v_mul_f32_e32 v2, 0x3f317217, v0
	v_fma_f32 v2, v0, s13, -v2
	v_fmac_f32_e32 v2, 0x3377d1cf, v0
	v_fmac_f32_e32 v2, 0x3f317217, v0
	v_cmp_lt_f32_e64 s[0:1], |v0|, s36
	s_nop 1
	v_cndmask_b32_e64 v0, v0, v2, s[0:1]
	v_cndmask_b32_e32 v2, 0, v60, vcc
	v_sub_f32_e32 v0, v0, v2
	v_sub_f32_e32 v0, v1, v0
	v_fmamk_f32 v119, v0, 0x3d800000, v118
	ds_read_b128 v[0:3], v5 offset:3264
	s_waitcnt lgkmcnt(0)
	v_fma_f32 v120, v65, v0, v69
	v_fmac_f32_e32 v120, v66, v1
	v_fmac_f32_e32 v120, v67, v2
	v_fmac_f32_e32 v120, v68, v3
	ds_read_b128 v[0:3], v5 offset:3280
	s_waitcnt lgkmcnt(0)
	v_fmac_f32_e32 v120, v55, v0
	v_fmac_f32_e32 v120, v62, v1
	v_fmac_f32_e32 v120, v63, v2
	v_fmac_f32_e32 v120, v64, v3
	ds_read_b128 v[0:3], v5 offset:3296
	s_waitcnt lgkmcnt(0)
	v_fmac_f32_e32 v120, v52, v0
	v_fmac_f32_e32 v120, v53, v1
	v_fmac_f32_e32 v120, v50, v2
	v_fmac_f32_e32 v120, v51, v3
	ds_read_b128 v[0:3], v5 offset:3312
	s_waitcnt lgkmcnt(0)
	v_pk_mul_f32 v[0:1], v[48:49], v[0:1]
	s_nop 0
	v_add_f32_e32 v0, v120, v0
	v_add_f32_e32 v120, v0, v1
	v_pk_mul_f32 v[0:1], v[46:47], v[2:3]
	s_nop 0
	v_add_f32_e32 v0, v120, v0
	v_add_f32_e32 v0, v0, v1
	v_min_f32_e32 v1, 0, v0
	v_mul_f32_e64 v0, |v0|, s11
	v_exp_f32_e32 v0, v0
	s_nop 0
	v_add_f32_e32 v0, 1.0, v0
	v_cmp_gt_f32_e32 vcc, s12, v0
	s_nop 1
	v_cndmask_b32_e64 v2, 0, 32, vcc
	v_ldexp_f32 v0, v0, v2
	v_log_f32_e32 v0, v0
	s_nop 0
	v_mul_f32_e32 v2, 0x3f317217, v0
	v_fma_f32 v2, v0, s13, -v2
	v_fmac_f32_e32 v2, 0x3377d1cf, v0
	v_fmac_f32_e32 v2, 0x3f317217, v0
	v_cmp_lt_f32_e64 s[0:1], |v0|, s36
	s_nop 1
	v_cndmask_b32_e64 v0, v0, v2, s[0:1]
	v_cndmask_b32_e32 v2, 0, v60, vcc
	v_sub_f32_e32 v0, v0, v2
	v_sub_f32_e32 v0, v1, v0
	v_fmamk_f32 v120, v0, 0x3d800000, v119
	ds_read_b128 v[0:3], v5 offset:3328
	s_waitcnt lgkmcnt(0)
	v_fma_f32 v121, v65, v0, v69
	v_fmac_f32_e32 v121, v66, v1
	v_fmac_f32_e32 v121, v67, v2
	v_fmac_f32_e32 v121, v68, v3
	ds_read_b128 v[0:3], v5 offset:3344
	s_waitcnt lgkmcnt(0)
	v_fmac_f32_e32 v121, v55, v0
	v_fmac_f32_e32 v121, v62, v1
	v_fmac_f32_e32 v121, v63, v2
	v_fmac_f32_e32 v121, v64, v3
	ds_read_b128 v[0:3], v5 offset:3360
	s_waitcnt lgkmcnt(0)
	v_fmac_f32_e32 v121, v52, v0
	v_fmac_f32_e32 v121, v53, v1
	v_fmac_f32_e32 v121, v50, v2
	v_fmac_f32_e32 v121, v51, v3
	ds_read_b128 v[0:3], v5 offset:3376
	s_waitcnt lgkmcnt(0)
	v_pk_mul_f32 v[0:1], v[48:49], v[0:1]
	s_nop 0
	v_add_f32_e32 v0, v121, v0
	v_add_f32_e32 v121, v0, v1
	v_pk_mul_f32 v[0:1], v[46:47], v[2:3]
	s_nop 0
	v_add_f32_e32 v0, v121, v0
	v_add_f32_e32 v0, v0, v1
	v_min_f32_e32 v1, 0, v0
	v_mul_f32_e64 v0, |v0|, s11
	v_exp_f32_e32 v0, v0
	s_nop 0
	v_add_f32_e32 v0, 1.0, v0
	v_cmp_gt_f32_e32 vcc, s12, v0
	s_nop 1
	v_cndmask_b32_e64 v2, 0, 32, vcc
	v_ldexp_f32 v0, v0, v2
	v_log_f32_e32 v0, v0
	s_nop 0
	v_mul_f32_e32 v2, 0x3f317217, v0
	v_fma_f32 v2, v0, s13, -v2
	v_fmac_f32_e32 v2, 0x3377d1cf, v0
	v_fmac_f32_e32 v2, 0x3f317217, v0
	v_cmp_lt_f32_e64 s[0:1], |v0|, s36
	s_nop 1
	v_cndmask_b32_e64 v0, v0, v2, s[0:1]
	v_cndmask_b32_e32 v2, 0, v60, vcc
	v_sub_f32_e32 v0, v0, v2
	v_sub_f32_e32 v0, v1, v0
	v_fmamk_f32 v121, v0, 0x3d800000, v120
	ds_read_b128 v[0:3], v5 offset:3392
	s_waitcnt lgkmcnt(0)
	v_fma_f32 v122, v65, v0, v69
	v_fmac_f32_e32 v122, v66, v1
	v_fmac_f32_e32 v122, v67, v2
	v_fmac_f32_e32 v122, v68, v3
	ds_read_b128 v[0:3], v5 offset:3408
	s_waitcnt lgkmcnt(0)
	v_fmac_f32_e32 v122, v55, v0
	v_fmac_f32_e32 v122, v62, v1
	v_fmac_f32_e32 v122, v63, v2
	v_fmac_f32_e32 v122, v64, v3
	ds_read_b128 v[0:3], v5 offset:3424
	s_waitcnt lgkmcnt(0)
	v_fmac_f32_e32 v122, v52, v0
	v_fmac_f32_e32 v122, v53, v1
	v_fmac_f32_e32 v122, v50, v2
	v_fmac_f32_e32 v122, v51, v3
	ds_read_b128 v[0:3], v5 offset:3440
	s_waitcnt lgkmcnt(0)
; __device__ __forceinline__ float log_sigmoid(float x) { return fminf(x, 0.f) - __logf(1.f + __expf(-fabsf(x))); }
; __device__ __forceinline__ void gla_prep_item(LAS unsigned char* lds, int item, const bf16_t* Z, const float* W2, const float* Bg, bf16_t* KDT, float* DEC) {
;     ...
;     for (int t = 0; t < 64; ++t) {
;         float x = bias;
; #pragma unroll
;         for (int r = 0; r < 16; ++r) x += zgs[t * 16 + r] * w[r];
;         gv[t] = log_sigmoid(x) * (1.f / 16.f); bend += gv[t];
	v_pk_mul_f32 v[0:1], v[48:49], v[0:1]
	s_nop 0
	v_add_f32_e32 v0, v122, v0
	v_add_f32_e32 v122, v0, v1
	v_pk_mul_f32 v[0:1], v[46:47], v[2:3]
	s_nop 0
	v_add_f32_e32 v0, v122, v0
	v_add_f32_e32 v0, v0, v1
	v_min_f32_e32 v1, 0, v0
	v_mul_f32_e64 v0, |v0|, s11
	v_exp_f32_e32 v0, v0
	s_nop 0
	v_add_f32_e32 v0, 1.0, v0
	v_cmp_gt_f32_e32 vcc, s12, v0
	s_nop 1
	v_cndmask_b32_e64 v2, 0, 32, vcc
	v_ldexp_f32 v0, v0, v2
	v_log_f32_e32 v0, v0
	s_nop 0
	v_mul_f32_e32 v2, 0x3f317217, v0
	v_fma_f32 v2, v0, s13, -v2
	v_fmac_f32_e32 v2, 0x3377d1cf, v0
	v_fmac_f32_e32 v2, 0x3f317217, v0
	v_cmp_lt_f32_e64 s[0:1], |v0|, s36
	s_nop 1
	v_cndmask_b32_e64 v0, v0, v2, s[0:1]
	v_cndmask_b32_e32 v2, 0, v60, vcc
	v_sub_f32_e32 v0, v0, v2
	v_sub_f32_e32 v0, v1, v0
	v_fmamk_f32 v122, v0, 0x3d800000, v121
	ds_read_b128 v[0:3], v5 offset:3456
	s_waitcnt lgkmcnt(0)
	v_fma_f32 v123, v65, v0, v69
	v_fmac_f32_e32 v123, v66, v1
	v_fmac_f32_e32 v123, v67, v2
	v_fmac_f32_e32 v123, v68, v3
	ds_read_b128 v[0:3], v5 offset:3472
	s_waitcnt lgkmcnt(0)
	v_fmac_f32_e32 v123, v55, v0
	v_fmac_f32_e32 v123, v62, v1
	v_fmac_f32_e32 v123, v63, v2
	v_fmac_f32_e32 v123, v64, v3
	ds_read_b128 v[0:3], v5 offset:3488
	s_waitcnt lgkmcnt(0)
	v_fmac_f32_e32 v123, v52, v0
	v_fmac_f32_e32 v123, v53, v1
	v_fmac_f32_e32 v123, v50, v2
	v_fmac_f32_e32 v123, v51, v3
	ds_read_b128 v[0:3], v5 offset:3504
	s_waitcnt lgkmcnt(0)
	v_pk_mul_f32 v[0:1], v[48:49], v[0:1]
	s_nop 0
	v_add_f32_e32 v0, v123, v0
	v_add_f32_e32 v123, v0, v1
	v_pk_mul_f32 v[0:1], v[46:47], v[2:3]
	s_nop 0
	v_add_f32_e32 v0, v123, v0
	v_add_f32_e32 v0, v0, v1
	v_min_f32_e32 v1, 0, v0
	v_mul_f32_e64 v0, |v0|, s11
	v_exp_f32_e32 v0, v0
	s_nop 0
	v_add_f32_e32 v0, 1.0, v0
	v_cmp_gt_f32_e32 vcc, s12, v0
	s_nop 1
	v_cndmask_b32_e64 v2, 0, 32, vcc
	v_ldexp_f32 v0, v0, v2
	v_log_f32_e32 v0, v0
	s_nop 0
	v_mul_f32_e32 v2, 0x3f317217, v0
	v_fma_f32 v2, v0, s13, -v2
	v_fmac_f32_e32 v2, 0x3377d1cf, v0
	v_fmac_f32_e32 v2, 0x3f317217, v0
	v_cmp_lt_f32_e64 s[0:1], |v0|, s36
	s_nop 1
	v_cndmask_b32_e64 v0, v0, v2, s[0:1]
	v_cndmask_b32_e32 v2, 0, v60, vcc
	v_sub_f32_e32 v0, v0, v2
	v_sub_f32_e32 v0, v1, v0
	v_fmamk_f32 v123, v0, 0x3d800000, v122
	ds_read_b128 v[0:3], v5 offset:3520
	s_waitcnt lgkmcnt(0)
	v_fma_f32 v124, v65, v0, v69
	v_fmac_f32_e32 v124, v66, v1
	v_fmac_f32_e32 v124, v67, v2
	v_fmac_f32_e32 v124, v68, v3
	ds_read_b128 v[0:3], v5 offset:3536
	s_waitcnt lgkmcnt(0)
	v_fmac_f32_e32 v124, v55, v0
	v_fmac_f32_e32 v124, v62, v1
	v_fmac_f32_e32 v124, v63, v2
	v_fmac_f32_e32 v124, v64, v3
	ds_read_b128 v[0:3], v5 offset:3552
	s_waitcnt lgkmcnt(0)
	v_fmac_f32_e32 v124, v52, v0
	v_fmac_f32_e32 v124, v53, v1
	v_fmac_f32_e32 v124, v50, v2
	v_fmac_f32_e32 v124, v51, v3
	ds_read_b128 v[0:3], v5 offset:3568
	s_waitcnt lgkmcnt(0)
	v_pk_mul_f32 v[0:1], v[48:49], v[0:1]
	s_nop 0
	v_add_f32_e32 v0, v124, v0
	v_add_f32_e32 v124, v0, v1
	v_pk_mul_f32 v[0:1], v[46:47], v[2:3]
	s_nop 0
	v_add_f32_e32 v0, v124, v0
	v_add_f32_e32 v0, v0, v1
	v_min_f32_e32 v1, 0, v0
	v_mul_f32_e64 v0, |v0|, s11
	v_exp_f32_e32 v0, v0
	s_nop 0
	v_add_f32_e32 v0, 1.0, v0
	v_cmp_gt_f32_e32 vcc, s12, v0
	s_nop 1
	v_cndmask_b32_e64 v2, 0, 32, vcc
	v_ldexp_f32 v0, v0, v2
	v_log_f32_e32 v0, v0
	s_nop 0
	v_mul_f32_e32 v2, 0x3f317217, v0
	v_fma_f32 v2, v0, s13, -v2
	v_fmac_f32_e32 v2, 0x3377d1cf, v0
	v_fmac_f32_e32 v2, 0x3f317217, v0
	v_cmp_lt_f32_e64 s[0:1], |v0|, s36
	s_nop 1
	v_cndmask_b32_e64 v0, v0, v2, s[0:1]
	v_cndmask_b32_e32 v2, 0, v60, vcc
	v_sub_f32_e32 v0, v0, v2
	v_sub_f32_e32 v0, v1, v0
	v_fmamk_f32 v124, v0, 0x3d800000, v123
	ds_read_b128 v[0:3], v5 offset:3584
	s_waitcnt lgkmcnt(0)
	v_fma_f32 v125, v65, v0, v69
	v_fmac_f32_e32 v125, v66, v1
	v_fmac_f32_e32 v125, v67, v2
	v_fmac_f32_e32 v125, v68, v3
	ds_read_b128 v[0:3], v5 offset:3600
	s_waitcnt lgkmcnt(0)
	v_fmac_f32_e32 v125, v55, v0
	v_fmac_f32_e32 v125, v62, v1
	v_fmac_f32_e32 v125, v63, v2
	v_fmac_f32_e32 v125, v64, v3
	ds_read_b128 v[0:3], v5 offset:3616
	s_waitcnt lgkmcnt(0)
	v_fmac_f32_e32 v125, v52, v0
	v_fmac_f32_e32 v125, v53, v1
	v_fmac_f32_e32 v125, v50, v2
	v_fmac_f32_e32 v125, v51, v3
	ds_read_b128 v[0:3], v5 offset:3632
	s_waitcnt lgkmcnt(0)
	v_pk_mul_f32 v[0:1], v[48:49], v[0:1]
	s_nop 0
	v_add_f32_e32 v0, v125, v0
	v_add_f32_e32 v125, v0, v1
	v_pk_mul_f32 v[0:1], v[46:47], v[2:3]
	s_nop 0
	v_add_f32_e32 v0, v125, v0
	v_add_f32_e32 v0, v0, v1
	v_min_f32_e32 v1, 0, v0
	v_mul_f32_e64 v0, |v0|, s11
	v_exp_f32_e32 v0, v0
	s_nop 0
	v_add_f32_e32 v0, 1.0, v0
	v_cmp_gt_f32_e32 vcc, s12, v0
	s_nop 1
	v_cndmask_b32_e64 v2, 0, 32, vcc
	v_ldexp_f32 v0, v0, v2
	v_log_f32_e32 v0, v0
	s_nop 0
	v_mul_f32_e32 v2, 0x3f317217, v0
	v_fma_f32 v2, v0, s13, -v2
	v_fmac_f32_e32 v2, 0x3377d1cf, v0
	v_fmac_f32_e32 v2, 0x3f317217, v0
	v_cmp_lt_f32_e64 s[0:1], |v0|, s36
	s_nop 1
	v_cndmask_b32_e64 v0, v0, v2, s[0:1]
	v_cndmask_b32_e32 v2, 0, v60, vcc
	v_sub_f32_e32 v0, v0, v2
	v_sub_f32_e32 v0, v1, v0
	v_fmamk_f32 v125, v0, 0x3d800000, v124
	ds_read_b128 v[0:3], v5 offset:3648
	s_waitcnt lgkmcnt(0)
	v_fma_f32 v126, v65, v0, v69
	v_fmac_f32_e32 v126, v66, v1
	v_fmac_f32_e32 v126, v67, v2
	v_fmac_f32_e32 v126, v68, v3
	ds_read_b128 v[0:3], v5 offset:3664
	s_waitcnt lgkmcnt(0)
	v_fmac_f32_e32 v126, v55, v0
	v_fmac_f32_e32 v126, v62, v1
	v_fmac_f32_e32 v126, v63, v2
	v_fmac_f32_e32 v126, v64, v3
	ds_read_b128 v[0:3], v5 offset:3680
	s_waitcnt lgkmcnt(0)
	v_fmac_f32_e32 v126, v52, v0
	v_fmac_f32_e32 v126, v53, v1
	v_fmac_f32_e32 v126, v50, v2
	v_fmac_f32_e32 v126, v51, v3
	ds_read_b128 v[0:3], v5 offset:3696
	s_waitcnt lgkmcnt(0)
; __device__ __forceinline__ float log_sigmoid(float x) { return fminf(x, 0.f) - __logf(1.f + __expf(-fabsf(x))); }
; __device__ __forceinline__ void gla_prep_item(LAS unsigned char* lds, int item, const bf16_t* Z, const float* W2, const float* Bg, bf16_t* KDT, float* DEC) {
;     ...
;     for (int t = 0; t < 64; ++t) {
;         float x = bias;
; #pragma unroll
;         for (int r = 0; r < 16; ++r) x += zgs[t * 16 + r] * w[r];
;         gv[t] = log_sigmoid(x) * (1.f / 16.f); bend += gv[t];
	v_pk_mul_f32 v[0:1], v[48:49], v[0:1]
	s_nop 0
	v_add_f32_e32 v0, v126, v0
	v_add_f32_e32 v126, v0, v1
	v_pk_mul_f32 v[0:1], v[46:47], v[2:3]
	s_nop 0
	v_add_f32_e32 v0, v126, v0
	v_add_f32_e32 v0, v0, v1
	v_min_f32_e32 v1, 0, v0
	v_mul_f32_e64 v0, |v0|, s11
	v_exp_f32_e32 v0, v0
	s_nop 0
	v_add_f32_e32 v0, 1.0, v0
	v_cmp_gt_f32_e32 vcc, s12, v0
	s_nop 1
	v_cndmask_b32_e64 v2, 0, 32, vcc
	v_ldexp_f32 v0, v0, v2
	v_log_f32_e32 v0, v0
	s_nop 0
	v_mul_f32_e32 v2, 0x3f317217, v0
	v_fma_f32 v2, v0, s13, -v2
	v_fmac_f32_e32 v2, 0x3377d1cf, v0
	v_fmac_f32_e32 v2, 0x3f317217, v0
	v_cmp_lt_f32_e64 s[0:1], |v0|, s36
	s_nop 1
	v_cndmask_b32_e64 v0, v0, v2, s[0:1]
	v_cndmask_b32_e32 v2, 0, v60, vcc
	v_sub_f32_e32 v0, v0, v2
	v_sub_f32_e32 v0, v1, v0
	v_fmamk_f32 v126, v0, 0x3d800000, v125
	ds_read_b128 v[0:3], v5 offset:3712
	s_waitcnt lgkmcnt(0)
	v_fma_f32 v127, v65, v0, v69
	v_fmac_f32_e32 v127, v66, v1
	v_fmac_f32_e32 v127, v67, v2
	v_fmac_f32_e32 v127, v68, v3
	ds_read_b128 v[0:3], v5 offset:3728
	s_waitcnt lgkmcnt(0)
	v_fmac_f32_e32 v127, v55, v0
	v_fmac_f32_e32 v127, v62, v1
	v_fmac_f32_e32 v127, v63, v2
	v_fmac_f32_e32 v127, v64, v3
	ds_read_b128 v[0:3], v5 offset:3744
	s_waitcnt lgkmcnt(0)
	v_fmac_f32_e32 v127, v52, v0
	v_fmac_f32_e32 v127, v53, v1
	v_fmac_f32_e32 v127, v50, v2
	v_fmac_f32_e32 v127, v51, v3
	ds_read_b128 v[0:3], v5 offset:3760
	s_waitcnt lgkmcnt(0)
	v_pk_mul_f32 v[0:1], v[48:49], v[0:1]
	s_nop 0
	v_add_f32_e32 v0, v127, v0
	v_add_f32_e32 v127, v0, v1
	v_pk_mul_f32 v[0:1], v[46:47], v[2:3]
	s_nop 0
	v_add_f32_e32 v0, v127, v0
	v_add_f32_e32 v0, v0, v1
	v_min_f32_e32 v1, 0, v0
	v_mul_f32_e64 v0, |v0|, s11
	v_exp_f32_e32 v0, v0
	s_nop 0
	v_add_f32_e32 v0, 1.0, v0
	v_cmp_gt_f32_e32 vcc, s12, v0
	s_nop 1
	v_cndmask_b32_e64 v2, 0, 32, vcc
	v_ldexp_f32 v0, v0, v2
	v_log_f32_e32 v0, v0
	s_nop 0
	v_mul_f32_e32 v2, 0x3f317217, v0
	v_fma_f32 v2, v0, s13, -v2
	v_fmac_f32_e32 v2, 0x3377d1cf, v0
	v_fmac_f32_e32 v2, 0x3f317217, v0
	v_cmp_lt_f32_e64 s[0:1], |v0|, s36
	s_nop 1
	v_cndmask_b32_e64 v0, v0, v2, s[0:1]
	v_cndmask_b32_e32 v2, 0, v60, vcc
	v_sub_f32_e32 v0, v0, v2
	v_sub_f32_e32 v0, v1, v0
	v_fmamk_f32 v127, v0, 0x3d800000, v126
	ds_read_b128 v[0:3], v5 offset:3776
	s_waitcnt lgkmcnt(0)
	v_fma_f32 v128, v65, v0, v69
	v_fmac_f32_e32 v128, v66, v1
	v_fmac_f32_e32 v128, v67, v2
	v_fmac_f32_e32 v128, v68, v3
	ds_read_b128 v[0:3], v5 offset:3792
	s_waitcnt lgkmcnt(0)
	v_fmac_f32_e32 v128, v55, v0
	v_fmac_f32_e32 v128, v62, v1
	v_fmac_f32_e32 v128, v63, v2
	v_fmac_f32_e32 v128, v64, v3
	ds_read_b128 v[0:3], v5 offset:3808
	s_waitcnt lgkmcnt(0)
	v_fmac_f32_e32 v128, v52, v0
	v_fmac_f32_e32 v128, v53, v1
	v_fmac_f32_e32 v128, v50, v2
	v_fmac_f32_e32 v128, v51, v3
	ds_read_b128 v[0:3], v5 offset:3824
	s_waitcnt lgkmcnt(0)
	v_pk_mul_f32 v[0:1], v[48:49], v[0:1]
	s_nop 0
	v_add_f32_e32 v0, v128, v0
	v_add_f32_e32 v128, v0, v1
	v_pk_mul_f32 v[0:1], v[46:47], v[2:3]
	s_nop 0
	v_add_f32_e32 v0, v128, v0
	v_add_f32_e32 v0, v0, v1
	v_min_f32_e32 v1, 0, v0
	v_mul_f32_e64 v0, |v0|, s11
	v_exp_f32_e32 v0, v0
	s_nop 0
	v_add_f32_e32 v0, 1.0, v0
	v_cmp_gt_f32_e32 vcc, s12, v0
	s_nop 1
	v_cndmask_b32_e64 v2, 0, 32, vcc
	v_ldexp_f32 v0, v0, v2
	v_log_f32_e32 v0, v0
	s_nop 0
	v_mul_f32_e32 v2, 0x3f317217, v0
	v_fma_f32 v2, v0, s13, -v2
	v_fmac_f32_e32 v2, 0x3377d1cf, v0
	v_fmac_f32_e32 v2, 0x3f317217, v0
	v_cmp_lt_f32_e64 s[0:1], |v0|, s36
	s_nop 1
	v_cndmask_b32_e64 v0, v0, v2, s[0:1]
	v_cndmask_b32_e32 v2, 0, v60, vcc
	v_sub_f32_e32 v0, v0, v2
	v_sub_f32_e32 v0, v1, v0
	v_fmamk_f32 v128, v0, 0x3d800000, v127
	ds_read_b128 v[0:3], v5 offset:3840
	s_waitcnt lgkmcnt(0)
	v_fma_f32 v129, v65, v0, v69
	v_fmac_f32_e32 v129, v66, v1
	v_fmac_f32_e32 v129, v67, v2
	v_fmac_f32_e32 v129, v68, v3
	ds_read_b128 v[0:3], v5 offset:3856
	s_waitcnt lgkmcnt(0)
	v_fmac_f32_e32 v129, v55, v0
	v_fmac_f32_e32 v129, v62, v1
	v_fmac_f32_e32 v129, v63, v2
	v_fmac_f32_e32 v129, v64, v3
	ds_read_b128 v[0:3], v5 offset:3872
	s_waitcnt lgkmcnt(0)
	v_fmac_f32_e32 v129, v52, v0
	v_fmac_f32_e32 v129, v53, v1
	v_fmac_f32_e32 v129, v50, v2
	v_fmac_f32_e32 v129, v51, v3
	ds_read_b128 v[0:3], v5 offset:3888
	s_waitcnt lgkmcnt(0)
	v_pk_mul_f32 v[0:1], v[48:49], v[0:1]
	s_nop 0
	v_add_f32_e32 v0, v129, v0
	v_add_f32_e32 v129, v0, v1
	v_pk_mul_f32 v[0:1], v[46:47], v[2:3]
	s_nop 0
	v_add_f32_e32 v0, v129, v0
	v_add_f32_e32 v0, v0, v1
	v_min_f32_e32 v1, 0, v0
	v_mul_f32_e64 v0, |v0|, s11
	v_exp_f32_e32 v0, v0
	s_nop 0
	v_add_f32_e32 v0, 1.0, v0
	v_cmp_gt_f32_e32 vcc, s12, v0
	s_nop 1
	v_cndmask_b32_e64 v2, 0, 32, vcc
	v_ldexp_f32 v0, v0, v2
	v_log_f32_e32 v0, v0
	s_nop 0
	v_mul_f32_e32 v2, 0x3f317217, v0
	v_fma_f32 v2, v0, s13, -v2
	v_fmac_f32_e32 v2, 0x3377d1cf, v0
	v_fmac_f32_e32 v2, 0x3f317217, v0
	v_cmp_lt_f32_e64 s[0:1], |v0|, s36
	s_nop 1
	v_cndmask_b32_e64 v0, v0, v2, s[0:1]
	v_cndmask_b32_e32 v2, 0, v60, vcc
	v_sub_f32_e32 v0, v0, v2
	v_sub_f32_e32 v0, v1, v0
	v_fmamk_f32 v129, v0, 0x3d800000, v128
	ds_read_b128 v[0:3], v5 offset:3904
	s_waitcnt lgkmcnt(0)
	v_fma_f32 v130, v65, v0, v69
	v_fmac_f32_e32 v130, v66, v1
	v_fmac_f32_e32 v130, v67, v2
	v_fmac_f32_e32 v130, v68, v3
	ds_read_b128 v[0:3], v5 offset:3920
	s_waitcnt lgkmcnt(0)
	v_fmac_f32_e32 v130, v55, v0
	v_fmac_f32_e32 v130, v62, v1
	v_fmac_f32_e32 v130, v63, v2
	v_fmac_f32_e32 v130, v64, v3
	ds_read_b128 v[0:3], v5 offset:3936
	s_waitcnt lgkmcnt(0)
	v_fmac_f32_e32 v130, v52, v0
	v_fmac_f32_e32 v130, v53, v1
	v_pk_mul_f32 v[0:1], v[50:51], v[2:3]
	s_nop 0
	v_add_f32_e32 v0, v130, v0
	v_add_f32_e32 v130, v0, v1
	ds_read_b128 v[0:3], v5 offset:3952
	s_waitcnt lgkmcnt(0)
; __device__ __forceinline__ unsigned pk2(float lo, float hi) { f32x2_t v = {lo, hi}; bf16x2_t b = __builtin_convertvector(v, bf16x2_t); return __builtin_bit_cast(unsigned, b); }
; __device__ __forceinline__ float log_sigmoid(float x) { return fminf(x, 0.f) - __logf(1.f + __expf(-fabsf(x))); }
; __device__ __forceinline__ void gla_prep_item(LAS unsigned char* lds, int item, const bf16_t* Z, const float* W2, const float* Bg, bf16_t* KDT, float* DEC) {
;     ...
;     for (int t = 0; t < 64; ++t) {
;         float x = bias;
; #pragma unroll
;         for (int r = 0; r < 16; ++r) x += zgs[t * 16 + r] * w[r];
;         gv[t] = log_sigmoid(x) * (1.f / 16.f); bend += gv[t];
;     }
;     float bc = 0.f;
;     bf16_t* dst = KDT + (size_t)((b * 4 + h) * 32 + c) * 8192 + (size_t)((kd >> 4) * 2 * 64 + (kd & 15)) * 8;
;     const bf16_t* gk = Z + row0 * ZLD + ZGK + col;
; #pragma unroll
;     for (int t8 = 0; t8 < 8; ++t8) {
;         float kv[8];
; #pragma unroll
;         for (int e = 0; e < 8; ++e) {
;             const int t = t8 * 8 + e;
;             bc += gv[t];
;             kv[e] = bf2f(gk[(size_t)t * ZLD]) * __expf(bend - bc);
;         }
;         u32x4 o; o.x = pk2(kv[0], kv[1]); o.y = pk2(kv[2], kv[3]); o.z = pk2(kv[4], kv[5]); o.w = pk2(kv[6], kv[7]);
;         *(u32x4*)(dst + ((t8 >> 2) * 64 + (t8 & 3) * 16) * 8) = o;
;     }
;     DEC[(size_t)((b * 4 + h) * 32 + c) * 128 + kd] = expf(bend);
	v_pk_mul_f32 v[0:1], v[48:49], v[0:1]
	s_nop 0
	v_add_f32_e32 v0, v130, v0
	v_add_f32_e32 v130, v0, v1
	v_pk_mul_f32 v[0:1], v[46:47], v[2:3]
	s_nop 0
	v_add_f32_e32 v0, v130, v0
	v_add_f32_e32 v0, v0, v1
	v_min_f32_e32 v1, 0, v0
	v_mul_f32_e64 v0, |v0|, s11
	v_exp_f32_e32 v0, v0
	s_nop 0
	v_add_f32_e32 v0, 1.0, v0
	v_cmp_gt_f32_e32 vcc, s12, v0
	s_nop 1
	v_cndmask_b32_e64 v2, 0, 32, vcc
	v_ldexp_f32 v0, v0, v2
	v_log_f32_e32 v0, v0
	s_nop 0
	v_mul_f32_e32 v2, 0x3f317217, v0
	v_fma_f32 v2, v0, s13, -v2
	v_fmac_f32_e32 v2, 0x3377d1cf, v0
	v_fmac_f32_e32 v2, 0x3f317217, v0
	v_cmp_lt_f32_e64 s[0:1], |v0|, s36
	s_nop 1
	v_cndmask_b32_e64 v0, v0, v2, s[0:1]
	v_cndmask_b32_e32 v2, 0, v60, vcc
	v_sub_f32_e32 v0, v0, v2
	v_sub_f32_e32 v0, v1, v0
	v_fmamk_f32 v130, v0, 0x3d800000, v129
	ds_read_b128 v[0:3], v5 offset:3968
	s_waitcnt lgkmcnt(0)
	v_fma_f32 v131, v65, v0, v69
	v_fmac_f32_e32 v131, v66, v1
	v_fmac_f32_e32 v131, v67, v2
	v_fmac_f32_e32 v131, v68, v3
	ds_read_b128 v[0:3], v5 offset:3984
	s_waitcnt lgkmcnt(0)
	v_fmac_f32_e32 v131, v55, v0
	v_fmac_f32_e32 v131, v62, v1
	v_fmac_f32_e32 v131, v63, v2
	v_fmac_f32_e32 v131, v64, v3
	ds_read_b128 v[0:3], v5 offset:4000
	s_waitcnt lgkmcnt(0)
	v_fmac_f32_e32 v131, v52, v0
	v_fmac_f32_e32 v131, v53, v1
	v_pk_mul_f32 v[0:1], v[50:51], v[2:3]
	s_nop 0
	v_add_f32_e32 v0, v131, v0
	v_add_f32_e32 v131, v0, v1
	ds_read_b128 v[0:3], v5 offset:4016
	s_waitcnt lgkmcnt(0)
	v_pk_mul_f32 v[0:1], v[48:49], v[0:1]
	s_nop 0
	v_add_f32_e32 v0, v131, v0
	v_add_f32_e32 v131, v0, v1
	v_pk_mul_f32 v[0:1], v[46:47], v[2:3]
	s_nop 0
	v_add_f32_e32 v0, v131, v0
	v_add_f32_e32 v0, v0, v1
	v_min_f32_e32 v1, 0, v0
	v_mul_f32_e64 v0, |v0|, s11
	v_exp_f32_e32 v0, v0
	s_nop 0
	v_add_f32_e32 v0, 1.0, v0
	v_cmp_gt_f32_e32 vcc, s12, v0
	s_nop 1
	v_cndmask_b32_e64 v2, 0, 32, vcc
	v_ldexp_f32 v0, v0, v2
	v_log_f32_e32 v0, v0
	s_nop 0
	v_mul_f32_e32 v2, 0x3f317217, v0
	v_fma_f32 v2, v0, s13, -v2
	v_fmac_f32_e32 v2, 0x3377d1cf, v0
	v_fmac_f32_e32 v2, 0x3f317217, v0
	v_cmp_lt_f32_e64 s[0:1], |v0|, s36
	s_nop 1
	v_cndmask_b32_e64 v0, v0, v2, s[0:1]
	v_cndmask_b32_e32 v2, 0, v60, vcc
	v_sub_f32_e32 v0, v0, v2
	v_sub_f32_e32 v0, v1, v0
	v_fmamk_f32 v131, v0, 0x3d800000, v130
	ds_read_b128 v[0:3], v5 offset:4032
	s_waitcnt lgkmcnt(0)
	v_fmac_f32_e32 v69, v65, v0
	v_fmac_f32_e32 v69, v66, v1
	v_fmac_f32_e32 v69, v67, v2
	v_fmac_f32_e32 v69, v68, v3
	ds_read_b128 v[0:3], v5 offset:4048
	s_waitcnt lgkmcnt(0)
	v_fmac_f32_e32 v69, v55, v0
	v_fmac_f32_e32 v69, v62, v1
	v_fmac_f32_e32 v69, v63, v2
	v_fmac_f32_e32 v69, v64, v3
	ds_read_b128 v[0:3], v5 offset:4064
	s_waitcnt lgkmcnt(0)
	v_pk_mul_f32 v[0:1], v[52:53], v[0:1]
	s_nop 0
	v_add_f32_e32 v0, v69, v0
	v_add_f32_e32 v52, v0, v1
	v_pk_mul_f32 v[0:1], v[50:51], v[2:3]
	s_nop 0
	v_add_f32_e32 v0, v52, v0
	v_add_f32_e32 v50, v0, v1
	ds_read_b128 v[0:3], v5 offset:4080
	s_waitcnt lgkmcnt(0)
	v_pk_mul_f32 v[0:1], v[48:49], v[0:1]
	s_nop 0
	v_add_f32_e32 v0, v50, v0
	v_add_f32_e32 v48, v0, v1
	v_pk_mul_f32 v[0:1], v[46:47], v[2:3]
	s_nop 0
	v_add_f32_e32 v0, v48, v0
	v_add_f32_e32 v0, v0, v1
	v_min_f32_e32 v1, 0, v0
	v_mul_f32_e64 v0, |v0|, s11
	v_exp_f32_e32 v0, v0
	s_nop 0
	v_add_f32_e32 v0, 1.0, v0
	v_cmp_gt_f32_e32 vcc, s12, v0
	s_nop 1
	v_cndmask_b32_e64 v2, 0, 32, vcc
	v_ldexp_f32 v0, v0, v2
	v_log_f32_e32 v0, v0
	s_nop 0
	v_mul_f32_e32 v2, 0x3f317217, v0
	v_fma_f32 v2, v0, s13, -v2
	v_fmac_f32_e32 v2, 0x3377d1cf, v0
	v_fmac_f32_e32 v2, 0x3f317217, v0
	v_cmp_lt_f32_e64 s[0:1], |v0|, s36
	s_nop 1
	v_cndmask_b32_e64 v0, v0, v2, s[0:1]
	v_mad_u64_u32 v[46:47], s[0:1], s6, v59, v[42:43]
	s_movk_i32 s0, 0x2000
	v_cndmask_b32_e32 v2, 0, v60, vcc
	v_add_u32_e32 v47, s7, v47
	v_add_co_u32_e32 v50, vcc, s0, v46
	v_sub_f32_e32 v0, v0, v2
	s_nop 0
	v_addc_co_u32_e32 v51, vcc, 0, v47, vcc
	s_waitcnt vmcnt(0)
	v_mov_b32_e32 v50, v141
	s_nop 0
	v_mov_b32_e32 v52, v140
	s_movk_i32 s0, 0x3000
	v_sub_f32_e32 v0, v1, v0
	v_fmamk_f32 v62, v0, 0x3d800000, v131
	v_sub_f32_e32 v48, v62, v54
	v_sub_f32_e32 v49, v62, v70
	v_mul_f32_e32 v48, 0x3fb8aa3b, v48
	v_mul_f32_e32 v49, 0x3fb8aa3b, v49
	v_exp_f32_e32 v48, v48
	v_exp_f32_e32 v49, v49
	v_lshl_add_u32 v0, s8, 7, v56
	v_or_b32_e32 v0, s9, v0
	v_ashrrev_i32_e32 v1, 31, v0
	v_lshlrev_b64 v[2:3], 14, v[0:1]
	v_lshl_add_u64 v[2:3], v[38:39], 0, v[2:3]
	v_lshlrev_b64 v[0:1], 9, v[0:1]
	v_lshl_add_u64 v[0:1], v[40:41], 0, v[0:1]
	s_nop 0
	v_lshlrev_b32_e32 v51, 16, v50
	s_nop 0
	v_lshlrev_b32_e32 v50, 16, v52
	v_add_co_u32_e32 v52, vcc, s0, v46
	s_movk_i32 s0, 0x5000
	s_nop 0
	v_addc_co_u32_e32 v53, vcc, 0, v47, vcc
	v_mov_b32_e32 v54, v142
	v_add_co_u32_e32 v52, vcc, s0, v46
	s_movk_i32 s0, 0x6000
	s_nop 0
	v_addc_co_u32_e32 v53, vcc, 0, v47, vcc
	v_mov_b32_e32 v52, v143
	v_pk_mul_f32 v[48:49], v[48:49], v[50:51]
	v_sub_f32_e32 v50, v62, v71
	v_sub_f32_e32 v51, v62, v72
	v_mul_f32_e32 v50, 0x3fb8aa3b, v50
	v_mul_f32_e32 v51, 0x3fb8aa3b, v51
	v_exp_f32_e32 v50, v50
	v_exp_f32_e32 v51, v51
	v_cvt_pk_bf16_f32 v48, v48, v49
	s_nop 0
	v_lshlrev_b32_e32 v53, 16, v52
	v_lshlrev_b32_e32 v52, 16, v54
	v_add_co_u32_e32 v54, vcc, s0, v46
	s_mov_b32 s0, 0x8000
	s_nop 0
	v_addc_co_u32_e32 v55, vcc, 0, v47, vcc
	v_mov_b32_e32 v63, v144
	v_add_co_u32_e32 v54, vcc, s0, v46
	s_mov_b32 s0, 0x9000
	s_nop 0
	v_addc_co_u32_e32 v55, vcc, 0, v47, vcc
	v_mov_b32_e32 v54, v145
	v_add_co_u32_e32 v64, vcc, s0, v46
	s_mov_b32 s0, 0xb000
	s_nop 0
	v_addc_co_u32_e32 v65, vcc, 0, v47, vcc
	v_pk_mul_f32 v[50:51], v[50:51], v[52:53]
	v_sub_f32_e32 v52, v62, v73
	v_sub_f32_e32 v53, v62, v74
	v_mul_f32_e32 v52, 0x3fb8aa3b, v52
	v_mul_f32_e32 v53, 0x3fb8aa3b, v53
	v_exp_f32_e32 v52, v52
; __device__ __forceinline__ unsigned pk2(float lo, float hi) { f32x2_t v = {lo, hi}; bf16x2_t b = __builtin_convertvector(v, bf16x2_t); return __builtin_bit_cast(unsigned, b); }
; __device__ __forceinline__ void gla_prep_item(LAS unsigned char* lds, int item, const bf16_t* Z, const float* W2, const float* Bg, bf16_t* KDT, float* DEC) {
;     ...
;     for (int t8 = 0; t8 < 8; ++t8) {
;         float kv[8];
; #pragma unroll
;         for (int e = 0; e < 8; ++e) {
;             const int t = t8 * 8 + e;
;             bc += gv[t];
;             kv[e] = bf2f(gk[(size_t)t * ZLD]) * __expf(bend - bc);
;         }
;         u32x4 o; o.x = pk2(kv[0], kv[1]); o.y = pk2(kv[2], kv[3]); o.z = pk2(kv[4], kv[5]); o.w = pk2(kv[6], kv[7]);
;         *(u32x4*)(dst + ((t8 >> 2) * 64 + (t8 & 3) * 16) * 8) = o;
;     }
	v_exp_f32_e32 v53, v53
	v_cvt_pk_bf16_f32 v49, v50, v51
	s_nop 0
	v_lshlrev_b32_e32 v55, 16, v54
	v_lshlrev_b32_e32 v54, 16, v63
	v_mov_b32_e32 v63, v146
	v_add_co_u32_e32 v64, vcc, s0, v46
	v_pk_mul_f32 v[52:53], v[52:53], v[54:55]
	s_nop 0
	v_addc_co_u32_e32 v65, vcc, 0, v47, vcc
	v_mov_b32_e32 v64, v147
	v_sub_f32_e32 v54, v62, v75
	v_sub_f32_e32 v55, v62, v77
	v_mul_f32_e32 v54, 0x3fb8aa3b, v54
	v_mul_f32_e32 v55, 0x3fb8aa3b, v55
	v_exp_f32_e32 v54, v54
	v_exp_f32_e32 v55, v55
	v_cvt_pk_bf16_f32 v50, v52, v53
	s_mov_b32 s0, 0xc000
	s_nop 0
	v_lshlrev_b32_e32 v65, 16, v64
	v_lshlrev_b32_e32 v64, 16, v63
	v_pk_mul_f32 v[54:55], v[54:55], v[64:65]
	s_nop 0
	v_cvt_pk_bf16_f32 v51, v54, v55
	global_store_dwordx4 v[2:3], v[48:51], off
	s_nop 1
	v_add_co_u32_e32 v50, vcc, s0, v46
	s_mov_b32 s0, 0xe000
	s_nop 0
	v_addc_co_u32_e32 v51, vcc, 0, v47, vcc
	v_mov_b32_e32 v52, v148
	v_add_co_u32_e32 v50, vcc, s0, v46
	s_mov_b32 s0, 0xf000
	s_nop 0
	v_addc_co_u32_e32 v51, vcc, 0, v47, vcc
	v_mov_b32_e32 v50, v149
	v_sub_f32_e32 v48, v62, v76
	v_sub_f32_e32 v49, v62, v78
	v_mul_f32_e32 v48, 0x3fb8aa3b, v48
	v_mul_f32_e32 v49, 0x3fb8aa3b, v49
	v_exp_f32_e32 v48, v48
	v_exp_f32_e32 v49, v49
	s_nop 0
	v_lshlrev_b32_e32 v51, 16, v50
	v_lshlrev_b32_e32 v50, 16, v52
	v_add_co_u32_e32 v52, vcc, s0, v46
	s_mov_b32 s0, 0x11000
	s_nop 0
	v_addc_co_u32_e32 v53, vcc, 0, v47, vcc
	v_mov_b32_e32 v54, v150
	v_add_co_u32_e32 v52, vcc, s0, v46
	s_mov_b32 s0, 0x12000
	s_nop 0
	v_addc_co_u32_e32 v53, vcc, 0, v47, vcc
	v_mov_b32_e32 v52, v151
	v_pk_mul_f32 v[48:49], v[48:49], v[50:51]
	v_sub_f32_e32 v50, v62, v79
	v_sub_f32_e32 v51, v62, v80
	v_mul_f32_e32 v50, 0x3fb8aa3b, v50
	v_mul_f32_e32 v51, 0x3fb8aa3b, v51
	v_exp_f32_e32 v50, v50
	v_exp_f32_e32 v51, v51
	v_cvt_pk_bf16_f32 v48, v48, v49
	s_nop 0
	v_lshlrev_b32_e32 v53, 16, v52
	v_lshlrev_b32_e32 v52, 16, v54
	v_add_co_u32_e32 v54, vcc, s0, v46
	s_mov_b32 s0, 0x14000
	s_nop 0
	v_addc_co_u32_e32 v55, vcc, 0, v47, vcc
	v_mov_b32_e32 v63, v152
	v_add_co_u32_e32 v54, vcc, s0, v46
	s_mov_b32 s0, 0x15000
	s_nop 0
	v_addc_co_u32_e32 v55, vcc, 0, v47, vcc
	v_mov_b32_e32 v54, v153
	v_add_co_u32_e32 v64, vcc, s0, v46
	s_mov_b32 s0, 0x17000
	s_nop 0
	v_addc_co_u32_e32 v65, vcc, 0, v47, vcc
	v_pk_mul_f32 v[50:51], v[50:51], v[52:53]
	v_sub_f32_e32 v52, v62, v81
	v_sub_f32_e32 v53, v62, v82
	v_mul_f32_e32 v52, 0x3fb8aa3b, v52
	v_mul_f32_e32 v53, 0x3fb8aa3b, v53
	v_exp_f32_e32 v52, v52
	v_exp_f32_e32 v53, v53
	v_cvt_pk_bf16_f32 v49, v50, v51
	s_nop 0
	v_lshlrev_b32_e32 v55, 16, v54
	v_lshlrev_b32_e32 v54, 16, v63
	v_mov_b32_e32 v63, v154
	v_add_co_u32_e32 v64, vcc, s0, v46
	v_pk_mul_f32 v[52:53], v[52:53], v[54:55]
	s_nop 0
	v_addc_co_u32_e32 v65, vcc, 0, v47, vcc
	v_mov_b32_e32 v64, v155
	v_sub_f32_e32 v54, v62, v83
	v_sub_f32_e32 v55, v62, v84
	v_mul_f32_e32 v54, 0x3fb8aa3b, v54
	v_mul_f32_e32 v55, 0x3fb8aa3b, v55
	v_exp_f32_e32 v54, v54
	v_exp_f32_e32 v55, v55
	v_cvt_pk_bf16_f32 v50, v52, v53
	s_mov_b32 s0, 0x18000
	s_nop 0
	v_lshlrev_b32_e32 v65, 16, v64
	v_lshlrev_b32_e32 v64, 16, v63
	v_pk_mul_f32 v[54:55], v[54:55], v[64:65]
	s_nop 0
	v_cvt_pk_bf16_f32 v51, v54, v55
	global_store_dwordx4 v[2:3], v[48:51], off offset:256
	s_nop 1
	v_add_co_u32_e32 v50, vcc, s0, v46
	s_mov_b32 s0, 0x1a000
	s_nop 0
	v_addc_co_u32_e32 v51, vcc, 0, v47, vcc
	v_mov_b32_e32 v52, v156
	v_add_co_u32_e32 v50, vcc, s0, v46
	s_mov_b32 s0, 0x1b000
	s_nop 0
	v_addc_co_u32_e32 v51, vcc, 0, v47, vcc
	v_mov_b32_e32 v50, v157
	v_sub_f32_e32 v48, v62, v85
	v_sub_f32_e32 v49, v62, v86
	v_mul_f32_e32 v48, 0x3fb8aa3b, v48
	v_mul_f32_e32 v49, 0x3fb8aa3b, v49
	v_exp_f32_e32 v48, v48
	v_exp_f32_e32 v49, v49
	s_nop 0
	v_lshlrev_b32_e32 v51, 16, v50
	v_lshlrev_b32_e32 v50, 16, v52
	v_add_co_u32_e32 v52, vcc, s0, v46
	s_mov_b32 s0, 0x1d000
	s_nop 0
	v_addc_co_u32_e32 v53, vcc, 0, v47, vcc
	v_mov_b32_e32 v54, v158
	v_add_co_u32_e32 v52, vcc, s0, v46
	s_mov_b32 s0, 0x1e000
	s_nop 0
	v_addc_co_u32_e32 v53, vcc, 0, v47, vcc
	v_mov_b32_e32 v52, v159
	v_pk_mul_f32 v[48:49], v[48:49], v[50:51]
	v_sub_f32_e32 v50, v62, v87
	v_sub_f32_e32 v51, v62, v88
	v_mul_f32_e32 v50, 0x3fb8aa3b, v50
	v_mul_f32_e32 v51, 0x3fb8aa3b, v51
	v_exp_f32_e32 v50, v50
	v_exp_f32_e32 v51, v51
	v_cvt_pk_bf16_f32 v48, v48, v49
	s_nop 0
	v_lshlrev_b32_e32 v53, 16, v52
	v_lshlrev_b32_e32 v52, 16, v54
	v_add_co_u32_e32 v54, vcc, s0, v46
	s_mov_b32 s0, 0x20000
	s_nop 0
	v_addc_co_u32_e32 v55, vcc, 0, v47, vcc
	v_mov_b32_e32 v63, v160
	v_add_co_u32_e32 v54, vcc, s0, v46
	s_mov_b32 s0, 0x21000
	s_nop 0
	v_addc_co_u32_e32 v55, vcc, 0, v47, vcc
	v_mov_b32_e32 v54, v161
	v_add_co_u32_e32 v64, vcc, s0, v46
	s_mov_b32 s0, 0x23000
	s_nop 0
	v_addc_co_u32_e32 v65, vcc, 0, v47, vcc
	v_pk_mul_f32 v[50:51], v[50:51], v[52:53]
	v_sub_f32_e32 v52, v62, v89
	v_sub_f32_e32 v53, v62, v90
	v_mul_f32_e32 v52, 0x3fb8aa3b, v52
	v_mul_f32_e32 v53, 0x3fb8aa3b, v53
	v_exp_f32_e32 v52, v52
	v_exp_f32_e32 v53, v53
	v_cvt_pk_bf16_f32 v49, v50, v51
	s_nop 0
	v_lshlrev_b32_e32 v55, 16, v54
	v_lshlrev_b32_e32 v54, 16, v63
	v_mov_b32_e32 v63, v162
	v_add_co_u32_e32 v64, vcc, s0, v46
	v_pk_mul_f32 v[52:53], v[52:53], v[54:55]
	s_nop 0
	v_addc_co_u32_e32 v65, vcc, 0, v47, vcc
	v_mov_b32_e32 v64, v163
	v_sub_f32_e32 v54, v62, v91
	v_sub_f32_e32 v55, v62, v92
	v_mul_f32_e32 v54, 0x3fb8aa3b, v54
	v_mul_f32_e32 v55, 0x3fb8aa3b, v55
	v_exp_f32_e32 v54, v54
	v_exp_f32_e32 v55, v55
	v_cvt_pk_bf16_f32 v50, v52, v53
	s_mov_b32 s0, 0x24000
	s_nop 0
	v_lshlrev_b32_e32 v65, 16, v64
	v_lshlrev_b32_e32 v64, 16, v63
	v_pk_mul_f32 v[54:55], v[54:55], v[64:65]
	s_nop 0
	v_cvt_pk_bf16_f32 v51, v54, v55
	global_store_dwordx4 v[2:3], v[48:51], off offset:512
; __device__ __forceinline__ unsigned pk2(float lo, float hi) { f32x2_t v = {lo, hi}; bf16x2_t b = __builtin_convertvector(v, bf16x2_t); return __builtin_bit_cast(unsigned, b); }
; __device__ __forceinline__ void gla_prep_item(LAS unsigned char* lds, int item, const bf16_t* Z, const float* W2, const float* Bg, bf16_t* KDT, float* DEC) {
;     ...
;     for (int t8 = 0; t8 < 8; ++t8) {
;         float kv[8];
; #pragma unroll
;         for (int e = 0; e < 8; ++e) {
;             const int t = t8 * 8 + e;
;             bc += gv[t];
;             kv[e] = bf2f(gk[(size_t)t * ZLD]) * __expf(bend - bc);
;         }
;         u32x4 o; o.x = pk2(kv[0], kv[1]); o.y = pk2(kv[2], kv[3]); o.z = pk2(kv[4], kv[5]); o.w = pk2(kv[6], kv[7]);
;         *(u32x4*)(dst + ((t8 >> 2) * 64 + (t8 & 3) * 16) * 8) = o;
;     }
	s_nop 1
	v_add_co_u32_e32 v50, vcc, s0, v46
	s_mov_b32 s0, 0x26000
	s_nop 0
	v_addc_co_u32_e32 v51, vcc, 0, v47, vcc
	v_mov_b32_e32 v52, v164
	v_add_co_u32_e32 v50, vcc, s0, v46
	s_mov_b32 s0, 0x27000
	s_nop 0
	v_addc_co_u32_e32 v51, vcc, 0, v47, vcc
	v_mov_b32_e32 v50, v165
	v_sub_f32_e32 v48, v62, v93
	v_sub_f32_e32 v49, v62, v94
	v_mul_f32_e32 v48, 0x3fb8aa3b, v48
	v_mul_f32_e32 v49, 0x3fb8aa3b, v49
	v_exp_f32_e32 v48, v48
	v_exp_f32_e32 v49, v49
	s_nop 0
	v_lshlrev_b32_e32 v51, 16, v50
	v_lshlrev_b32_e32 v50, 16, v52
	v_add_co_u32_e32 v52, vcc, s0, v46
	s_mov_b32 s0, 0x29000
	s_nop 0
	v_addc_co_u32_e32 v53, vcc, 0, v47, vcc
	v_mov_b32_e32 v54, v166
	v_add_co_u32_e32 v52, vcc, s0, v46
	s_mov_b32 s0, 0x2a000
	s_nop 0
	v_addc_co_u32_e32 v53, vcc, 0, v47, vcc
	v_mov_b32_e32 v52, v167
	v_pk_mul_f32 v[48:49], v[48:49], v[50:51]
	v_sub_f32_e32 v50, v62, v95
	v_sub_f32_e32 v51, v62, v96
	v_mul_f32_e32 v50, 0x3fb8aa3b, v50
	v_mul_f32_e32 v51, 0x3fb8aa3b, v51
	v_exp_f32_e32 v50, v50
	v_exp_f32_e32 v51, v51
	v_cvt_pk_bf16_f32 v48, v48, v49
	s_nop 0
	v_lshlrev_b32_e32 v53, 16, v52
	v_lshlrev_b32_e32 v52, 16, v54
	v_add_co_u32_e32 v54, vcc, s0, v46
	s_mov_b32 s0, 0x2c000
	s_nop 0
	v_addc_co_u32_e32 v55, vcc, 0, v47, vcc
	v_mov_b32_e32 v63, v168
	v_add_co_u32_e32 v54, vcc, s0, v46
	s_mov_b32 s0, 0x2d000
	s_nop 0
	v_addc_co_u32_e32 v55, vcc, 0, v47, vcc
	v_mov_b32_e32 v54, v169
	v_add_co_u32_e32 v64, vcc, s0, v46
	s_mov_b32 s0, 0x2f000
	s_nop 0
	v_addc_co_u32_e32 v65, vcc, 0, v47, vcc
	v_pk_mul_f32 v[50:51], v[50:51], v[52:53]
	v_sub_f32_e32 v52, v62, v97
	v_sub_f32_e32 v53, v62, v98
	v_mul_f32_e32 v52, 0x3fb8aa3b, v52
	v_mul_f32_e32 v53, 0x3fb8aa3b, v53
	v_exp_f32_e32 v52, v52
	v_exp_f32_e32 v53, v53
	v_cvt_pk_bf16_f32 v49, v50, v51
	s_nop 0
	v_lshlrev_b32_e32 v55, 16, v54
	v_lshlrev_b32_e32 v54, 16, v63
	v_mov_b32_e32 v63, v170
	v_add_co_u32_e32 v64, vcc, s0, v46
	v_pk_mul_f32 v[52:53], v[52:53], v[54:55]
	s_nop 0
	v_addc_co_u32_e32 v65, vcc, 0, v47, vcc
	v_mov_b32_e32 v64, v171
	v_sub_f32_e32 v54, v62, v99
	v_sub_f32_e32 v55, v62, v100
	v_mul_f32_e32 v54, 0x3fb8aa3b, v54
	v_mul_f32_e32 v55, 0x3fb8aa3b, v55
	v_exp_f32_e32 v54, v54
	v_exp_f32_e32 v55, v55
	v_cvt_pk_bf16_f32 v50, v52, v53
	s_mov_b32 s0, 0x30000
	s_nop 0
	v_lshlrev_b32_e32 v65, 16, v64
	v_lshlrev_b32_e32 v64, 16, v63
	v_pk_mul_f32 v[54:55], v[54:55], v[64:65]
	s_nop 0
	v_cvt_pk_bf16_f32 v51, v54, v55
	global_store_dwordx4 v[2:3], v[48:51], off offset:768
	s_nop 1
	v_add_co_u32_e32 v50, vcc, s0, v46
	s_mov_b32 s0, 0x32000
	s_nop 0
	v_addc_co_u32_e32 v51, vcc, 0, v47, vcc
	v_mov_b32_e32 v52, v172
	v_add_co_u32_e32 v50, vcc, s0, v46
	s_mov_b32 s0, 0x33000
	s_nop 0
	v_addc_co_u32_e32 v51, vcc, 0, v47, vcc
	v_mov_b32_e32 v50, v173
	v_sub_f32_e32 v48, v62, v101
	v_sub_f32_e32 v49, v62, v102
	v_mul_f32_e32 v48, 0x3fb8aa3b, v48
	v_mul_f32_e32 v49, 0x3fb8aa3b, v49
	v_exp_f32_e32 v48, v48
	v_exp_f32_e32 v49, v49
	s_nop 0
	v_lshlrev_b32_e32 v51, 16, v50
	v_lshlrev_b32_e32 v50, 16, v52
	v_add_co_u32_e32 v52, vcc, s0, v46
	s_mov_b32 s0, 0x35000
	s_nop 0
	v_addc_co_u32_e32 v53, vcc, 0, v47, vcc
	v_mov_b32_e32 v54, v174
	v_add_co_u32_e32 v52, vcc, s0, v46
	s_mov_b32 s0, 0x36000
	s_nop 0
	v_addc_co_u32_e32 v53, vcc, 0, v47, vcc
	v_mov_b32_e32 v52, v175
	v_pk_mul_f32 v[48:49], v[48:49], v[50:51]
	v_sub_f32_e32 v50, v62, v103
	v_sub_f32_e32 v51, v62, v104
	v_mul_f32_e32 v50, 0x3fb8aa3b, v50
	v_mul_f32_e32 v51, 0x3fb8aa3b, v51
	v_exp_f32_e32 v50, v50
	v_exp_f32_e32 v51, v51
	v_cvt_pk_bf16_f32 v48, v48, v49
	s_nop 0
	v_lshlrev_b32_e32 v53, 16, v52
	v_lshlrev_b32_e32 v52, 16, v54
	v_add_co_u32_e32 v54, vcc, s0, v46
	s_mov_b32 s0, 0x38000
	s_nop 0
	v_addc_co_u32_e32 v55, vcc, 0, v47, vcc
	v_mov_b32_e32 v63, v176
	v_add_co_u32_e32 v54, vcc, s0, v46
	s_mov_b32 s0, 0x39000
	s_nop 0
	v_addc_co_u32_e32 v55, vcc, 0, v47, vcc
	v_mov_b32_e32 v54, v177
	v_add_co_u32_e32 v64, vcc, s0, v46
	s_mov_b32 s0, 0x3b000
	s_nop 0
	v_addc_co_u32_e32 v65, vcc, 0, v47, vcc
	v_pk_mul_f32 v[50:51], v[50:51], v[52:53]
	v_sub_f32_e32 v52, v62, v105
	v_sub_f32_e32 v53, v62, v106
	v_mul_f32_e32 v52, 0x3fb8aa3b, v52
	v_mul_f32_e32 v53, 0x3fb8aa3b, v53
	v_exp_f32_e32 v52, v52
	v_exp_f32_e32 v53, v53
	v_cvt_pk_bf16_f32 v49, v50, v51
	s_nop 0
	v_lshlrev_b32_e32 v55, 16, v54
	v_lshlrev_b32_e32 v54, 16, v63
	v_mov_b32_e32 v63, v178
	v_add_co_u32_e32 v64, vcc, s0, v46
	v_pk_mul_f32 v[52:53], v[52:53], v[54:55]
	s_nop 0
	v_addc_co_u32_e32 v65, vcc, 0, v47, vcc
	v_mov_b32_e32 v64, v179
	v_sub_f32_e32 v54, v62, v107
	v_sub_f32_e32 v55, v62, v108
	v_mul_f32_e32 v54, 0x3fb8aa3b, v54
	v_mul_f32_e32 v55, 0x3fb8aa3b, v55
	v_exp_f32_e32 v54, v54
	v_exp_f32_e32 v55, v55
	v_cvt_pk_bf16_f32 v50, v52, v53
	s_mov_b32 s0, 0x3c000
	s_nop 0
	v_lshlrev_b32_e32 v65, 16, v64
	v_lshlrev_b32_e32 v64, 16, v63
	v_pk_mul_f32 v[54:55], v[54:55], v[64:65]
	s_nop 0
	v_cvt_pk_bf16_f32 v51, v54, v55
	global_store_dwordx4 v[2:3], v[48:51], off offset:1024
	s_nop 1
	v_add_co_u32_e32 v50, vcc, s0, v46
	s_mov_b32 s0, 0x3e000
	s_nop 0
	v_addc_co_u32_e32 v51, vcc, 0, v47, vcc
	v_mov_b32_e32 v52, v180
	v_add_co_u32_e32 v50, vcc, s0, v46
	s_mov_b32 s0, 0x3f000
	s_nop 0
	v_addc_co_u32_e32 v51, vcc, 0, v47, vcc
	v_mov_b32_e32 v50, v181
	v_sub_f32_e32 v48, v62, v109
	v_sub_f32_e32 v49, v62, v110
	v_mul_f32_e32 v48, 0x3fb8aa3b, v48
	v_mul_f32_e32 v49, 0x3fb8aa3b, v49
	v_exp_f32_e32 v48, v48
	v_exp_f32_e32 v49, v49
	s_nop 0
	v_lshlrev_b32_e32 v51, 16, v50
	v_lshlrev_b32_e32 v50, 16, v52
	v_add_co_u32_e32 v52, vcc, s0, v46
	s_mov_b32 s0, 0x41000
	s_nop 0
	v_addc_co_u32_e32 v53, vcc, 0, v47, vcc
	v_mov_b32_e32 v54, v182
	v_add_co_u32_e32 v52, vcc, s0, v46
	s_mov_b32 s0, 0x42000
; __device__ __forceinline__ unsigned pk2(float lo, float hi) { f32x2_t v = {lo, hi}; bf16x2_t b = __builtin_convertvector(v, bf16x2_t); return __builtin_bit_cast(unsigned, b); }
; __device__ __forceinline__ void gla_prep_item(LAS unsigned char* lds, int item, const bf16_t* Z, const float* W2, const float* Bg, bf16_t* KDT, float* DEC) {
;     ...
;     for (int t8 = 0; t8 < 8; ++t8) {
;         float kv[8];
; #pragma unroll
;         for (int e = 0; e < 8; ++e) {
;             const int t = t8 * 8 + e;
;             bc += gv[t];
;             kv[e] = bf2f(gk[(size_t)t * ZLD]) * __expf(bend - bc);
;         }
;         u32x4 o; o.x = pk2(kv[0], kv[1]); o.y = pk2(kv[2], kv[3]); o.z = pk2(kv[4], kv[5]); o.w = pk2(kv[6], kv[7]);
;         *(u32x4*)(dst + ((t8 >> 2) * 64 + (t8 & 3) * 16) * 8) = o;
;     }
;     DEC[(size_t)((b * 4 + h) * 32 + c) * 128 + kd] = expf(bend);
;     __syncthreads();
	s_nop 0
	v_addc_co_u32_e32 v53, vcc, 0, v47, vcc
	v_mov_b32_e32 v52, v183
	v_pk_mul_f32 v[48:49], v[48:49], v[50:51]
	v_sub_f32_e32 v50, v62, v111
	v_sub_f32_e32 v51, v62, v112
	v_mul_f32_e32 v50, 0x3fb8aa3b, v50
	v_mul_f32_e32 v51, 0x3fb8aa3b, v51
	v_exp_f32_e32 v50, v50
	v_exp_f32_e32 v51, v51
	v_cvt_pk_bf16_f32 v48, v48, v49
	s_nop 0
	v_lshlrev_b32_e32 v53, 16, v52
	v_lshlrev_b32_e32 v52, 16, v54
	v_add_co_u32_e32 v54, vcc, s0, v46
	s_mov_b32 s0, 0x44000
	s_nop 0
	v_addc_co_u32_e32 v55, vcc, 0, v47, vcc
	v_mov_b32_e32 v63, v186
	v_add_co_u32_e32 v54, vcc, s0, v46
	s_mov_b32 s0, 0x45000
	s_nop 0
	v_addc_co_u32_e32 v55, vcc, 0, v47, vcc
	v_mov_b32_e32 v54, v187
	v_add_co_u32_e32 v64, vcc, s0, v46
	s_mov_b32 s0, 0x47000
	s_nop 0
	v_addc_co_u32_e32 v65, vcc, 0, v47, vcc
	v_pk_mul_f32 v[50:51], v[50:51], v[52:53]
	v_sub_f32_e32 v52, v62, v113
	v_sub_f32_e32 v53, v62, v114
	v_mul_f32_e32 v52, 0x3fb8aa3b, v52
	v_mul_f32_e32 v53, 0x3fb8aa3b, v53
	v_exp_f32_e32 v52, v52
	v_exp_f32_e32 v53, v53
	v_cvt_pk_bf16_f32 v49, v50, v51
	s_nop 0
	v_lshlrev_b32_e32 v55, 16, v54
	v_lshlrev_b32_e32 v54, 16, v63
	v_mov_b32_e32 v63, v188
	v_add_co_u32_e32 v64, vcc, s0, v46
	v_pk_mul_f32 v[52:53], v[52:53], v[54:55]
	s_nop 0
	v_addc_co_u32_e32 v65, vcc, 0, v47, vcc
	v_mov_b32_e32 v64, v189
	v_sub_f32_e32 v54, v62, v115
	v_sub_f32_e32 v55, v62, v116
	v_mul_f32_e32 v54, 0x3fb8aa3b, v54
	v_mul_f32_e32 v55, 0x3fb8aa3b, v55
	v_exp_f32_e32 v54, v54
	v_exp_f32_e32 v55, v55
	v_cvt_pk_bf16_f32 v50, v52, v53
	s_mov_b32 s0, 0x48000
	s_nop 0
	v_lshlrev_b32_e32 v65, 16, v64
	v_lshlrev_b32_e32 v64, 16, v63
	v_pk_mul_f32 v[54:55], v[54:55], v[64:65]
	s_nop 0
	v_cvt_pk_bf16_f32 v51, v54, v55
	global_store_dwordx4 v[2:3], v[48:51], off offset:1280
	s_nop 1
	v_add_co_u32_e32 v50, vcc, s0, v46
	s_mov_b32 s0, 0x4a000
	s_nop 0
	v_addc_co_u32_e32 v51, vcc, 0, v47, vcc
	v_mov_b32_e32 v52, v190
	v_add_co_u32_e32 v50, vcc, s0, v46
	s_mov_b32 s0, 0x4b000
	s_nop 0
	v_addc_co_u32_e32 v51, vcc, 0, v47, vcc
	v_mov_b32_e32 v50, v191
	v_sub_f32_e32 v48, v62, v117
	v_sub_f32_e32 v49, v62, v118
	v_mul_f32_e32 v48, 0x3fb8aa3b, v48
	v_mul_f32_e32 v49, 0x3fb8aa3b, v49
	v_exp_f32_e32 v48, v48
	v_exp_f32_e32 v49, v49
	s_nop 0
	v_lshlrev_b32_e32 v51, 16, v50
	v_lshlrev_b32_e32 v50, 16, v52
	v_add_co_u32_e32 v52, vcc, s0, v46
	s_mov_b32 s0, 0x4d000
	s_nop 0
	v_addc_co_u32_e32 v53, vcc, 0, v47, vcc
	v_mov_b32_e32 v54, v192
	v_add_co_u32_e32 v52, vcc, s0, v46
	s_mov_b32 s0, 0x4e000
	s_nop 0
	v_addc_co_u32_e32 v53, vcc, 0, v47, vcc
	v_mov_b32_e32 v52, v193
	v_pk_mul_f32 v[48:49], v[48:49], v[50:51]
	v_sub_f32_e32 v50, v62, v119
	v_sub_f32_e32 v51, v62, v120
	v_mul_f32_e32 v50, 0x3fb8aa3b, v50
	v_mul_f32_e32 v51, 0x3fb8aa3b, v51
	v_exp_f32_e32 v50, v50
	v_exp_f32_e32 v51, v51
	v_cvt_pk_bf16_f32 v48, v48, v49
	s_nop 0
	v_lshlrev_b32_e32 v53, 16, v52
	v_lshlrev_b32_e32 v52, 16, v54
	v_add_co_u32_e32 v54, vcc, s0, v46
	s_mov_b32 s0, 0x50000
	s_nop 0
	v_addc_co_u32_e32 v55, vcc, 0, v47, vcc
	v_mov_b32_e32 v63, v194
	v_add_co_u32_e32 v54, vcc, s0, v46
	s_mov_b32 s0, 0x51000
	s_nop 0
	v_addc_co_u32_e32 v55, vcc, 0, v47, vcc
	v_mov_b32_e32 v54, v195
	v_add_co_u32_e32 v64, vcc, s0, v46
	s_mov_b32 s0, 0x53000
	s_nop 0
	v_addc_co_u32_e32 v65, vcc, 0, v47, vcc
	v_pk_mul_f32 v[50:51], v[50:51], v[52:53]
	v_sub_f32_e32 v52, v62, v121
	v_sub_f32_e32 v53, v62, v122
	v_mul_f32_e32 v52, 0x3fb8aa3b, v52
	v_mul_f32_e32 v53, 0x3fb8aa3b, v53
	v_exp_f32_e32 v52, v52
	v_exp_f32_e32 v53, v53
	v_cvt_pk_bf16_f32 v49, v50, v51
	s_nop 0
	v_lshlrev_b32_e32 v55, 16, v54
	v_lshlrev_b32_e32 v54, 16, v63
	v_mov_b32_e32 v63, v196
	v_add_co_u32_e32 v64, vcc, s0, v46
	v_pk_mul_f32 v[52:53], v[52:53], v[54:55]
	s_nop 0
	v_addc_co_u32_e32 v65, vcc, 0, v47, vcc
	v_mov_b32_e32 v64, v197
	v_sub_f32_e32 v54, v62, v123
	v_sub_f32_e32 v55, v62, v124
	v_mul_f32_e32 v54, 0x3fb8aa3b, v54
	v_mul_f32_e32 v55, 0x3fb8aa3b, v55
	v_exp_f32_e32 v54, v54
	v_exp_f32_e32 v55, v55
	v_cvt_pk_bf16_f32 v50, v52, v53
	s_mov_b32 s0, 0x3fb8aa3b
	s_nop 0
	v_lshlrev_b32_e32 v65, 16, v64
	v_lshlrev_b32_e32 v64, 16, v63
	v_pk_mul_f32 v[54:55], v[54:55], v[64:65]
	s_nop 0
	v_cvt_pk_bf16_f32 v51, v54, v55
	global_store_dwordx4 v[2:3], v[48:51], off offset:1536
	s_nop 1
	v_add_co_u32_e32 v50, vcc, s37, v46
	v_sub_f32_e32 v48, v62, v125
	s_nop 0
	v_addc_co_u32_e32 v51, vcc, 0, v47, vcc
	v_mov_b32_e32 v52, v198
	v_add_co_u32_e32 v50, vcc, s52, v46
	v_sub_f32_e32 v49, v62, v126
	s_nop 0
	v_addc_co_u32_e32 v51, vcc, 0, v47, vcc
	v_mov_b32_e32 v50, v199
	v_mul_f32_e32 v48, 0x3fb8aa3b, v48
	v_mul_f32_e32 v49, 0x3fb8aa3b, v49
	v_exp_f32_e32 v48, v48
	v_exp_f32_e32 v49, v49
	s_nop 0
	v_lshlrev_b32_e32 v51, 16, v50
	v_lshlrev_b32_e32 v50, 16, v52
	v_add_co_u32_e32 v52, vcc, s53, v46
	v_pk_mul_f32 v[48:49], v[48:49], v[50:51]
	s_nop 0
	v_addc_co_u32_e32 v53, vcc, 0, v47, vcc
	v_mov_b32_e32 v54, v200
	v_add_co_u32_e32 v52, vcc, s58, v46
	v_sub_f32_e32 v50, v62, v127
	s_nop 0
	v_addc_co_u32_e32 v53, vcc, 0, v47, vcc
	v_mov_b32_e32 v52, v201
	v_sub_f32_e32 v51, v62, v128
	v_mul_f32_e32 v50, 0x3fb8aa3b, v50
	v_mul_f32_e32 v51, 0x3fb8aa3b, v51
	v_exp_f32_e32 v50, v50
	v_exp_f32_e32 v51, v51
	s_nop 0
	v_lshlrev_b32_e32 v53, 16, v52
	v_lshlrev_b32_e32 v52, 16, v54
	v_add_co_u32_e32 v54, vcc, s59, v46
	v_pk_mul_f32 v[50:51], v[50:51], v[52:53]
	s_nop 0
	v_addc_co_u32_e32 v55, vcc, 0, v47, vcc
	v_mov_b32_e32 v63, v202
	v_add_co_u32_e32 v54, vcc, s60, v46
	v_sub_f32_e32 v52, v62, v129
	s_nop 0
	v_addc_co_u32_e32 v55, vcc, 0, v47, vcc
	v_mov_b32_e32 v54, v203
	v_add_co_u32_e32 v64, vcc, s61, v46
	v_sub_f32_e32 v53, v62, v130
	s_nop 0
	v_addc_co_u32_e32 v65, vcc, 0, v47, vcc
	v_add_co_u32_e32 v46, vcc, s62, v46
	v_mul_f32_e32 v52, 0x3fb8aa3b, v52
	s_nop 0
	v_addc_co_u32_e32 v47, vcc, 0, v47, vcc
	v_mov_b32_e32 v46, v205
	v_mul_f32_e32 v53, 0x3fb8aa3b, v53
	v_exp_f32_e32 v52, v52
	v_exp_f32_e32 v53, v53
	v_cmp_ngt_f32_e32 vcc, s63, v62
	s_nop 0
	v_lshlrev_b32_e32 v55, 16, v54
	v_lshlrev_b32_e32 v54, 16, v63
	v_mov_b32_e32 v63, v204
	v_pk_mul_f32 v[52:53], v[52:53], v[54:55]
	v_sub_f32_e32 v54, v62, v131
	v_sub_f32_e32 v55, v62, v62
	v_mul_f32_e32 v54, 0x3fb8aa3b, v54
	v_mul_f32_e32 v55, 0x3fb8aa3b, v55
	v_exp_f32_e32 v54, v54
	v_exp_f32_e32 v55, v55
	s_nop 0
	v_lshlrev_b32_e32 v47, 16, v46
	s_nop 0
	v_lshlrev_b32_e32 v46, 16, v63
	v_pk_mul_f32 v[54:55], v[54:55], v[46:47]
	v_cvt_pk_bf16_f32 v46, v48, v49
	v_cvt_pk_bf16_f32 v47, v50, v51
	v_cvt_pk_bf16_f32 v48, v52, v53
	v_cvt_pk_bf16_f32 v49, v54, v55
	global_store_dwordx4 v[2:3], v[46:49], off offset:1792
	v_mul_f32_e32 v2, 0x3fb8aa3b, v62
	v_fma_f32 v3, v62, s0, -v2
	v_rndne_f32_e32 v46, v2
	v_fmac_f32_e32 v3, 0x32a5705f, v62
	v_sub_f32_e32 v2, v2, v46
	v_add_f32_e32 v2, v2, v3
	v_exp_f32_e32 v2, v2
	v_cvt_i32_f32_e32 v3, v46
	v_ldexp_f32 v2, v2, v3
	v_cndmask_b32_e32 v2, 0, v2, vcc
	v_cmp_nlt_f32_e32 vcc, s64, v62
	s_nop 1
	v_cndmask_b32_e32 v2, v61, v2, vcc
	global_store_dword v[0:1], v2, off
	s_barrier
	s_cbranch_scc0 .LBB0_597
	s_branch .LBB0_595
